# code placement: combo15 with every K-loop MFMA segment starting at byte phase 0 mod 8 (alignment pad placed in the preceding load segment's tail)
# speedup vs baseline: 1.0026x; 1.0013x over previous
; #define PG8_STAGE(bufoff, gbase, unused) do { _Pragma("unroll") for (int _i = 0; _i < 2; ++_i) \
;         __builtin_amdgcn_global_load_lds((const unsigned*)((const char*)(gbase) + voff + _i * 8192), (LAS unsigned*)(lds + (bufoff) + ldsw + _i * 8192), 16, 0, 0); } while (0)
; #define PG8_LDA(dst, b, h) do { _Pragma("unroll") for (int m = 0; m < 4; ++m) _Pragma("unroll") for (int k = 0; k < 2; ++k) dst[m][k] = *(const LAS bf16x8*)(lds + PG8_SA(b, h) + aoff + m * 2048 + (FP8 ? k * 16 : k * 1024)); } while (0)
; #define PG8_LDB(dst, b, h) do { _Pragma("unroll") for (int n = 0; n < 2; ++n) _Pragma("unroll") for (int k = 0; k < 2; ++k) dst[n][k] = *(const LAS bf16x8*)(lds + PG8_SB(b, h) + boff + n * 2048 + (FP8 ? k * 16 : k * 1024)); } while (0)
; #define PG8_WAIT_V(n) asm volatile("s_waitcnt vmcnt(" #n ")" ::: "memory")
; #define PG8_WAIT_L(n) asm volatile("s_waitcnt lgkmcnt(" #n ")" ::: "memory")
; #define PG8_BAR __builtin_amdgcn_s_barrier()
; #define PG8_SCHED __builtin_amdgcn_sched_barrier(0)
; template <class Epi, class Sched, bool ALIGN_EPI, bool SP2, int MODE  >
; __device__ __forceinline__ void gemm_phase(LAS unsigned char* lds, const Gemm g, const Sched S, const Epi E, unsigned long long& probe_acc, int epi_id, int wv) {
;     ...
;             PG8_LDB(B0, 0, 0); PG8_LDB(B1, 0, 1); PG8_SCHED; PG8_LDA(At, 0, 0); PG8_STAGE(PG8_SA(1, 1), a1 + hA, voffA);
;             PG8_WAIT_V(8); PG8_WAIT_L(0); PG8_BAR; PG8_MMA(0, 0, At, B0); PG8_MMA(0, 1, At, B1); PG8_BAR; PG8_SCHED;
;             PG8_LDA(At, 0, 1); PG8_STAGE(PG8_SB(0, 0), b2, voffB); PG8_STAGE(PG8_SB(0, 1), b2 + hB, voffB); PG8_STAGE(PG8_SA(0, 0), a2, voffA);
;             PG8_WAIT_V(8); PG8_WAIT_L(0); PG8_BAR; PG8_MMA(1, 0, At, B0); PG8_MMA(1, 1, At, B1); PG8_BAR; PG8_SCHED;
;             PG8_LDB(B0, 1, 0); PG8_LDB(B1, 1, 1); PG8_SCHED; PG8_LDA(At, 1, 0); PG8_STAGE(PG8_SA(0, 1), a2 + hA, voffA);
;             PG8_WAIT_V(8); PG8_WAIT_L(0); PG8_BAR; PG8_MMA(0, 0, At, B0); PG8_MMA(0, 1, At, B1); PG8_BAR; PG8_SCHED;
;             PG8_LDA(At, 1, 1); PG8_STAGE(PG8_SB(1, 0), b3, voffB); PG8_STAGE(PG8_SB(1, 1), b3 + hB, voffB); PG8_STAGE(PG8_SA(1, 0), a3, voffA);
;             PG8_WAIT_V(8); PG8_WAIT_L(0); PG8_BAR; PG8_MMA(1, 0, At, B0); PG8_MMA(1, 1, At, B1); PG8_BAR; PG8_SCHED;
.LBB0_325:
	s_mov_b64 s[28:29], s[10:11]
	s_mov_b32 s11, s1
	s_mov_b32 s26, s1
	s_add_i32 s40, s40, 1
	v_readlane_b32 s1, v254, 6
	s_mov_b64 s[14:15], s[4:5]
	s_mul_i32 s1, s40, s1
	v_readlane_b32 s4, v254, 35
	s_add_i32 s1, s1, s4
	s_cmpk_lt_i32 s1, 0x160
	s_cselect_b64 s[24:25], -1, 0
	s_and_b32 s4, s1, 7
	v_readlane_b32 s5, v254, 18
	s_mov_b32 s10, s69
	s_mov_b32 s8, s69
	s_or_b32 s69, s4, s5
	s_ashr_i32 s1, s1, 3
	s_and_b64 s[4:5], s[24:25], exec
	s_cselect_b32 s10, s69, s10
	s_cselect_b32 s4, s1, s11
	s_ashr_i32 s11, s10, 31
	s_lshl_b64 s[10:11], s[10:11], 19
	s_add_u32 s10, s34, s10
	s_addc_u32 s11, s35, s11
	s_and_b64 s[16:17], s[24:25], exec
	s_cselect_b32 s27, s11, s29
	s_cselect_b32 s46, s10, s28
	s_ashr_i32 s5, s4, 31
	s_lshl_b64 s[4:5], s[4:5], 19
	s_add_u32 s4, s36, s4
	s_addc_u32 s5, s37, s5
	s_and_b64 s[16:17], s[24:25], exec
	s_cselect_b32 vcc_lo, s5, s15
	s_cselect_b32 vcc_hi, s4, s14
	s_add_u32 s16, s14, 0x8000
	s_addc_u32 s17, s15, 0
	s_mov_b32 s14, -2
	s_waitcnt lgkmcnt(0)
	v_add_u32_e32 v0, s39, v212
	ds_read_b128 v[132:135], v0
	ds_read_b128 v[136:139], v0 offset:1024
	ds_read_b128 v[140:143], v0 offset:2048
	ds_read_b128 v[144:147], v0 offset:3072
	v_add_u32_e32 v0, s65, v212
	ds_read_b128 v[148:151], v0
	ds_read_b128 v[152:155], v0 offset:1024
	ds_read_b128 v[156:159], v0 offset:2048
	ds_read_b128 v[160:163], v0 offset:3072
	s_add_u32 s30, s28, 0x8000
	s_addc_u32 s31, s29, 0
	s_cmp_eq_u32 s14, 12
	s_cselect_b32 s23, s27, s31
	s_cselect_b32 s22, s46, s30
	s_cselect_b32 s21, vcc_lo, s17
	s_cselect_b32 s20, vcc_hi, s16
	v_lshl_add_u64 v[184:185], s[28:29], 0, v[130:131]
	v_lshl_add_u64 v[204:205], v[184:185], 0, s[80:81]
	s_add_i32 m0, s85, 0xc000
	ds_read_b128 v[164:167], v213
	ds_read_b128 v[168:171], v213 offset:1024
	ds_read_b128 v[172:175], v213 offset:2048
	ds_read_b128 v[176:179], v213 offset:3072
	ds_read_b128 v[180:183], v213 offset:4096
	ds_read_b128 v[190:193], v213 offset:5120
	ds_read_b128 v[196:199], v213 offset:6144
	ds_read_b128 v[200:203], v213 offset:7168
	global_load_lds_dwordx4 v[204:205], off
	v_lshl_add_u64 v[184:185], v[184:185], 0, s[82:83]
	s_add_i32 m0, s85, 0xe000
	s_nop 0
	global_load_lds_dwordx4 v[184:185], off
	.p2align 3
	s_waitcnt vmcnt(8)
	s_waitcnt lgkmcnt(0)
	s_setprio 1
	s_barrier
	v_mfma_i32_16x16x64_i8 v[126:129], v[132:135], v[164:167], 0
	v_mfma_i32_16x16x64_i8 v[102:105], v[140:143], v[164:167], 0
	v_mfma_i32_16x16x64_i8 v[122:125], v[132:135], v[172:175], 0
	v_mfma_i32_16x16x64_i8 v[94:97], v[140:143], v[172:175], 0
	v_mfma_i32_16x16x64_i8 v[118:121], v[132:135], v[180:183], 0
	v_mfma_i32_16x16x64_i8 v[46:49], v[140:143], v[180:183], 0
	v_mfma_i32_16x16x64_i8 v[110:113], v[132:135], v[196:199], 0
	v_mfma_i32_16x16x64_i8 v[38:41], v[140:143], v[196:199], 0
	v_mfma_i32_16x16x64_i8 v[126:129], v[136:139], v[168:171], v[126:129]
	v_mfma_i32_16x16x64_i8 v[102:105], v[144:147], v[168:171], v[102:105]
	v_mfma_i32_16x16x64_i8 v[122:125], v[136:139], v[176:179], v[122:125]
	v_mfma_i32_16x16x64_i8 v[94:97], v[144:147], v[176:179], v[94:97]
	v_mfma_i32_16x16x64_i8 v[118:121], v[136:139], v[190:193], v[118:121]
	v_mfma_i32_16x16x64_i8 v[46:49], v[144:147], v[190:193], v[46:49]
	v_mfma_i32_16x16x64_i8 v[110:113], v[136:139], v[200:203], v[110:113]
	v_mfma_i32_16x16x64_i8 v[38:41], v[144:147], v[200:203], v[38:41]
	v_mfma_i32_16x16x64_i8 v[114:117], v[148:151], v[164:167], 0
	v_mfma_i32_16x16x64_i8 v[82:85], v[156:159], v[164:167], 0
	v_mfma_i32_16x16x64_i8 v[106:109], v[148:151], v[172:175], 0
	v_mfma_i32_16x16x64_i8 v[74:77], v[156:159], v[172:175], 0
	v_mfma_i32_16x16x64_i8 v[98:101], v[148:151], v[180:183], 0
	v_mfma_i32_16x16x64_i8 v[42:45], v[156:159], v[180:183], 0
	v_mfma_i32_16x16x64_i8 v[90:93], v[148:151], v[196:199], 0
	v_mfma_i32_16x16x64_i8 v[34:37], v[156:159], v[196:199], 0
	v_mfma_i32_16x16x64_i8 v[114:117], v[152:155], v[168:171], v[114:117]
	v_mfma_i32_16x16x64_i8 v[82:85], v[160:163], v[168:171], v[82:85]
	v_mfma_i32_16x16x64_i8 v[106:109], v[152:155], v[176:179], v[106:109]
	v_mfma_i32_16x16x64_i8 v[74:77], v[160:163], v[176:179], v[74:77]
	v_mfma_i32_16x16x64_i8 v[98:101], v[152:155], v[190:193], v[98:101]
	v_mfma_i32_16x16x64_i8 v[42:45], v[160:163], v[190:193], v[42:45]
	v_mfma_i32_16x16x64_i8 v[90:93], v[152:155], v[200:203], v[90:93]
	v_mfma_i32_16x16x64_i8 v[34:37], v[160:163], v[200:203], v[34:37]
	s_barrier
	s_setprio 0
	s_mov_b32 m0, s41
	v_lshl_add_u64 v[184:185], s[20:21], 0, v[130:131]
	ds_read_b128 v[164:167], v213 offset:16384
	ds_read_b128 v[168:171], v213 offset:17408
	ds_read_b128 v[172:175], v213 offset:18432
	ds_read_b128 v[176:179], v213 offset:19456
	ds_read_b128 v[180:183], v213 offset:20480
	ds_read_b128 v[190:193], v213 offset:21504
	ds_read_b128 v[196:199], v213 offset:22528
	ds_read_b128 v[200:203], v213 offset:23552
	global_load_lds_dwordx4 v[184:185], off
	v_lshl_add_u64 v[204:205], v[184:185], 0, s[70:71]
	s_mov_b32 m0, s64
	s_nop 0
	global_load_lds_dwordx4 v[204:205], off
	v_lshl_add_u64 v[204:205], v[184:185], 0, s[72:73]
	s_mov_b32 m0, s68
	s_nop 0
	global_load_lds_dwordx4 v[204:205], off
	v_lshl_add_u64 v[204:205], v[184:185], 0, s[74:75]
	s_mov_b32 m0, s84
	s_nop 0
	global_load_lds_dwordx4 v[204:205], off
	v_lshl_add_u64 v[204:205], s[22:23], 0, v[130:131]
	s_mov_b32 m0, s85
	v_lshl_add_u64 v[206:207], v[204:205], 0, s[70:71]
	global_load_lds_dwordx4 v[204:205], off
	s_mov_b32 m0, s86
	s_nop 0
	global_load_lds_dwordx4 v[206:207], off
	.p2align 3
	s_waitcnt vmcnt(8)
	s_waitcnt lgkmcnt(0)
	s_setprio 1
	s_barrier
; #define PG8_STAGE(bufoff, gbase, unused) do { _Pragma("unroll") for (int _i = 0; _i < 2; ++_i) \
;         __builtin_amdgcn_global_load_lds((const unsigned*)((const char*)(gbase) + voff + _i * 8192), (LAS unsigned*)(lds + (bufoff) + ldsw + _i * 8192), 16, 0, 0); } while (0)
; #define PG8_LDA(dst, b, h) do { _Pragma("unroll") for (int m = 0; m < 4; ++m) _Pragma("unroll") for (int k = 0; k < 2; ++k) dst[m][k] = *(const LAS bf16x8*)(lds + PG8_SA(b, h) + aoff + m * 2048 + (FP8 ? k * 16 : k * 1024)); } while (0)
; #define PG8_LDB(dst, b, h) do { _Pragma("unroll") for (int n = 0; n < 2; ++n) _Pragma("unroll") for (int k = 0; k < 2; ++k) dst[n][k] = *(const LAS bf16x8*)(lds + PG8_SB(b, h) + boff + n * 2048 + (FP8 ? k * 16 : k * 1024)); } while (0)
; #define PG8_WAIT_V(n) asm volatile("s_waitcnt vmcnt(" #n ")" ::: "memory")
; #define PG8_WAIT_L(n) asm volatile("s_waitcnt lgkmcnt(" #n ")" ::: "memory")
; #define PG8_BAR __builtin_amdgcn_s_barrier()
; #define PG8_SCHED __builtin_amdgcn_sched_barrier(0)
; template <class Epi, class Sched, bool ALIGN_EPI, bool SP2, int MODE  >
; __device__ __forceinline__ void gemm_phase(LAS unsigned char* lds, const Gemm g, const Sched S, const Epi E, unsigned long long& probe_acc, int epi_id, int wv) {
;     ...
;             PG8_LDB(B0, 0, 0); PG8_LDB(B1, 0, 1); PG8_SCHED; PG8_LDA(At, 0, 0); PG8_STAGE(PG8_SA(1, 1), a1 + hA, voffA);
;             PG8_WAIT_V(8); PG8_WAIT_L(0); PG8_BAR; PG8_MMA(0, 0, At, B0); PG8_MMA(0, 1, At, B1); PG8_BAR; PG8_SCHED;
;             PG8_LDA(At, 0, 1); PG8_STAGE(PG8_SB(0, 0), b2, voffB); PG8_STAGE(PG8_SB(0, 1), b2 + hB, voffB); PG8_STAGE(PG8_SA(0, 0), a2, voffA);
;             PG8_WAIT_V(8); PG8_WAIT_L(0); PG8_BAR; PG8_MMA(1, 0, At, B0); PG8_MMA(1, 1, At, B1); PG8_BAR; PG8_SCHED;
;             PG8_LDB(B0, 1, 0); PG8_LDB(B1, 1, 1); PG8_SCHED; PG8_LDA(At, 1, 0); PG8_STAGE(PG8_SA(0, 1), a2 + hA, voffA);
;             PG8_WAIT_V(8); PG8_WAIT_L(0); PG8_BAR; PG8_MMA(0, 0, At, B0); PG8_MMA(0, 1, At, B1); PG8_BAR; PG8_SCHED;
;             PG8_LDA(At, 1, 1); PG8_STAGE(PG8_SB(1, 0), b3, voffB); PG8_STAGE(PG8_SB(1, 1), b3 + hB, voffB); PG8_STAGE(PG8_SA(1, 0), a3, voffA);
;             PG8_WAIT_V(8); PG8_WAIT_L(0); PG8_BAR; PG8_MMA(1, 0, At, B0); PG8_MMA(1, 1, At, B1); PG8_BAR; PG8_SCHED;
	v_mfma_i32_16x16x64_i8 v[86:89], v[132:135], v[164:167], 0
	v_mfma_i32_16x16x64_i8 v[30:33], v[140:143], v[164:167], 0
	v_mfma_i32_16x16x64_i8 v[78:81], v[132:135], v[172:175], 0
	v_mfma_i32_16x16x64_i8 v[22:25], v[140:143], v[172:175], 0
	v_mfma_i32_16x16x64_i8 v[70:73], v[132:135], v[180:183], 0
	v_mfma_i32_16x16x64_i8 v[14:17], v[140:143], v[180:183], 0
	v_mfma_i32_16x16x64_i8 v[62:65], v[132:135], v[196:199], 0
	v_mfma_i32_16x16x64_i8 v[2:5], v[140:143], v[196:199], 0
	v_mfma_i32_16x16x64_i8 v[86:89], v[136:139], v[168:171], v[86:89]
	v_mfma_i32_16x16x64_i8 v[30:33], v[144:147], v[168:171], v[30:33]
	v_mfma_i32_16x16x64_i8 v[78:81], v[136:139], v[176:179], v[78:81]
	v_mfma_i32_16x16x64_i8 v[22:25], v[144:147], v[176:179], v[22:25]
	v_mfma_i32_16x16x64_i8 v[70:73], v[136:139], v[190:193], v[70:73]
	v_mfma_i32_16x16x64_i8 v[14:17], v[144:147], v[190:193], v[14:17]
	v_mfma_i32_16x16x64_i8 v[62:65], v[136:139], v[200:203], v[62:65]
	v_mfma_i32_16x16x64_i8 v[2:5], v[144:147], v[200:203], v[2:5]
	v_mfma_i32_16x16x64_i8 v[66:69], v[148:151], v[164:167], 0
	v_mfma_i32_16x16x64_i8 v[26:29], v[156:159], v[164:167], 0
	v_mfma_i32_16x16x64_i8 v[58:61], v[148:151], v[172:175], 0
	v_mfma_i32_16x16x64_i8 v[18:21], v[156:159], v[172:175], 0
	v_mfma_i32_16x16x64_i8 v[54:57], v[148:151], v[180:183], 0
	v_mfma_i32_16x16x64_i8 v[10:13], v[156:159], v[180:183], 0
	v_mfma_i32_16x16x64_i8 v[50:53], v[148:151], v[196:199], 0
	v_mfma_i32_16x16x64_i8 v[6:9], v[156:159], v[196:199], 0
	v_mfma_i32_16x16x64_i8 v[66:69], v[152:155], v[168:171], v[66:69]
	v_mfma_i32_16x16x64_i8 v[26:29], v[160:163], v[168:171], v[26:29]
	v_mfma_i32_16x16x64_i8 v[58:61], v[152:155], v[176:179], v[58:61]
	v_mfma_i32_16x16x64_i8 v[18:21], v[160:163], v[176:179], v[18:21]
	v_mfma_i32_16x16x64_i8 v[54:57], v[152:155], v[190:193], v[54:57]
	v_mfma_i32_16x16x64_i8 v[10:13], v[160:163], v[190:193], v[10:13]
	v_mfma_i32_16x16x64_i8 v[50:53], v[152:155], v[200:203], v[50:53]
	v_mfma_i32_16x16x64_i8 v[6:9], v[160:163], v[200:203], v[6:9]
	s_barrier
	s_setprio 0
	v_add_u32_e32 v0, s90, v212
	ds_read_b128 v[132:135], v0
	ds_read_b128 v[136:139], v0 offset:1024
	ds_read_b128 v[140:143], v0 offset:2048
	ds_read_b128 v[144:147], v0 offset:3072
	v_add_u32_e32 v0, s95, v212
	ds_read_b128 v[148:151], v0
	ds_read_b128 v[152:155], v0 offset:1024
	ds_read_b128 v[156:159], v0 offset:2048
	ds_read_b128 v[160:163], v0 offset:3072
	s_mov_b32 m0, s87
	v_lshl_add_u64 v[206:207], v[204:205], 0, s[72:73]
	ds_read_b128 v[164:167], v213 offset:32768
	ds_read_b128 v[168:171], v213 offset:33792
	ds_read_b128 v[172:175], v213 offset:34816
	ds_read_b128 v[176:179], v213 offset:35840
	ds_read_b128 v[180:183], v213 offset:36864
	ds_read_b128 v[190:193], v213 offset:37888
	ds_read_b128 v[196:199], v213 offset:38912
	ds_read_b128 v[200:203], v213 offset:39936
	global_load_lds_dwordx4 v[206:207], off
	v_lshl_add_u64 v[206:207], v[204:205], 0, s[74:75]
	s_mov_b32 m0, s88
	s_nop 0
	global_load_lds_dwordx4 v[206:207], off
	.p2align 3
	s_waitcnt vmcnt(8)
	s_waitcnt lgkmcnt(0)
	s_setprio 1
	s_barrier
	v_mfma_i32_16x16x64_i8 v[126:129], v[132:135], v[164:167], v[126:129]
	v_mfma_i32_16x16x64_i8 v[102:105], v[140:143], v[164:167], v[102:105]
	v_mfma_i32_16x16x64_i8 v[122:125], v[132:135], v[172:175], v[122:125]
	v_mfma_i32_16x16x64_i8 v[94:97], v[140:143], v[172:175], v[94:97]
	v_mfma_i32_16x16x64_i8 v[118:121], v[132:135], v[180:183], v[118:121]
	v_mfma_i32_16x16x64_i8 v[46:49], v[140:143], v[180:183], v[46:49]
	v_mfma_i32_16x16x64_i8 v[110:113], v[132:135], v[196:199], v[110:113]
	v_mfma_i32_16x16x64_i8 v[38:41], v[140:143], v[196:199], v[38:41]
	v_mfma_i32_16x16x64_i8 v[126:129], v[136:139], v[168:171], v[126:129]
	v_mfma_i32_16x16x64_i8 v[102:105], v[144:147], v[168:171], v[102:105]
	v_mfma_i32_16x16x64_i8 v[122:125], v[136:139], v[176:179], v[122:125]
	v_mfma_i32_16x16x64_i8 v[94:97], v[144:147], v[176:179], v[94:97]
	v_mfma_i32_16x16x64_i8 v[118:121], v[136:139], v[190:193], v[118:121]
	v_mfma_i32_16x16x64_i8 v[46:49], v[144:147], v[190:193], v[46:49]
	v_mfma_i32_16x16x64_i8 v[110:113], v[136:139], v[200:203], v[110:113]
	v_mfma_i32_16x16x64_i8 v[38:41], v[144:147], v[200:203], v[38:41]
	v_mfma_i32_16x16x64_i8 v[114:117], v[148:151], v[164:167], v[114:117]
	v_mfma_i32_16x16x64_i8 v[82:85], v[156:159], v[164:167], v[82:85]
	v_mfma_i32_16x16x64_i8 v[106:109], v[148:151], v[172:175], v[106:109]
	v_mfma_i32_16x16x64_i8 v[74:77], v[156:159], v[172:175], v[74:77]
	v_mfma_i32_16x16x64_i8 v[98:101], v[148:151], v[180:183], v[98:101]
	v_mfma_i32_16x16x64_i8 v[42:45], v[156:159], v[180:183], v[42:45]
	v_mfma_i32_16x16x64_i8 v[90:93], v[148:151], v[196:199], v[90:93]
	v_mfma_i32_16x16x64_i8 v[34:37], v[156:159], v[196:199], v[34:37]
	v_mfma_i32_16x16x64_i8 v[114:117], v[152:155], v[168:171], v[114:117]
	v_mfma_i32_16x16x64_i8 v[82:85], v[160:163], v[168:171], v[82:85]
	v_mfma_i32_16x16x64_i8 v[106:109], v[152:155], v[176:179], v[106:109]
	v_mfma_i32_16x16x64_i8 v[74:77], v[160:163], v[176:179], v[74:77]
	v_mfma_i32_16x16x64_i8 v[98:101], v[152:155], v[190:193], v[98:101]
	v_mfma_i32_16x16x64_i8 v[42:45], v[160:163], v[190:193], v[42:45]
	v_mfma_i32_16x16x64_i8 v[90:93], v[152:155], v[200:203], v[90:93]
	v_mfma_i32_16x16x64_i8 v[34:37], v[160:163], v[200:203], v[34:37]
	s_barrier
; #define PG8_STAGE(bufoff, gbase, unused) do { _Pragma("unroll") for (int _i = 0; _i < 2; ++_i) \
;         __builtin_amdgcn_global_load_lds((const unsigned*)((const char*)(gbase) + voff + _i * 8192), (LAS unsigned*)(lds + (bufoff) + ldsw + _i * 8192), 16, 0, 0); } while (0)
; #define PG8_LDA(dst, b, h) do { _Pragma("unroll") for (int m = 0; m < 4; ++m) _Pragma("unroll") for (int k = 0; k < 2; ++k) dst[m][k] = *(const LAS bf16x8*)(lds + PG8_SA(b, h) + aoff + m * 2048 + (FP8 ? k * 16 : k * 1024)); } while (0)
; #define PG8_LDB(dst, b, h) do { _Pragma("unroll") for (int n = 0; n < 2; ++n) _Pragma("unroll") for (int k = 0; k < 2; ++k) dst[n][k] = *(const LAS bf16x8*)(lds + PG8_SB(b, h) + boff + n * 2048 + (FP8 ? k * 16 : k * 1024)); } while (0)
; #define PG8_WAIT_V(n) asm volatile("s_waitcnt vmcnt(" #n ")" ::: "memory")
; #define PG8_WAIT_L(n) asm volatile("s_waitcnt lgkmcnt(" #n ")" ::: "memory")
; #define PG8_BAR __builtin_amdgcn_s_barrier()
; #define PG8_SCHED __builtin_amdgcn_sched_barrier(0)
; template <class Epi, class Sched, bool ALIGN_EPI, bool SP2, int MODE  >
; __device__ __forceinline__ void gemm_phase(LAS unsigned char* lds, const Gemm g, const Sched S, const Epi E, unsigned long long& probe_acc, int epi_id, int wv) {
;     ...
;             PG8_LDB(B0, 0, 0); PG8_LDB(B1, 0, 1); PG8_SCHED; PG8_LDA(At, 0, 0); PG8_STAGE(PG8_SA(1, 1), a1 + hA, voffA);
;             PG8_WAIT_V(8); PG8_WAIT_L(0); PG8_BAR; PG8_MMA(0, 0, At, B0); PG8_MMA(0, 1, At, B1); PG8_BAR; PG8_SCHED;
;             PG8_LDA(At, 0, 1); PG8_STAGE(PG8_SB(0, 0), b2, voffB); PG8_STAGE(PG8_SB(0, 1), b2 + hB, voffB); PG8_STAGE(PG8_SA(0, 0), a2, voffA);
;             PG8_WAIT_V(8); PG8_WAIT_L(0); PG8_BAR; PG8_MMA(1, 0, At, B0); PG8_MMA(1, 1, At, B1); PG8_BAR; PG8_SCHED;
;             PG8_LDB(B0, 1, 0); PG8_LDB(B1, 1, 1); PG8_SCHED; PG8_LDA(At, 1, 0); PG8_STAGE(PG8_SA(0, 1), a2 + hA, voffA);
;             PG8_WAIT_V(8); PG8_WAIT_L(0); PG8_BAR; PG8_MMA(0, 0, At, B0); PG8_MMA(0, 1, At, B1); PG8_BAR; PG8_SCHED;
;             PG8_LDA(At, 1, 1); PG8_STAGE(PG8_SB(1, 0), b3, voffB); PG8_STAGE(PG8_SB(1, 1), b3 + hB, voffB); PG8_STAGE(PG8_SA(1, 0), a3, voffA);
;             PG8_WAIT_V(8); PG8_WAIT_L(0); PG8_BAR; PG8_MMA(1, 0, At, B0); PG8_MMA(1, 1, At, B1); PG8_BAR; PG8_SCHED;
	s_setprio 0
	s_mov_b32 m0, s91
	v_lshl_add_u64 v[206:207], v[184:185], 0, s[76:77]
	ds_read_b128 v[164:167], v213 offset:49152
	ds_read_b128 v[168:171], v213 offset:50176
	ds_read_b128 v[172:175], v213 offset:51200
	ds_read_b128 v[176:179], v213 offset:52224
	ds_read_b128 v[180:183], v213 offset:53248
	ds_read_b128 v[190:193], v213 offset:54272
	ds_read_b128 v[196:199], v213 offset:55296
	ds_read_b128 v[200:203], v213 offset:56320
	global_load_lds_dwordx4 v[206:207], off
	v_lshl_add_u64 v[206:207], v[184:185], 0, s[78:79]
	s_mov_b32 m0, s92
	s_nop 0
	global_load_lds_dwordx4 v[206:207], off
	v_lshl_add_u64 v[206:207], v[184:185], 0, s[80:81]
	s_mov_b32 m0, s2
	v_lshl_add_u64 v[184:185], v[184:185], 0, s[82:83]
	global_load_lds_dwordx4 v[206:207], off
	s_mov_b32 m0, s3
	s_nop 0
	global_load_lds_dwordx4 v[184:185], off
	v_lshl_add_u64 v[184:185], v[204:205], 0, s[76:77]
	s_mov_b32 m0, s93
	s_nop 0
	global_load_lds_dwordx4 v[184:185], off
	v_lshl_add_u64 v[184:185], v[204:205], 0, s[78:79]
	s_mov_b32 m0, s94
	s_nop 0
	global_load_lds_dwordx4 v[184:185], off
	.p2align 3
	s_waitcnt vmcnt(8)
	s_waitcnt lgkmcnt(0)
	s_setprio 1
	s_barrier
	v_mfma_i32_16x16x64_i8 v[86:89], v[132:135], v[164:167], v[86:89]
	v_mfma_i32_16x16x64_i8 v[30:33], v[140:143], v[164:167], v[30:33]
	v_mfma_i32_16x16x64_i8 v[78:81], v[132:135], v[172:175], v[78:81]
	v_mfma_i32_16x16x64_i8 v[22:25], v[140:143], v[172:175], v[22:25]
	v_mfma_i32_16x16x64_i8 v[70:73], v[132:135], v[180:183], v[70:73]
	v_mfma_i32_16x16x64_i8 v[14:17], v[140:143], v[180:183], v[14:17]
	v_mfma_i32_16x16x64_i8 v[62:65], v[132:135], v[196:199], v[62:65]
	v_mfma_i32_16x16x64_i8 v[2:5], v[140:143], v[196:199], v[2:5]
	v_mfma_i32_16x16x64_i8 v[86:89], v[136:139], v[168:171], v[86:89]
	v_mfma_i32_16x16x64_i8 v[30:33], v[144:147], v[168:171], v[30:33]
	v_mfma_i32_16x16x64_i8 v[78:81], v[136:139], v[176:179], v[78:81]
	v_mfma_i32_16x16x64_i8 v[22:25], v[144:147], v[176:179], v[22:25]
	v_mfma_i32_16x16x64_i8 v[70:73], v[136:139], v[190:193], v[70:73]
	v_mfma_i32_16x16x64_i8 v[14:17], v[144:147], v[190:193], v[14:17]
	v_mfma_i32_16x16x64_i8 v[62:65], v[136:139], v[200:203], v[62:65]
	v_mfma_i32_16x16x64_i8 v[2:5], v[144:147], v[200:203], v[2:5]
	v_mfma_i32_16x16x64_i8 v[66:69], v[148:151], v[164:167], v[66:69]
	v_mfma_i32_16x16x64_i8 v[26:29], v[156:159], v[164:167], v[26:29]
	v_mfma_i32_16x16x64_i8 v[58:61], v[148:151], v[172:175], v[58:61]
	v_mfma_i32_16x16x64_i8 v[18:21], v[156:159], v[172:175], v[18:21]
	v_mfma_i32_16x16x64_i8 v[54:57], v[148:151], v[180:183], v[54:57]
	v_mfma_i32_16x16x64_i8 v[10:13], v[156:159], v[180:183], v[10:13]
	v_mfma_i32_16x16x64_i8 v[50:53], v[148:151], v[196:199], v[50:53]
	v_mfma_i32_16x16x64_i8 v[6:9], v[156:159], v[196:199], v[6:9]
	v_mfma_i32_16x16x64_i8 v[66:69], v[152:155], v[168:171], v[66:69]
	v_mfma_i32_16x16x64_i8 v[26:29], v[160:163], v[168:171], v[26:29]
	v_mfma_i32_16x16x64_i8 v[58:61], v[152:155], v[176:179], v[58:61]
	v_mfma_i32_16x16x64_i8 v[18:21], v[160:163], v[176:179], v[18:21]
	v_mfma_i32_16x16x64_i8 v[54:57], v[152:155], v[190:193], v[54:57]
	v_mfma_i32_16x16x64_i8 v[10:13], v[160:163], v[190:193], v[10:13]
	v_mfma_i32_16x16x64_i8 v[50:53], v[152:155], v[200:203], v[50:53]
	v_mfma_i32_16x16x64_i8 v[6:9], v[160:163], v[200:203], v[6:9]
	s_barrier
	s_setprio 0
	s_add_i32 s14, s14, 2
	s_add_u32 s16, s16, 0x8000
	s_addc_u32 s17, s17, 0
	s_cmp_gt_u32 s14, 13
	s_mov_b64 s[28:29], s[30:31]
.LBB0_326:
	v_add_u32_e32 v0, s39, v212
	ds_read_b128 v[132:135], v0
	ds_read_b128 v[136:139], v0 offset:1024
	ds_read_b128 v[140:143], v0 offset:2048
	ds_read_b128 v[144:147], v0 offset:3072
	v_add_u32_e32 v0, s65, v212
	ds_read_b128 v[148:151], v0
	ds_read_b128 v[152:155], v0 offset:1024
	ds_read_b128 v[156:159], v0 offset:2048
	ds_read_b128 v[160:163], v0 offset:3072
	s_add_u32 s30, s28, 0x8000
	s_addc_u32 s31, s29, 0
	s_cmp_eq_u32 s14, 12
	s_cselect_b32 s23, s27, s31
	s_cselect_b32 s22, s46, s30
	s_cselect_b32 s21, vcc_lo, s17
	s_cselect_b32 s20, vcc_hi, s16
	v_lshl_add_u64 v[184:185], s[28:29], 0, v[130:131]
	v_lshl_add_u64 v[204:205], v[184:185], 0, s[80:81]
	s_add_i32 m0, s85, 0xc000
	ds_read_b128 v[164:167], v213
	ds_read_b128 v[168:171], v213 offset:1024
	ds_read_b128 v[172:175], v213 offset:2048
	ds_read_b128 v[176:179], v213 offset:3072
	ds_read_b128 v[180:183], v213 offset:4096
	ds_read_b128 v[190:193], v213 offset:5120
	ds_read_b128 v[196:199], v213 offset:6144
	ds_read_b128 v[200:203], v213 offset:7168
	global_load_lds_dwordx4 v[204:205], off
	v_lshl_add_u64 v[184:185], v[184:185], 0, s[82:83]
	s_add_i32 m0, s85, 0xe000
	s_nop 0
	global_load_lds_dwordx4 v[184:185], off
	.p2align 3
	s_waitcnt vmcnt(8)
	s_waitcnt lgkmcnt(0)
	s_setprio 1
	s_barrier
; #define PG8_STAGE(bufoff, gbase, unused) do { _Pragma("unroll") for (int _i = 0; _i < 2; ++_i) \
;         __builtin_amdgcn_global_load_lds((const unsigned*)((const char*)(gbase) + voff + _i * 8192), (LAS unsigned*)(lds + (bufoff) + ldsw + _i * 8192), 16, 0, 0); } while (0)
; #define PG8_LDA(dst, b, h) do { _Pragma("unroll") for (int m = 0; m < 4; ++m) _Pragma("unroll") for (int k = 0; k < 2; ++k) dst[m][k] = *(const LAS bf16x8*)(lds + PG8_SA(b, h) + aoff + m * 2048 + (FP8 ? k * 16 : k * 1024)); } while (0)
; #define PG8_LDB(dst, b, h) do { _Pragma("unroll") for (int n = 0; n < 2; ++n) _Pragma("unroll") for (int k = 0; k < 2; ++k) dst[n][k] = *(const LAS bf16x8*)(lds + PG8_SB(b, h) + boff + n * 2048 + (FP8 ? k * 16 : k * 1024)); } while (0)
; #define PG8_WAIT_V(n) asm volatile("s_waitcnt vmcnt(" #n ")" ::: "memory")
; #define PG8_WAIT_L(n) asm volatile("s_waitcnt lgkmcnt(" #n ")" ::: "memory")
; #define PG8_BAR __builtin_amdgcn_s_barrier()
; #define PG8_SCHED __builtin_amdgcn_sched_barrier(0)
; template <class Epi, class Sched, bool ALIGN_EPI, bool SP2, int MODE  >
; __device__ __forceinline__ void gemm_phase(LAS unsigned char* lds, const Gemm g, const Sched S, const Epi E, unsigned long long& probe_acc, int epi_id, int wv) {
;     ...
;             PG8_LDB(B0, 0, 0); PG8_LDB(B1, 0, 1); PG8_SCHED; PG8_LDA(At, 0, 0); PG8_STAGE(PG8_SA(1, 1), a1 + hA, voffA);
;             PG8_WAIT_V(8); PG8_WAIT_L(0); PG8_BAR; PG8_MMA(0, 0, At, B0); PG8_MMA(0, 1, At, B1); PG8_BAR; PG8_SCHED;
;             PG8_LDA(At, 0, 1); PG8_STAGE(PG8_SB(0, 0), b2, voffB); PG8_STAGE(PG8_SB(0, 1), b2 + hB, voffB); PG8_STAGE(PG8_SA(0, 0), a2, voffA);
;             PG8_WAIT_V(8); PG8_WAIT_L(0); PG8_BAR; PG8_MMA(1, 0, At, B0); PG8_MMA(1, 1, At, B1); PG8_BAR; PG8_SCHED;
;             PG8_LDB(B0, 1, 0); PG8_LDB(B1, 1, 1); PG8_SCHED; PG8_LDA(At, 1, 0); PG8_STAGE(PG8_SA(0, 1), a2 + hA, voffA);
;             PG8_WAIT_V(8); PG8_WAIT_L(0); PG8_BAR; PG8_MMA(0, 0, At, B0); PG8_MMA(0, 1, At, B1); PG8_BAR; PG8_SCHED;
;             PG8_LDA(At, 1, 1); PG8_STAGE(PG8_SB(1, 0), b3, voffB); PG8_STAGE(PG8_SB(1, 1), b3 + hB, voffB); PG8_STAGE(PG8_SA(1, 0), a3, voffA);
;             PG8_WAIT_V(8); PG8_WAIT_L(0); PG8_BAR; PG8_MMA(1, 0, At, B0); PG8_MMA(1, 1, At, B1); PG8_BAR; PG8_SCHED;
	v_mfma_i32_16x16x64_i8 v[126:129], v[132:135], v[164:167], v[126:129]
	v_mfma_i32_16x16x64_i8 v[102:105], v[140:143], v[164:167], v[102:105]
	v_mfma_i32_16x16x64_i8 v[122:125], v[132:135], v[172:175], v[122:125]
	v_mfma_i32_16x16x64_i8 v[94:97], v[140:143], v[172:175], v[94:97]
	v_mfma_i32_16x16x64_i8 v[118:121], v[132:135], v[180:183], v[118:121]
	v_mfma_i32_16x16x64_i8 v[46:49], v[140:143], v[180:183], v[46:49]
	v_mfma_i32_16x16x64_i8 v[110:113], v[132:135], v[196:199], v[110:113]
	v_mfma_i32_16x16x64_i8 v[38:41], v[140:143], v[196:199], v[38:41]
	v_mfma_i32_16x16x64_i8 v[126:129], v[136:139], v[168:171], v[126:129]
	v_mfma_i32_16x16x64_i8 v[102:105], v[144:147], v[168:171], v[102:105]
	v_mfma_i32_16x16x64_i8 v[122:125], v[136:139], v[176:179], v[122:125]
	v_mfma_i32_16x16x64_i8 v[94:97], v[144:147], v[176:179], v[94:97]
	v_mfma_i32_16x16x64_i8 v[118:121], v[136:139], v[190:193], v[118:121]
	v_mfma_i32_16x16x64_i8 v[46:49], v[144:147], v[190:193], v[46:49]
	v_mfma_i32_16x16x64_i8 v[110:113], v[136:139], v[200:203], v[110:113]
	v_mfma_i32_16x16x64_i8 v[38:41], v[144:147], v[200:203], v[38:41]
	v_mfma_i32_16x16x64_i8 v[114:117], v[148:151], v[164:167], v[114:117]
	v_mfma_i32_16x16x64_i8 v[82:85], v[156:159], v[164:167], v[82:85]
	v_mfma_i32_16x16x64_i8 v[106:109], v[148:151], v[172:175], v[106:109]
	v_mfma_i32_16x16x64_i8 v[74:77], v[156:159], v[172:175], v[74:77]
	v_mfma_i32_16x16x64_i8 v[98:101], v[148:151], v[180:183], v[98:101]
	v_mfma_i32_16x16x64_i8 v[42:45], v[156:159], v[180:183], v[42:45]
	v_mfma_i32_16x16x64_i8 v[90:93], v[148:151], v[196:199], v[90:93]
	v_mfma_i32_16x16x64_i8 v[34:37], v[156:159], v[196:199], v[34:37]
	v_mfma_i32_16x16x64_i8 v[114:117], v[152:155], v[168:171], v[114:117]
	v_mfma_i32_16x16x64_i8 v[82:85], v[160:163], v[168:171], v[82:85]
	v_mfma_i32_16x16x64_i8 v[106:109], v[152:155], v[176:179], v[106:109]
	v_mfma_i32_16x16x64_i8 v[74:77], v[160:163], v[176:179], v[74:77]
	v_mfma_i32_16x16x64_i8 v[98:101], v[152:155], v[190:193], v[98:101]
	v_mfma_i32_16x16x64_i8 v[42:45], v[160:163], v[190:193], v[42:45]
	v_mfma_i32_16x16x64_i8 v[90:93], v[152:155], v[200:203], v[90:93]
	v_mfma_i32_16x16x64_i8 v[34:37], v[160:163], v[200:203], v[34:37]
	s_barrier
	s_setprio 0
	s_mov_b32 m0, s41
	v_lshl_add_u64 v[184:185], s[20:21], 0, v[130:131]
	ds_read_b128 v[164:167], v213 offset:16384
	ds_read_b128 v[168:171], v213 offset:17408
	ds_read_b128 v[172:175], v213 offset:18432
	ds_read_b128 v[176:179], v213 offset:19456
	ds_read_b128 v[180:183], v213 offset:20480
	ds_read_b128 v[190:193], v213 offset:21504
	ds_read_b128 v[196:199], v213 offset:22528
	ds_read_b128 v[200:203], v213 offset:23552
	global_load_lds_dwordx4 v[184:185], off
	v_lshl_add_u64 v[204:205], v[184:185], 0, s[70:71]
	s_mov_b32 m0, s64
	s_nop 0
	global_load_lds_dwordx4 v[204:205], off
	v_lshl_add_u64 v[204:205], v[184:185], 0, s[72:73]
	s_mov_b32 m0, s68
	s_nop 0
	global_load_lds_dwordx4 v[204:205], off
	v_lshl_add_u64 v[204:205], v[184:185], 0, s[74:75]
	s_mov_b32 m0, s84
	s_nop 0
	global_load_lds_dwordx4 v[204:205], off
	v_lshl_add_u64 v[204:205], s[22:23], 0, v[130:131]
	s_mov_b32 m0, s85
	v_lshl_add_u64 v[206:207], v[204:205], 0, s[70:71]
	global_load_lds_dwordx4 v[204:205], off
	s_mov_b32 m0, s86
	s_nop 0
	global_load_lds_dwordx4 v[206:207], off
	.p2align 3
	s_waitcnt vmcnt(8)
	s_waitcnt lgkmcnt(0)
	s_setprio 1
	s_barrier
	v_mfma_i32_16x16x64_i8 v[86:89], v[132:135], v[164:167], v[86:89]
	v_mfma_i32_16x16x64_i8 v[30:33], v[140:143], v[164:167], v[30:33]
	v_mfma_i32_16x16x64_i8 v[78:81], v[132:135], v[172:175], v[78:81]
	v_mfma_i32_16x16x64_i8 v[22:25], v[140:143], v[172:175], v[22:25]
	v_mfma_i32_16x16x64_i8 v[70:73], v[132:135], v[180:183], v[70:73]
	v_mfma_i32_16x16x64_i8 v[14:17], v[140:143], v[180:183], v[14:17]
	v_mfma_i32_16x16x64_i8 v[62:65], v[132:135], v[196:199], v[62:65]
	v_mfma_i32_16x16x64_i8 v[2:5], v[140:143], v[196:199], v[2:5]
	v_mfma_i32_16x16x64_i8 v[86:89], v[136:139], v[168:171], v[86:89]
	v_mfma_i32_16x16x64_i8 v[30:33], v[144:147], v[168:171], v[30:33]
	v_mfma_i32_16x16x64_i8 v[78:81], v[136:139], v[176:179], v[78:81]
	v_mfma_i32_16x16x64_i8 v[22:25], v[144:147], v[176:179], v[22:25]
	v_mfma_i32_16x16x64_i8 v[70:73], v[136:139], v[190:193], v[70:73]
	v_mfma_i32_16x16x64_i8 v[14:17], v[144:147], v[190:193], v[14:17]
	v_mfma_i32_16x16x64_i8 v[62:65], v[136:139], v[200:203], v[62:65]
	v_mfma_i32_16x16x64_i8 v[2:5], v[144:147], v[200:203], v[2:5]
	v_mfma_i32_16x16x64_i8 v[66:69], v[148:151], v[164:167], v[66:69]
	v_mfma_i32_16x16x64_i8 v[26:29], v[156:159], v[164:167], v[26:29]
	v_mfma_i32_16x16x64_i8 v[58:61], v[148:151], v[172:175], v[58:61]
	v_mfma_i32_16x16x64_i8 v[18:21], v[156:159], v[172:175], v[18:21]
	v_mfma_i32_16x16x64_i8 v[54:57], v[148:151], v[180:183], v[54:57]
	v_mfma_i32_16x16x64_i8 v[10:13], v[156:159], v[180:183], v[10:13]
	v_mfma_i32_16x16x64_i8 v[50:53], v[148:151], v[196:199], v[50:53]
	v_mfma_i32_16x16x64_i8 v[6:9], v[156:159], v[196:199], v[6:9]
	v_mfma_i32_16x16x64_i8 v[66:69], v[152:155], v[168:171], v[66:69]
	v_mfma_i32_16x16x64_i8 v[26:29], v[160:163], v[168:171], v[26:29]
	v_mfma_i32_16x16x64_i8 v[58:61], v[152:155], v[176:179], v[58:61]
	v_mfma_i32_16x16x64_i8 v[18:21], v[160:163], v[176:179], v[18:21]
	v_mfma_i32_16x16x64_i8 v[54:57], v[152:155], v[190:193], v[54:57]
	v_mfma_i32_16x16x64_i8 v[10:13], v[160:163], v[190:193], v[10:13]
	v_mfma_i32_16x16x64_i8 v[50:53], v[152:155], v[200:203], v[50:53]
	v_mfma_i32_16x16x64_i8 v[6:9], v[160:163], v[200:203], v[6:9]
	s_barrier
; #define PG8_STAGE(bufoff, gbase, unused) do { _Pragma("unroll") for (int _i = 0; _i < 2; ++_i) \
;         __builtin_amdgcn_global_load_lds((const unsigned*)((const char*)(gbase) + voff + _i * 8192), (LAS unsigned*)(lds + (bufoff) + ldsw + _i * 8192), 16, 0, 0); } while (0)
; #define PG8_LDA(dst, b, h) do { _Pragma("unroll") for (int m = 0; m < 4; ++m) _Pragma("unroll") for (int k = 0; k < 2; ++k) dst[m][k] = *(const LAS bf16x8*)(lds + PG8_SA(b, h) + aoff + m * 2048 + (FP8 ? k * 16 : k * 1024)); } while (0)
; #define PG8_LDB(dst, b, h) do { _Pragma("unroll") for (int n = 0; n < 2; ++n) _Pragma("unroll") for (int k = 0; k < 2; ++k) dst[n][k] = *(const LAS bf16x8*)(lds + PG8_SB(b, h) + boff + n * 2048 + (FP8 ? k * 16 : k * 1024)); } while (0)
; #define PG8_WAIT_V(n) asm volatile("s_waitcnt vmcnt(" #n ")" ::: "memory")
; #define PG8_WAIT_L(n) asm volatile("s_waitcnt lgkmcnt(" #n ")" ::: "memory")
; #define PG8_BAR __builtin_amdgcn_s_barrier()
; #define PG8_SCHED __builtin_amdgcn_sched_barrier(0)
; template <class Epi, class Sched, bool ALIGN_EPI, bool SP2, int MODE  >
; __device__ __forceinline__ void gemm_phase(LAS unsigned char* lds, const Gemm g, const Sched S, const Epi E, unsigned long long& probe_acc, int epi_id, int wv) {
;     ...
;             PG8_LDB(B0, 0, 0); PG8_LDB(B1, 0, 1); PG8_SCHED; PG8_LDA(At, 0, 0); PG8_STAGE(PG8_SA(1, 1), a1 + hA, voffA);
;             PG8_WAIT_V(8); PG8_WAIT_L(0); PG8_BAR; PG8_MMA(0, 0, At, B0); PG8_MMA(0, 1, At, B1); PG8_BAR; PG8_SCHED;
;             PG8_LDA(At, 0, 1); PG8_STAGE(PG8_SB(0, 0), b2, voffB); PG8_STAGE(PG8_SB(0, 1), b2 + hB, voffB); PG8_STAGE(PG8_SA(0, 0), a2, voffA);
;             PG8_WAIT_V(8); PG8_WAIT_L(0); PG8_BAR; PG8_MMA(1, 0, At, B0); PG8_MMA(1, 1, At, B1); PG8_BAR; PG8_SCHED;
;             PG8_LDB(B0, 1, 0); PG8_LDB(B1, 1, 1); PG8_SCHED; PG8_LDA(At, 1, 0); PG8_STAGE(PG8_SA(0, 1), a2 + hA, voffA);
;             PG8_WAIT_V(8); PG8_WAIT_L(0); PG8_BAR; PG8_MMA(0, 0, At, B0); PG8_MMA(0, 1, At, B1); PG8_BAR; PG8_SCHED;
;             PG8_LDA(At, 1, 1); PG8_STAGE(PG8_SB(1, 0), b3, voffB); PG8_STAGE(PG8_SB(1, 1), b3 + hB, voffB); PG8_STAGE(PG8_SA(1, 0), a3, voffA);
;             PG8_WAIT_V(8); PG8_WAIT_L(0); PG8_BAR; PG8_MMA(1, 0, At, B0); PG8_MMA(1, 1, At, B1); PG8_BAR; PG8_SCHED;
	s_setprio 0
	v_add_u32_e32 v0, s90, v212
	ds_read_b128 v[132:135], v0
	ds_read_b128 v[136:139], v0 offset:1024
	ds_read_b128 v[140:143], v0 offset:2048
	ds_read_b128 v[144:147], v0 offset:3072
	v_add_u32_e32 v0, s95, v212
	ds_read_b128 v[148:151], v0
	ds_read_b128 v[152:155], v0 offset:1024
	ds_read_b128 v[156:159], v0 offset:2048
	ds_read_b128 v[160:163], v0 offset:3072
	s_mov_b32 m0, s87
	v_lshl_add_u64 v[206:207], v[204:205], 0, s[72:73]
	ds_read_b128 v[164:167], v213 offset:32768
	ds_read_b128 v[168:171], v213 offset:33792
	ds_read_b128 v[172:175], v213 offset:34816
	ds_read_b128 v[176:179], v213 offset:35840
	ds_read_b128 v[180:183], v213 offset:36864
	ds_read_b128 v[190:193], v213 offset:37888
	ds_read_b128 v[196:199], v213 offset:38912
	ds_read_b128 v[200:203], v213 offset:39936
	global_load_lds_dwordx4 v[206:207], off
	v_lshl_add_u64 v[206:207], v[204:205], 0, s[74:75]
	s_mov_b32 m0, s88
	s_nop 0
	global_load_lds_dwordx4 v[206:207], off
	.p2align 3
	s_waitcnt vmcnt(8)
	s_waitcnt lgkmcnt(0)
	s_setprio 1
	s_barrier
	v_mfma_i32_16x16x64_i8 v[126:129], v[132:135], v[164:167], v[126:129]
	v_mfma_i32_16x16x64_i8 v[102:105], v[140:143], v[164:167], v[102:105]
	v_mfma_i32_16x16x64_i8 v[122:125], v[132:135], v[172:175], v[122:125]
	v_mfma_i32_16x16x64_i8 v[94:97], v[140:143], v[172:175], v[94:97]
	v_mfma_i32_16x16x64_i8 v[118:121], v[132:135], v[180:183], v[118:121]
	v_mfma_i32_16x16x64_i8 v[46:49], v[140:143], v[180:183], v[46:49]
	v_mfma_i32_16x16x64_i8 v[110:113], v[132:135], v[196:199], v[110:113]
	v_mfma_i32_16x16x64_i8 v[38:41], v[140:143], v[196:199], v[38:41]
	v_mfma_i32_16x16x64_i8 v[126:129], v[136:139], v[168:171], v[126:129]
	v_mfma_i32_16x16x64_i8 v[102:105], v[144:147], v[168:171], v[102:105]
	v_mfma_i32_16x16x64_i8 v[122:125], v[136:139], v[176:179], v[122:125]
	v_mfma_i32_16x16x64_i8 v[94:97], v[144:147], v[176:179], v[94:97]
	v_mfma_i32_16x16x64_i8 v[118:121], v[136:139], v[190:193], v[118:121]
	v_mfma_i32_16x16x64_i8 v[46:49], v[144:147], v[190:193], v[46:49]
	v_mfma_i32_16x16x64_i8 v[110:113], v[136:139], v[200:203], v[110:113]
	v_mfma_i32_16x16x64_i8 v[38:41], v[144:147], v[200:203], v[38:41]
	v_mfma_i32_16x16x64_i8 v[114:117], v[148:151], v[164:167], v[114:117]
	v_mfma_i32_16x16x64_i8 v[82:85], v[156:159], v[164:167], v[82:85]
	v_mfma_i32_16x16x64_i8 v[106:109], v[148:151], v[172:175], v[106:109]
	v_mfma_i32_16x16x64_i8 v[74:77], v[156:159], v[172:175], v[74:77]
	v_mfma_i32_16x16x64_i8 v[98:101], v[148:151], v[180:183], v[98:101]
	v_mfma_i32_16x16x64_i8 v[42:45], v[156:159], v[180:183], v[42:45]
	v_mfma_i32_16x16x64_i8 v[90:93], v[148:151], v[196:199], v[90:93]
	v_mfma_i32_16x16x64_i8 v[34:37], v[156:159], v[196:199], v[34:37]
	v_mfma_i32_16x16x64_i8 v[114:117], v[152:155], v[168:171], v[114:117]
	v_mfma_i32_16x16x64_i8 v[82:85], v[160:163], v[168:171], v[82:85]
	v_mfma_i32_16x16x64_i8 v[106:109], v[152:155], v[176:179], v[106:109]
	v_mfma_i32_16x16x64_i8 v[74:77], v[160:163], v[176:179], v[74:77]
	v_mfma_i32_16x16x64_i8 v[98:101], v[152:155], v[190:193], v[98:101]
	v_mfma_i32_16x16x64_i8 v[42:45], v[160:163], v[190:193], v[42:45]
	v_mfma_i32_16x16x64_i8 v[90:93], v[152:155], v[200:203], v[90:93]
	v_mfma_i32_16x16x64_i8 v[34:37], v[160:163], v[200:203], v[34:37]
	s_barrier
	s_setprio 0
	s_mov_b32 m0, s91
	v_lshl_add_u64 v[206:207], v[184:185], 0, s[76:77]
	ds_read_b128 v[164:167], v213 offset:49152
	ds_read_b128 v[168:171], v213 offset:50176
	ds_read_b128 v[172:175], v213 offset:51200
	ds_read_b128 v[176:179], v213 offset:52224
	ds_read_b128 v[180:183], v213 offset:53248
	ds_read_b128 v[190:193], v213 offset:54272
	ds_read_b128 v[196:199], v213 offset:55296
	ds_read_b128 v[200:203], v213 offset:56320
	global_load_lds_dwordx4 v[206:207], off
	v_lshl_add_u64 v[206:207], v[184:185], 0, s[78:79]
	s_mov_b32 m0, s92
	s_nop 0
	global_load_lds_dwordx4 v[206:207], off
	v_lshl_add_u64 v[206:207], v[184:185], 0, s[80:81]
	s_mov_b32 m0, s2
	v_lshl_add_u64 v[184:185], v[184:185], 0, s[82:83]
	global_load_lds_dwordx4 v[206:207], off
	s_mov_b32 m0, s3
	s_nop 0
	global_load_lds_dwordx4 v[184:185], off
	v_lshl_add_u64 v[184:185], v[204:205], 0, s[76:77]
	s_mov_b32 m0, s93
	s_nop 0
	global_load_lds_dwordx4 v[184:185], off
	v_lshl_add_u64 v[184:185], v[204:205], 0, s[78:79]
	s_mov_b32 m0, s94
	s_nop 0
	global_load_lds_dwordx4 v[184:185], off
	.p2align 3
	s_waitcnt vmcnt(8)
	s_waitcnt lgkmcnt(0)
	s_setprio 1
	s_barrier
	v_mfma_i32_16x16x64_i8 v[86:89], v[132:135], v[164:167], v[86:89]
	v_mfma_i32_16x16x64_i8 v[30:33], v[140:143], v[164:167], v[30:33]
	v_mfma_i32_16x16x64_i8 v[78:81], v[132:135], v[172:175], v[78:81]
	v_mfma_i32_16x16x64_i8 v[22:25], v[140:143], v[172:175], v[22:25]
	v_mfma_i32_16x16x64_i8 v[70:73], v[132:135], v[180:183], v[70:73]
	v_mfma_i32_16x16x64_i8 v[14:17], v[140:143], v[180:183], v[14:17]
	v_mfma_i32_16x16x64_i8 v[62:65], v[132:135], v[196:199], v[62:65]
	v_mfma_i32_16x16x64_i8 v[2:5], v[140:143], v[196:199], v[2:5]
	v_mfma_i32_16x16x64_i8 v[86:89], v[136:139], v[168:171], v[86:89]
	v_mfma_i32_16x16x64_i8 v[30:33], v[144:147], v[168:171], v[30:33]
	v_mfma_i32_16x16x64_i8 v[78:81], v[136:139], v[176:179], v[78:81]
	v_mfma_i32_16x16x64_i8 v[22:25], v[144:147], v[176:179], v[22:25]
	v_mfma_i32_16x16x64_i8 v[70:73], v[136:139], v[190:193], v[70:73]
	v_mfma_i32_16x16x64_i8 v[14:17], v[144:147], v[190:193], v[14:17]
	v_mfma_i32_16x16x64_i8 v[62:65], v[136:139], v[200:203], v[62:65]
	v_mfma_i32_16x16x64_i8 v[2:5], v[144:147], v[200:203], v[2:5]
	v_mfma_i32_16x16x64_i8 v[66:69], v[148:151], v[164:167], v[66:69]
	v_mfma_i32_16x16x64_i8 v[26:29], v[156:159], v[164:167], v[26:29]
	v_mfma_i32_16x16x64_i8 v[58:61], v[148:151], v[172:175], v[58:61]
	v_mfma_i32_16x16x64_i8 v[18:21], v[156:159], v[172:175], v[18:21]
	v_mfma_i32_16x16x64_i8 v[54:57], v[148:151], v[180:183], v[54:57]
	v_mfma_i32_16x16x64_i8 v[10:13], v[156:159], v[180:183], v[10:13]
	v_mfma_i32_16x16x64_i8 v[50:53], v[148:151], v[196:199], v[50:53]
	v_mfma_i32_16x16x64_i8 v[6:9], v[156:159], v[196:199], v[6:9]
	v_mfma_i32_16x16x64_i8 v[66:69], v[152:155], v[168:171], v[66:69]
	v_mfma_i32_16x16x64_i8 v[26:29], v[160:163], v[168:171], v[26:29]
	v_mfma_i32_16x16x64_i8 v[58:61], v[152:155], v[176:179], v[58:61]
	v_mfma_i32_16x16x64_i8 v[18:21], v[160:163], v[176:179], v[18:21]
	v_mfma_i32_16x16x64_i8 v[54:57], v[152:155], v[190:193], v[54:57]
	v_mfma_i32_16x16x64_i8 v[10:13], v[160:163], v[190:193], v[10:13]
	v_mfma_i32_16x16x64_i8 v[50:53], v[152:155], v[200:203], v[50:53]
	v_mfma_i32_16x16x64_i8 v[6:9], v[160:163], v[200:203], v[6:9]
	s_barrier
	s_setprio 0
	s_add_i32 s14, s14, 2
	s_add_u32 s16, s16, 0x8000
	s_addc_u32 s17, s17, 0
	s_cmp_gt_u32 s14, 13
	s_mov_b64 s[28:29], s[30:31]
	s_cbranch_scc0 .LBB0_326
	v_readlane_b32 s14, v255, 11
	v_readlane_b32 s15, v255, 12
	s_and_b64 vcc, exec, s[14:15]
	s_cbranch_vccz .LBB0_329
	s_barrier

;     __device__ __forceinline__ bool next(int i, Unit& u) const { const int off = i * H + (r >> 1); if (off >= 8 * nN) return false; u.pm = 16 * g + 8 * (r & 1) + (off & 7); u.pn = off >> 3; return true; }
; #define PG8_STAGE(bufoff, gbase, unused) do { _Pragma("unroll") for (int _i = 0; _i < 2; ++_i) \
;         __builtin_amdgcn_global_load_lds((const unsigned*)((const char*)(gbase) + voff + _i * 8192), (LAS unsigned*)(lds + (bufoff) + ldsw + _i * 8192), 16, 0, 0); } while (0)
; #define PG8_LDA(dst, b, h) do { _Pragma("unroll") for (int m = 0; m < 4; ++m) _Pragma("unroll") for (int k = 0; k < 2; ++k) dst[m][k] = *(const LAS bf16x8*)(lds + PG8_SA(b, h) + aoff + m * 2048 + (FP8 ? k * 16 : k * 1024)); } while (0)
; #define PG8_LDB(dst, b, h) do { _Pragma("unroll") for (int n = 0; n < 2; ++n) _Pragma("unroll") for (int k = 0; k < 2; ++k) dst[n][k] = *(const LAS bf16x8*)(lds + PG8_SB(b, h) + boff + n * 2048 + (FP8 ? k * 16 : k * 1024)); } while (0)
; #define PG8_BAR __builtin_amdgcn_s_barrier()
; template <class Epi, class Sched, bool ALIGN_EPI, bool SP2, int MODE  >
; __device__ __forceinline__ void gemm_phase(LAS unsigned char* lds, const Gemm g, const Sched S, const Epi E, unsigned long long& probe_acc, int epi_id, int wv) {
;     ...
;         const bool has_next = S.next(ui + 1, nxt);
;         const char* nA = has_next ? (const char*)g.A + (size_t)nxt.pm * tA + (g.gt ? (size_t)(nxt.pn / g.gt) * gK2 : 0) : cA; const char* nB = has_next ? (const char*)g.Bt + (size_t)nxt.pn * tB : cB;
;         for (int t = 0; t < nt; t += 2) {
;             const bool last = (t == nt - 2);
;             const char* a1 = cA + (size_t)(t + 1) * kstep;
;             const char* a2 = last ? nA : cA + (size_t)(t + 2) * kstep; const char* b2 = last ? nB : cB + (size_t)(t + 2) * kstep;
;             const char* a3 = a2 + kstep; const char* b3 = b2 + kstep;
;             if constexpr (SP2) {
;             PG8_LDB(B0, 0, 0); PG8_LDB(B1, 0, 1); PG8_SCHED; PG8_LDA(At, 0, 0); PG8_STAGE(PG8_SA(1, 1), a1 + hA, voffA);
;             PG8_WAIT_V(8); PG8_WAIT_L(0); PG8_BAR; PG8_MMA(0, 0, At, B0); PG8_MMA(0, 1, At, B1); PG8_BAR; PG8_SCHED;
;             PG8_LDA(At, 0, 1); PG8_STAGE(PG8_SB(0, 0), b2, voffB); PG8_STAGE(PG8_SB(0, 1), b2 + hB, voffB); PG8_STAGE(PG8_SA(0, 0), a2, voffA);
;             PG8_WAIT_V(8); PG8_WAIT_L(0); PG8_BAR; PG8_MMA(1, 0, At, B0); PG8_MMA(1, 1, At, B1); PG8_BAR; PG8_SCHED;
.LBB0_364:
	s_mov_b64 s[20:21], s[4:5]
	s_add_i32 s84, s84, 1
	v_readlane_b32 s4, v254, 6
	s_mul_i32 s4, s84, s4
	v_readlane_b32 s5, v254, 35
	s_add_i32 s4, s4, s5
	s_cmpk_lt_i32 s4, 0xc0
	s_mov_b64 s[18:19], s[10:11]
	s_cselect_b64 s[16:17], -1, 0
	s_and_b32 s5, s4, 7
	v_readlane_b32 s10, v254, 18
	s_mov_b32 s8, s87
	s_mov_b32 s9, s86
	s_mov_b32 s88, s87
	s_mov_b32 s89, s86
	s_or_b32 s87, s5, s10
	s_ashr_i32 s86, s4, 3
	s_and_b64 s[4:5], s[16:17], exec
	s_cselect_b32 s10, s87, s8
	s_cselect_b32 s4, s86, s9
	s_ashr_i32 s11, s10, 31
	s_lshl_b64 s[10:11], s[10:11], 20
	s_add_u32 s10, s58, s10
	s_addc_u32 s11, s59, s11
	s_and_b64 s[90:91], s[16:17], exec
	s_cselect_b32 s46, s11, s19
	s_cselect_b32 s90, s10, s18
	s_ashr_i32 s5, s4, 31
	s_lshl_b64 s[4:5], s[4:5], 20
	s_add_u32 s4, s0, s4
	s_addc_u32 s5, s1, s5
	s_and_b64 s[92:93], s[16:17], exec
	s_cselect_b32 s91, s5, s21
	s_cselect_b32 s92, s4, s20
	s_add_u32 s93, s20, 0x8000
	s_addc_u32 s94, s21, 0
	s_mov_b32 s95, -2
	v_add_u32_e32 v0, s2, v166
	s_waitcnt vmcnt(0)
	ds_read_b128 v[130:133], v0
	ds_read_b128 v[134:137], v0 offset:1024
	ds_read_b128 v[138:141], v0 offset:2048
	ds_read_b128 v[142:145], v0 offset:3072
	v_add_u32_e32 v0, s23, v166
	ds_read_b128 v[146:149], v0
	ds_read_b128 v[150:153], v0 offset:1024
	s_waitcnt lgkmcnt(0)
	ds_read_b128 v[156:159], v0 offset:2048
	ds_read_b128 v[160:163], v0 offset:3072
	s_add_u32 s20, s18, 0x8000
	s_addc_u32 s21, s19, 0
	s_cmp_eq_u32 s95, 28
	s_cselect_b32 vcc_hi, s46, s21
	s_cselect_b32 vcc_lo, s90, s20
	s_cselect_b32 s9, s91, s94
	s_cselect_b32 s8, s92, s93
	v_lshl_add_u64 v[184:185], s[18:19], 0, v[154:155]
	v_lshl_add_u64 v[204:205], v[184:185], 0, s[52:53]
	s_add_i32 m0, s26, 0xc000
	ds_read_b128 v[168:171], v167
	ds_read_b128 v[172:175], v167 offset:1024
	ds_read_b128 v[176:179], v167 offset:2048
	ds_read_b128 v[180:183], v167 offset:3072
	ds_read_b128 v[188:191], v167 offset:4096
	ds_read_b128 v[192:195], v167 offset:5120
	ds_read_b128 v[196:199], v167 offset:6144
	ds_read_b128 v[200:203], v167 offset:7168
	global_load_lds_dwordx4 v[204:205], off
	v_lshl_add_u64 v[184:185], v[184:185], 0, s[54:55]
	s_add_i32 m0, s26, 0xe000
	s_nop 0
	global_load_lds_dwordx4 v[184:185], off
	.p2align 3
	s_waitcnt vmcnt(8)
	s_waitcnt lgkmcnt(0)
	s_setprio 1
	s_barrier
	v_mfma_f32_16x16x32_bf16 v[126:129], v[130:133], v[168:171], 0
	v_mfma_f32_16x16x32_bf16 v[122:125], v[138:141], v[168:171], 0
	v_mfma_f32_16x16x32_bf16 v[110:113], v[130:133], v[176:179], 0
	v_mfma_f32_16x16x32_bf16 v[106:109], v[138:141], v[176:179], 0
	v_mfma_f32_16x16x32_bf16 v[94:97], v[130:133], v[188:191], 0
	v_mfma_f32_16x16x32_bf16 v[90:93], v[138:141], v[188:191], 0
	v_mfma_f32_16x16x32_bf16 v[78:81], v[130:133], v[196:199], 0
	v_mfma_f32_16x16x32_bf16 v[74:77], v[138:141], v[196:199], 0
	v_mfma_f32_16x16x32_bf16 v[126:129], v[134:137], v[172:175], v[126:129]
	v_mfma_f32_16x16x32_bf16 v[122:125], v[142:145], v[172:175], v[122:125]
	v_mfma_f32_16x16x32_bf16 v[110:113], v[134:137], v[180:183], v[110:113]
	v_mfma_f32_16x16x32_bf16 v[106:109], v[142:145], v[180:183], v[106:109]
	v_mfma_f32_16x16x32_bf16 v[94:97], v[134:137], v[192:195], v[94:97]
	v_mfma_f32_16x16x32_bf16 v[90:93], v[142:145], v[192:195], v[90:93]
	v_mfma_f32_16x16x32_bf16 v[78:81], v[134:137], v[200:203], v[78:81]
	v_mfma_f32_16x16x32_bf16 v[74:77], v[142:145], v[200:203], v[74:77]
	v_mfma_f32_16x16x32_bf16 v[118:121], v[146:149], v[168:171], 0
	v_mfma_f32_16x16x32_bf16 v[114:117], v[156:159], v[168:171], 0
	v_mfma_f32_16x16x32_bf16 v[102:105], v[146:149], v[176:179], 0
	v_mfma_f32_16x16x32_bf16 v[98:101], v[156:159], v[176:179], 0
	v_mfma_f32_16x16x32_bf16 v[86:89], v[146:149], v[188:191], 0
	v_mfma_f32_16x16x32_bf16 v[82:85], v[156:159], v[188:191], 0
	v_mfma_f32_16x16x32_bf16 v[70:73], v[146:149], v[196:199], 0
	v_mfma_f32_16x16x32_bf16 v[66:69], v[156:159], v[196:199], 0
	v_mfma_f32_16x16x32_bf16 v[118:121], v[150:153], v[172:175], v[118:121]
	v_mfma_f32_16x16x32_bf16 v[114:117], v[160:163], v[172:175], v[114:117]
	v_mfma_f32_16x16x32_bf16 v[102:105], v[150:153], v[180:183], v[102:105]
	v_mfma_f32_16x16x32_bf16 v[98:101], v[160:163], v[180:183], v[98:101]
	v_mfma_f32_16x16x32_bf16 v[86:89], v[150:153], v[192:195], v[86:89]
	v_mfma_f32_16x16x32_bf16 v[82:85], v[160:163], v[192:195], v[82:85]
	v_mfma_f32_16x16x32_bf16 v[70:73], v[150:153], v[200:203], v[70:73]
	v_mfma_f32_16x16x32_bf16 v[66:69], v[160:163], v[200:203], v[66:69]
	s_barrier
	s_setprio 0
	s_mov_b32 m0, s3
	v_lshl_add_u64 v[184:185], s[8:9], 0, v[154:155]
	ds_read_b128 v[168:171], v167 offset:16384
	ds_read_b128 v[172:175], v167 offset:17408
	ds_read_b128 v[176:179], v167 offset:18432
	ds_read_b128 v[180:183], v167 offset:19456
	ds_read_b128 v[188:191], v167 offset:20480
	ds_read_b128 v[192:195], v167 offset:21504
	ds_read_b128 v[196:199], v167 offset:22528
	ds_read_b128 v[200:203], v167 offset:23552
	global_load_lds_dwordx4 v[184:185], off
	v_lshl_add_u64 v[204:205], v[184:185], 0, s[70:71]
	s_mov_b32 m0, s22
	s_nop 0
	global_load_lds_dwordx4 v[204:205], off
	v_lshl_add_u64 v[204:205], v[184:185], 0, s[96:97]
	s_mov_b32 m0, s24
	s_nop 0
	global_load_lds_dwordx4 v[204:205], off
	v_lshl_add_u64 v[204:205], v[184:185], 0, s[60:61]
	s_mov_b32 m0, s25
	s_nop 0
	global_load_lds_dwordx4 v[204:205], off
	v_lshl_add_u64 v[204:205], vcc, 0, v[154:155]
	s_mov_b32 m0, s26
	v_lshl_add_u64 v[206:207], v[204:205], 0, s[70:71]
	global_load_lds_dwordx4 v[204:205], off
	s_mov_b32 m0, s27
	s_nop 0
	global_load_lds_dwordx4 v[206:207], off
	.p2align 3
	s_waitcnt vmcnt(8)
	s_waitcnt lgkmcnt(0)
	s_setprio 1
	s_barrier
; #define PG8_STAGE(bufoff, gbase, unused) do { _Pragma("unroll") for (int _i = 0; _i < 2; ++_i) \
;         __builtin_amdgcn_global_load_lds((const unsigned*)((const char*)(gbase) + voff + _i * 8192), (LAS unsigned*)(lds + (bufoff) + ldsw + _i * 8192), 16, 0, 0); } while (0)
; #define PG8_LDA(dst, b, h) do { _Pragma("unroll") for (int m = 0; m < 4; ++m) _Pragma("unroll") for (int k = 0; k < 2; ++k) dst[m][k] = *(const LAS bf16x8*)(lds + PG8_SA(b, h) + aoff + m * 2048 + (FP8 ? k * 16 : k * 1024)); } while (0)
; #define PG8_LDB(dst, b, h) do { _Pragma("unroll") for (int n = 0; n < 2; ++n) _Pragma("unroll") for (int k = 0; k < 2; ++k) dst[n][k] = *(const LAS bf16x8*)(lds + PG8_SB(b, h) + boff + n * 2048 + (FP8 ? k * 16 : k * 1024)); } while (0)
; #define PG8_WAIT_V(n) asm volatile("s_waitcnt vmcnt(" #n ")" ::: "memory")
; #define PG8_WAIT_L(n) asm volatile("s_waitcnt lgkmcnt(" #n ")" ::: "memory")
; #define PG8_BAR __builtin_amdgcn_s_barrier()
; #define PG8_SCHED __builtin_amdgcn_sched_barrier(0)
; template <class Epi, class Sched, bool ALIGN_EPI, bool SP2, int MODE  >
; __device__ __forceinline__ void gemm_phase(LAS unsigned char* lds, const Gemm g, const Sched S, const Epi E, unsigned long long& probe_acc, int epi_id, int wv) {
;     ...
;             PG8_WAIT_V(8); PG8_WAIT_L(0); PG8_BAR; PG8_MMA(0, 0, At, B0); PG8_MMA(0, 1, At, B1); PG8_BAR; PG8_SCHED;
;             PG8_LDA(At, 0, 1); PG8_STAGE(PG8_SB(0, 0), b2, voffB); PG8_STAGE(PG8_SB(0, 1), b2 + hB, voffB); PG8_STAGE(PG8_SA(0, 0), a2, voffA);
;             PG8_WAIT_V(8); PG8_WAIT_L(0); PG8_BAR; PG8_MMA(1, 0, At, B0); PG8_MMA(1, 1, At, B1); PG8_BAR; PG8_SCHED;
;             PG8_LDB(B0, 1, 0); PG8_LDB(B1, 1, 1); PG8_SCHED; PG8_LDA(At, 1, 0); PG8_STAGE(PG8_SA(0, 1), a2 + hA, voffA);
;             PG8_WAIT_V(8); PG8_WAIT_L(0); PG8_BAR; PG8_MMA(0, 0, At, B0); PG8_MMA(0, 1, At, B1); PG8_BAR; PG8_SCHED;
;             PG8_LDA(At, 1, 1); PG8_STAGE(PG8_SB(1, 0), b3, voffB); PG8_STAGE(PG8_SB(1, 1), b3 + hB, voffB); PG8_STAGE(PG8_SA(1, 0), a3, voffA);
;             PG8_WAIT_V(8); PG8_WAIT_L(0); PG8_BAR; PG8_MMA(1, 0, At, B0); PG8_MMA(1, 1, At, B1); PG8_BAR; PG8_SCHED;
	v_mfma_f32_16x16x32_bf16 v[62:65], v[130:133], v[168:171], 0
	v_mfma_f32_16x16x32_bf16 v[58:61], v[138:141], v[168:171], 0
	v_mfma_f32_16x16x32_bf16 v[46:49], v[130:133], v[176:179], 0
	v_mfma_f32_16x16x32_bf16 v[42:45], v[138:141], v[176:179], 0
	v_mfma_f32_16x16x32_bf16 v[30:33], v[130:133], v[188:191], 0
	v_mfma_f32_16x16x32_bf16 v[26:29], v[138:141], v[188:191], 0
	v_mfma_f32_16x16x32_bf16 v[14:17], v[130:133], v[196:199], 0
	v_mfma_f32_16x16x32_bf16 v[10:13], v[138:141], v[196:199], 0
	v_mfma_f32_16x16x32_bf16 v[62:65], v[134:137], v[172:175], v[62:65]
	v_mfma_f32_16x16x32_bf16 v[58:61], v[142:145], v[172:175], v[58:61]
	v_mfma_f32_16x16x32_bf16 v[46:49], v[134:137], v[180:183], v[46:49]
	v_mfma_f32_16x16x32_bf16 v[42:45], v[142:145], v[180:183], v[42:45]
	v_mfma_f32_16x16x32_bf16 v[30:33], v[134:137], v[192:195], v[30:33]
	v_mfma_f32_16x16x32_bf16 v[26:29], v[142:145], v[192:195], v[26:29]
	v_mfma_f32_16x16x32_bf16 v[14:17], v[134:137], v[200:203], v[14:17]
	v_mfma_f32_16x16x32_bf16 v[10:13], v[142:145], v[200:203], v[10:13]
	v_mfma_f32_16x16x32_bf16 v[54:57], v[146:149], v[168:171], 0
	v_mfma_f32_16x16x32_bf16 v[50:53], v[156:159], v[168:171], 0
	v_mfma_f32_16x16x32_bf16 v[38:41], v[146:149], v[176:179], 0
	v_mfma_f32_16x16x32_bf16 v[34:37], v[156:159], v[176:179], 0
	v_mfma_f32_16x16x32_bf16 v[22:25], v[146:149], v[188:191], 0
	v_mfma_f32_16x16x32_bf16 v[18:21], v[156:159], v[188:191], 0
	v_mfma_f32_16x16x32_bf16 v[6:9], v[146:149], v[196:199], 0
	v_mfma_f32_16x16x32_bf16 v[2:5], v[156:159], v[196:199], 0
	v_mfma_f32_16x16x32_bf16 v[54:57], v[150:153], v[172:175], v[54:57]
	v_mfma_f32_16x16x32_bf16 v[50:53], v[160:163], v[172:175], v[50:53]
	v_mfma_f32_16x16x32_bf16 v[38:41], v[150:153], v[180:183], v[38:41]
	v_mfma_f32_16x16x32_bf16 v[34:37], v[160:163], v[180:183], v[34:37]
	v_mfma_f32_16x16x32_bf16 v[22:25], v[150:153], v[192:195], v[22:25]
	v_mfma_f32_16x16x32_bf16 v[18:21], v[160:163], v[192:195], v[18:21]
	v_mfma_f32_16x16x32_bf16 v[6:9], v[150:153], v[200:203], v[6:9]
	v_mfma_f32_16x16x32_bf16 v[2:5], v[160:163], v[200:203], v[2:5]
	s_barrier
	s_setprio 0
	v_add_u32_e32 v0, s31, v166
	ds_read_b128 v[130:133], v0
	ds_read_b128 v[134:137], v0 offset:1024
	ds_read_b128 v[138:141], v0 offset:2048
	ds_read_b128 v[142:145], v0 offset:3072
	v_add_u32_e32 v0, s39, v166
	ds_read_b128 v[146:149], v0
	ds_read_b128 v[150:153], v0 offset:1024
	ds_read_b128 v[156:159], v0 offset:2048
	ds_read_b128 v[160:163], v0 offset:3072
	s_mov_b32 m0, s28
	v_lshl_add_u64 v[206:207], v[204:205], 0, s[96:97]
	ds_read_b128 v[168:171], v167 offset:32768
	ds_read_b128 v[172:175], v167 offset:33792
	ds_read_b128 v[176:179], v167 offset:34816
	ds_read_b128 v[180:183], v167 offset:35840
	ds_read_b128 v[188:191], v167 offset:36864
	ds_read_b128 v[192:195], v167 offset:37888
	ds_read_b128 v[196:199], v167 offset:38912
	ds_read_b128 v[200:203], v167 offset:39936
	global_load_lds_dwordx4 v[206:207], off
	v_lshl_add_u64 v[206:207], v[204:205], 0, s[60:61]
	s_mov_b32 m0, s29
	s_nop 0
	global_load_lds_dwordx4 v[206:207], off
	.p2align 3
	s_waitcnt vmcnt(8)
	s_waitcnt lgkmcnt(0)
	s_setprio 1
	s_barrier
	v_mfma_f32_16x16x32_bf16 v[126:129], v[130:133], v[168:171], v[126:129]
	v_mfma_f32_16x16x32_bf16 v[122:125], v[138:141], v[168:171], v[122:125]
	v_mfma_f32_16x16x32_bf16 v[110:113], v[130:133], v[176:179], v[110:113]
	v_mfma_f32_16x16x32_bf16 v[106:109], v[138:141], v[176:179], v[106:109]
	v_mfma_f32_16x16x32_bf16 v[94:97], v[130:133], v[188:191], v[94:97]
	v_mfma_f32_16x16x32_bf16 v[90:93], v[138:141], v[188:191], v[90:93]
	v_mfma_f32_16x16x32_bf16 v[78:81], v[130:133], v[196:199], v[78:81]
	v_mfma_f32_16x16x32_bf16 v[74:77], v[138:141], v[196:199], v[74:77]
	v_mfma_f32_16x16x32_bf16 v[126:129], v[134:137], v[172:175], v[126:129]
	v_mfma_f32_16x16x32_bf16 v[122:125], v[142:145], v[172:175], v[122:125]
	v_mfma_f32_16x16x32_bf16 v[110:113], v[134:137], v[180:183], v[110:113]
	v_mfma_f32_16x16x32_bf16 v[106:109], v[142:145], v[180:183], v[106:109]
	v_mfma_f32_16x16x32_bf16 v[94:97], v[134:137], v[192:195], v[94:97]
	v_mfma_f32_16x16x32_bf16 v[90:93], v[142:145], v[192:195], v[90:93]
	v_mfma_f32_16x16x32_bf16 v[78:81], v[134:137], v[200:203], v[78:81]
	v_mfma_f32_16x16x32_bf16 v[74:77], v[142:145], v[200:203], v[74:77]
	v_mfma_f32_16x16x32_bf16 v[118:121], v[146:149], v[168:171], v[118:121]
	v_mfma_f32_16x16x32_bf16 v[114:117], v[156:159], v[168:171], v[114:117]
	v_mfma_f32_16x16x32_bf16 v[102:105], v[146:149], v[176:179], v[102:105]
	v_mfma_f32_16x16x32_bf16 v[98:101], v[156:159], v[176:179], v[98:101]
	v_mfma_f32_16x16x32_bf16 v[86:89], v[146:149], v[188:191], v[86:89]
	v_mfma_f32_16x16x32_bf16 v[82:85], v[156:159], v[188:191], v[82:85]
	v_mfma_f32_16x16x32_bf16 v[70:73], v[146:149], v[196:199], v[70:73]
	v_mfma_f32_16x16x32_bf16 v[66:69], v[156:159], v[196:199], v[66:69]
	v_mfma_f32_16x16x32_bf16 v[118:121], v[150:153], v[172:175], v[118:121]
	v_mfma_f32_16x16x32_bf16 v[114:117], v[160:163], v[172:175], v[114:117]
	v_mfma_f32_16x16x32_bf16 v[102:105], v[150:153], v[180:183], v[102:105]
	v_mfma_f32_16x16x32_bf16 v[98:101], v[160:163], v[180:183], v[98:101]
	v_mfma_f32_16x16x32_bf16 v[86:89], v[150:153], v[192:195], v[86:89]
	v_mfma_f32_16x16x32_bf16 v[82:85], v[160:163], v[192:195], v[82:85]
	v_mfma_f32_16x16x32_bf16 v[70:73], v[150:153], v[200:203], v[70:73]
	v_mfma_f32_16x16x32_bf16 v[66:69], v[160:163], v[200:203], v[66:69]
	s_barrier
; #define PG8_STAGE(bufoff, gbase, unused) do { _Pragma("unroll") for (int _i = 0; _i < 2; ++_i) \
;         __builtin_amdgcn_global_load_lds((const unsigned*)((const char*)(gbase) + voff + _i * 8192), (LAS unsigned*)(lds + (bufoff) + ldsw + _i * 8192), 16, 0, 0); } while (0)
; #define PG8_LDA(dst, b, h) do { _Pragma("unroll") for (int m = 0; m < 4; ++m) _Pragma("unroll") for (int k = 0; k < 2; ++k) dst[m][k] = *(const LAS bf16x8*)(lds + PG8_SA(b, h) + aoff + m * 2048 + (FP8 ? k * 16 : k * 1024)); } while (0)
; #define PG8_LDB(dst, b, h) do { _Pragma("unroll") for (int n = 0; n < 2; ++n) _Pragma("unroll") for (int k = 0; k < 2; ++k) dst[n][k] = *(const LAS bf16x8*)(lds + PG8_SB(b, h) + boff + n * 2048 + (FP8 ? k * 16 : k * 1024)); } while (0)
; template <class Epi, class Sched, bool ALIGN_EPI, bool SP2, int MODE  >
; __device__ __forceinline__ void gemm_phase(LAS unsigned char* lds, const Gemm g, const Sched S, const Epi E, unsigned long long& probe_acc, int epi_id, int wv) {
;     ...
;         for (int t = 0; t < nt; t += 2) {
;             const bool last = (t == nt - 2);
;             const char* a1 = cA + (size_t)(t + 1) * kstep;
;             const char* a2 = last ? nA : cA + (size_t)(t + 2) * kstep; const char* b2 = last ? nB : cB + (size_t)(t + 2) * kstep;
;             const char* a3 = a2 + kstep; const char* b3 = b2 + kstep;
;             if constexpr (SP2) {
;             PG8_LDB(B0, 0, 0); PG8_LDB(B1, 0, 1); PG8_SCHED; PG8_LDA(At, 0, 0); PG8_STAGE(PG8_SA(1, 1), a1 + hA, voffA);
;             PG8_WAIT_V(8); PG8_WAIT_L(0); PG8_BAR; PG8_MMA(0, 0, At, B0); PG8_MMA(0, 1, At, B1); PG8_BAR; PG8_SCHED;
;             PG8_LDA(At, 0, 1); PG8_STAGE(PG8_SB(0, 0), b2, voffB); PG8_STAGE(PG8_SB(0, 1), b2 + hB, voffB); PG8_STAGE(PG8_SA(0, 0), a2, voffA);
;             PG8_WAIT_V(8); PG8_WAIT_L(0); PG8_BAR; PG8_MMA(1, 0, At, B0); PG8_MMA(1, 1, At, B1); PG8_BAR; PG8_SCHED;
;             PG8_LDB(B0, 1, 0); PG8_LDB(B1, 1, 1); PG8_SCHED; PG8_LDA(At, 1, 0); PG8_STAGE(PG8_SA(0, 1), a2 + hA, voffA);
;             PG8_WAIT_V(8); PG8_WAIT_L(0); PG8_BAR; PG8_MMA(0, 0, At, B0); PG8_MMA(0, 1, At, B1); PG8_BAR; PG8_SCHED;
;             PG8_LDA(At, 1, 1); PG8_STAGE(PG8_SB(1, 0), b3, voffB); PG8_STAGE(PG8_SB(1, 1), b3 + hB, voffB); PG8_STAGE(PG8_SA(1, 0), a3, voffA);
;             PG8_WAIT_V(8); PG8_WAIT_L(0); PG8_BAR; PG8_MMA(1, 0, At, B0); PG8_MMA(1, 1, At, B1); PG8_BAR; PG8_SCHED;
	s_setprio 0
	s_mov_b32 m0, s34
	v_lshl_add_u64 v[206:207], v[184:185], 0, s[76:77]
	ds_read_b128 v[168:171], v167 offset:49152
	ds_read_b128 v[172:175], v167 offset:50176
	ds_read_b128 v[176:179], v167 offset:51200
	ds_read_b128 v[180:183], v167 offset:52224
	ds_read_b128 v[188:191], v167 offset:53248
	ds_read_b128 v[192:195], v167 offset:54272
	ds_read_b128 v[196:199], v167 offset:55296
	ds_read_b128 v[200:203], v167 offset:56320
	global_load_lds_dwordx4 v[206:207], off
	v_lshl_add_u64 v[206:207], v[184:185], 0, s[78:79]
	s_mov_b32 m0, s35
	s_nop 0
	global_load_lds_dwordx4 v[206:207], off
	v_lshl_add_u64 v[206:207], v[184:185], 0, s[52:53]
	s_mov_b32 m0, s40
	v_lshl_add_u64 v[184:185], v[184:185], 0, s[54:55]
	global_load_lds_dwordx4 v[206:207], off
	s_mov_b32 m0, s41
	s_nop 0
	global_load_lds_dwordx4 v[184:185], off
	v_lshl_add_u64 v[184:185], v[204:205], 0, s[76:77]
	s_mov_b32 m0, s36
	s_nop 0
	global_load_lds_dwordx4 v[184:185], off
	v_lshl_add_u64 v[184:185], v[204:205], 0, s[78:79]
	s_mov_b32 m0, s37
	s_nop 0
	global_load_lds_dwordx4 v[184:185], off
	.p2align 3
	s_waitcnt vmcnt(8)
	s_waitcnt lgkmcnt(0)
	s_setprio 1
	s_barrier
	v_mfma_f32_16x16x32_bf16 v[62:65], v[130:133], v[168:171], v[62:65]
	v_mfma_f32_16x16x32_bf16 v[58:61], v[138:141], v[168:171], v[58:61]
	v_mfma_f32_16x16x32_bf16 v[46:49], v[130:133], v[176:179], v[46:49]
	v_mfma_f32_16x16x32_bf16 v[42:45], v[138:141], v[176:179], v[42:45]
	v_mfma_f32_16x16x32_bf16 v[30:33], v[130:133], v[188:191], v[30:33]
	v_mfma_f32_16x16x32_bf16 v[26:29], v[138:141], v[188:191], v[26:29]
	v_mfma_f32_16x16x32_bf16 v[14:17], v[130:133], v[196:199], v[14:17]
	v_mfma_f32_16x16x32_bf16 v[10:13], v[138:141], v[196:199], v[10:13]
	v_mfma_f32_16x16x32_bf16 v[62:65], v[134:137], v[172:175], v[62:65]
	v_mfma_f32_16x16x32_bf16 v[58:61], v[142:145], v[172:175], v[58:61]
	v_mfma_f32_16x16x32_bf16 v[46:49], v[134:137], v[180:183], v[46:49]
	v_mfma_f32_16x16x32_bf16 v[42:45], v[142:145], v[180:183], v[42:45]
	v_mfma_f32_16x16x32_bf16 v[30:33], v[134:137], v[192:195], v[30:33]
	v_mfma_f32_16x16x32_bf16 v[26:29], v[142:145], v[192:195], v[26:29]
	v_mfma_f32_16x16x32_bf16 v[14:17], v[134:137], v[200:203], v[14:17]
	v_mfma_f32_16x16x32_bf16 v[10:13], v[142:145], v[200:203], v[10:13]
	v_mfma_f32_16x16x32_bf16 v[54:57], v[146:149], v[168:171], v[54:57]
	v_mfma_f32_16x16x32_bf16 v[50:53], v[156:159], v[168:171], v[50:53]
	v_mfma_f32_16x16x32_bf16 v[38:41], v[146:149], v[176:179], v[38:41]
	v_mfma_f32_16x16x32_bf16 v[34:37], v[156:159], v[176:179], v[34:37]
	v_mfma_f32_16x16x32_bf16 v[22:25], v[146:149], v[188:191], v[22:25]
	v_mfma_f32_16x16x32_bf16 v[18:21], v[156:159], v[188:191], v[18:21]
	v_mfma_f32_16x16x32_bf16 v[6:9], v[146:149], v[196:199], v[6:9]
	v_mfma_f32_16x16x32_bf16 v[2:5], v[156:159], v[196:199], v[2:5]
	v_mfma_f32_16x16x32_bf16 v[54:57], v[150:153], v[172:175], v[54:57]
	v_mfma_f32_16x16x32_bf16 v[50:53], v[160:163], v[172:175], v[50:53]
	v_mfma_f32_16x16x32_bf16 v[38:41], v[150:153], v[180:183], v[38:41]
	v_mfma_f32_16x16x32_bf16 v[34:37], v[160:163], v[180:183], v[34:37]
	v_mfma_f32_16x16x32_bf16 v[22:25], v[150:153], v[192:195], v[22:25]
	v_mfma_f32_16x16x32_bf16 v[18:21], v[160:163], v[192:195], v[18:21]
	v_mfma_f32_16x16x32_bf16 v[6:9], v[150:153], v[200:203], v[6:9]
	v_mfma_f32_16x16x32_bf16 v[2:5], v[160:163], v[200:203], v[2:5]
	s_barrier
	s_setprio 0
	s_add_i32 s95, s95, 2
	s_add_u32 s93, s93, 0x8000
	s_addc_u32 s94, s94, 0
	s_cmp_gt_u32 s95, 29
	s_mov_b64 s[18:19], s[20:21]
.LBB0_365:
	v_add_u32_e32 v0, s2, v166
	s_waitcnt vmcnt(0)
	ds_read_b128 v[130:133], v0
	ds_read_b128 v[134:137], v0 offset:1024
	ds_read_b128 v[138:141], v0 offset:2048
	ds_read_b128 v[142:145], v0 offset:3072
	v_add_u32_e32 v0, s23, v166
	ds_read_b128 v[146:149], v0
	ds_read_b128 v[150:153], v0 offset:1024
	s_waitcnt lgkmcnt(0)
	ds_read_b128 v[156:159], v0 offset:2048
	ds_read_b128 v[160:163], v0 offset:3072
	s_add_u32 s20, s18, 0x8000
	s_addc_u32 s21, s19, 0
	s_cmp_eq_u32 s95, 28
	s_cselect_b32 vcc_hi, s46, s21
	s_cselect_b32 vcc_lo, s90, s20
	s_cselect_b32 s9, s91, s94
	s_cselect_b32 s8, s92, s93
	v_lshl_add_u64 v[184:185], s[18:19], 0, v[154:155]
	v_lshl_add_u64 v[204:205], v[184:185], 0, s[52:53]
	s_add_i32 m0, s26, 0xc000
	ds_read_b128 v[168:171], v167
	ds_read_b128 v[172:175], v167 offset:1024
	ds_read_b128 v[176:179], v167 offset:2048
	ds_read_b128 v[180:183], v167 offset:3072
	ds_read_b128 v[188:191], v167 offset:4096
	ds_read_b128 v[192:195], v167 offset:5120
	ds_read_b128 v[196:199], v167 offset:6144
	ds_read_b128 v[200:203], v167 offset:7168
	global_load_lds_dwordx4 v[204:205], off
	v_lshl_add_u64 v[184:185], v[184:185], 0, s[54:55]
	s_add_i32 m0, s26, 0xe000
	s_nop 0
	global_load_lds_dwordx4 v[184:185], off
	.p2align 3
	s_waitcnt vmcnt(8)
	s_waitcnt lgkmcnt(0)
	s_setprio 1
	s_barrier
; #define PG8_STAGE(bufoff, gbase, unused) do { _Pragma("unroll") for (int _i = 0; _i < 2; ++_i) \
;         __builtin_amdgcn_global_load_lds((const unsigned*)((const char*)(gbase) + voff + _i * 8192), (LAS unsigned*)(lds + (bufoff) + ldsw + _i * 8192), 16, 0, 0); } while (0)
; #define PG8_LDA(dst, b, h) do { _Pragma("unroll") for (int m = 0; m < 4; ++m) _Pragma("unroll") for (int k = 0; k < 2; ++k) dst[m][k] = *(const LAS bf16x8*)(lds + PG8_SA(b, h) + aoff + m * 2048 + (FP8 ? k * 16 : k * 1024)); } while (0)
; #define PG8_LDB(dst, b, h) do { _Pragma("unroll") for (int n = 0; n < 2; ++n) _Pragma("unroll") for (int k = 0; k < 2; ++k) dst[n][k] = *(const LAS bf16x8*)(lds + PG8_SB(b, h) + boff + n * 2048 + (FP8 ? k * 16 : k * 1024)); } while (0)
; #define PG8_WAIT_V(n) asm volatile("s_waitcnt vmcnt(" #n ")" ::: "memory")
; #define PG8_WAIT_L(n) asm volatile("s_waitcnt lgkmcnt(" #n ")" ::: "memory")
; #define PG8_BAR __builtin_amdgcn_s_barrier()
; #define PG8_SCHED __builtin_amdgcn_sched_barrier(0)
; template <class Epi, class Sched, bool ALIGN_EPI, bool SP2, int MODE  >
; __device__ __forceinline__ void gemm_phase(LAS unsigned char* lds, const Gemm g, const Sched S, const Epi E, unsigned long long& probe_acc, int epi_id, int wv) {
;     ...
;             PG8_LDB(B0, 0, 0); PG8_LDB(B1, 0, 1); PG8_SCHED; PG8_LDA(At, 0, 0); PG8_STAGE(PG8_SA(1, 1), a1 + hA, voffA);
;             PG8_WAIT_V(8); PG8_WAIT_L(0); PG8_BAR; PG8_MMA(0, 0, At, B0); PG8_MMA(0, 1, At, B1); PG8_BAR; PG8_SCHED;
;             PG8_LDA(At, 0, 1); PG8_STAGE(PG8_SB(0, 0), b2, voffB); PG8_STAGE(PG8_SB(0, 1), b2 + hB, voffB); PG8_STAGE(PG8_SA(0, 0), a2, voffA);
;             PG8_WAIT_V(8); PG8_WAIT_L(0); PG8_BAR; PG8_MMA(1, 0, At, B0); PG8_MMA(1, 1, At, B1); PG8_BAR; PG8_SCHED;
;             PG8_LDB(B0, 1, 0); PG8_LDB(B1, 1, 1); PG8_SCHED; PG8_LDA(At, 1, 0); PG8_STAGE(PG8_SA(0, 1), a2 + hA, voffA);
;             PG8_WAIT_V(8); PG8_WAIT_L(0); PG8_BAR; PG8_MMA(0, 0, At, B0); PG8_MMA(0, 1, At, B1); PG8_BAR; PG8_SCHED;
	v_mfma_f32_16x16x32_bf16 v[126:129], v[130:133], v[168:171], v[126:129]
	v_mfma_f32_16x16x32_bf16 v[122:125], v[138:141], v[168:171], v[122:125]
	v_mfma_f32_16x16x32_bf16 v[110:113], v[130:133], v[176:179], v[110:113]
	v_mfma_f32_16x16x32_bf16 v[106:109], v[138:141], v[176:179], v[106:109]
	v_mfma_f32_16x16x32_bf16 v[94:97], v[130:133], v[188:191], v[94:97]
	v_mfma_f32_16x16x32_bf16 v[90:93], v[138:141], v[188:191], v[90:93]
	v_mfma_f32_16x16x32_bf16 v[78:81], v[130:133], v[196:199], v[78:81]
	v_mfma_f32_16x16x32_bf16 v[74:77], v[138:141], v[196:199], v[74:77]
	v_mfma_f32_16x16x32_bf16 v[126:129], v[134:137], v[172:175], v[126:129]
	v_mfma_f32_16x16x32_bf16 v[122:125], v[142:145], v[172:175], v[122:125]
	v_mfma_f32_16x16x32_bf16 v[110:113], v[134:137], v[180:183], v[110:113]
	v_mfma_f32_16x16x32_bf16 v[106:109], v[142:145], v[180:183], v[106:109]
	v_mfma_f32_16x16x32_bf16 v[94:97], v[134:137], v[192:195], v[94:97]
	v_mfma_f32_16x16x32_bf16 v[90:93], v[142:145], v[192:195], v[90:93]
	v_mfma_f32_16x16x32_bf16 v[78:81], v[134:137], v[200:203], v[78:81]
	v_mfma_f32_16x16x32_bf16 v[74:77], v[142:145], v[200:203], v[74:77]
	v_mfma_f32_16x16x32_bf16 v[118:121], v[146:149], v[168:171], v[118:121]
	v_mfma_f32_16x16x32_bf16 v[114:117], v[156:159], v[168:171], v[114:117]
	v_mfma_f32_16x16x32_bf16 v[102:105], v[146:149], v[176:179], v[102:105]
	v_mfma_f32_16x16x32_bf16 v[98:101], v[156:159], v[176:179], v[98:101]
	v_mfma_f32_16x16x32_bf16 v[86:89], v[146:149], v[188:191], v[86:89]
	v_mfma_f32_16x16x32_bf16 v[82:85], v[156:159], v[188:191], v[82:85]
	v_mfma_f32_16x16x32_bf16 v[70:73], v[146:149], v[196:199], v[70:73]
	v_mfma_f32_16x16x32_bf16 v[66:69], v[156:159], v[196:199], v[66:69]
	v_mfma_f32_16x16x32_bf16 v[118:121], v[150:153], v[172:175], v[118:121]
	v_mfma_f32_16x16x32_bf16 v[114:117], v[160:163], v[172:175], v[114:117]
	v_mfma_f32_16x16x32_bf16 v[102:105], v[150:153], v[180:183], v[102:105]
	v_mfma_f32_16x16x32_bf16 v[98:101], v[160:163], v[180:183], v[98:101]
	v_mfma_f32_16x16x32_bf16 v[86:89], v[150:153], v[192:195], v[86:89]
	v_mfma_f32_16x16x32_bf16 v[82:85], v[160:163], v[192:195], v[82:85]
	v_mfma_f32_16x16x32_bf16 v[70:73], v[150:153], v[200:203], v[70:73]
	v_mfma_f32_16x16x32_bf16 v[66:69], v[160:163], v[200:203], v[66:69]
	s_barrier
	s_setprio 0
	s_mov_b32 m0, s3
	v_lshl_add_u64 v[184:185], s[8:9], 0, v[154:155]
	ds_read_b128 v[168:171], v167 offset:16384
	ds_read_b128 v[172:175], v167 offset:17408
	ds_read_b128 v[176:179], v167 offset:18432
	ds_read_b128 v[180:183], v167 offset:19456
	ds_read_b128 v[188:191], v167 offset:20480
	ds_read_b128 v[192:195], v167 offset:21504
	ds_read_b128 v[196:199], v167 offset:22528
	ds_read_b128 v[200:203], v167 offset:23552
	global_load_lds_dwordx4 v[184:185], off
	v_lshl_add_u64 v[204:205], v[184:185], 0, s[70:71]
	s_mov_b32 m0, s22
	s_nop 0
	global_load_lds_dwordx4 v[204:205], off
	v_lshl_add_u64 v[204:205], v[184:185], 0, s[96:97]
	s_mov_b32 m0, s24
	s_nop 0
	global_load_lds_dwordx4 v[204:205], off
	v_lshl_add_u64 v[204:205], v[184:185], 0, s[60:61]
	s_mov_b32 m0, s25
	s_nop 0
	global_load_lds_dwordx4 v[204:205], off
	v_lshl_add_u64 v[204:205], vcc, 0, v[154:155]
	s_mov_b32 m0, s26
	v_lshl_add_u64 v[206:207], v[204:205], 0, s[70:71]
	global_load_lds_dwordx4 v[204:205], off
	s_mov_b32 m0, s27
	s_nop 0
	global_load_lds_dwordx4 v[206:207], off
	.p2align 3
	s_waitcnt vmcnt(8)
	s_waitcnt lgkmcnt(0)
	s_setprio 1
	s_barrier
	v_mfma_f32_16x16x32_bf16 v[62:65], v[130:133], v[168:171], v[62:65]
	v_mfma_f32_16x16x32_bf16 v[58:61], v[138:141], v[168:171], v[58:61]
	v_mfma_f32_16x16x32_bf16 v[46:49], v[130:133], v[176:179], v[46:49]
	v_mfma_f32_16x16x32_bf16 v[42:45], v[138:141], v[176:179], v[42:45]
	v_mfma_f32_16x16x32_bf16 v[30:33], v[130:133], v[188:191], v[30:33]
	v_mfma_f32_16x16x32_bf16 v[26:29], v[138:141], v[188:191], v[26:29]
	v_mfma_f32_16x16x32_bf16 v[14:17], v[130:133], v[196:199], v[14:17]
	v_mfma_f32_16x16x32_bf16 v[10:13], v[138:141], v[196:199], v[10:13]
	v_mfma_f32_16x16x32_bf16 v[62:65], v[134:137], v[172:175], v[62:65]
	v_mfma_f32_16x16x32_bf16 v[58:61], v[142:145], v[172:175], v[58:61]
	v_mfma_f32_16x16x32_bf16 v[46:49], v[134:137], v[180:183], v[46:49]
	v_mfma_f32_16x16x32_bf16 v[42:45], v[142:145], v[180:183], v[42:45]
	v_mfma_f32_16x16x32_bf16 v[30:33], v[134:137], v[192:195], v[30:33]
	v_mfma_f32_16x16x32_bf16 v[26:29], v[142:145], v[192:195], v[26:29]
	v_mfma_f32_16x16x32_bf16 v[14:17], v[134:137], v[200:203], v[14:17]
	v_mfma_f32_16x16x32_bf16 v[10:13], v[142:145], v[200:203], v[10:13]
	v_mfma_f32_16x16x32_bf16 v[54:57], v[146:149], v[168:171], v[54:57]
	v_mfma_f32_16x16x32_bf16 v[50:53], v[156:159], v[168:171], v[50:53]
	v_mfma_f32_16x16x32_bf16 v[38:41], v[146:149], v[176:179], v[38:41]
	v_mfma_f32_16x16x32_bf16 v[34:37], v[156:159], v[176:179], v[34:37]
	v_mfma_f32_16x16x32_bf16 v[22:25], v[146:149], v[188:191], v[22:25]
	v_mfma_f32_16x16x32_bf16 v[18:21], v[156:159], v[188:191], v[18:21]
	v_mfma_f32_16x16x32_bf16 v[6:9], v[146:149], v[196:199], v[6:9]
	v_mfma_f32_16x16x32_bf16 v[2:5], v[156:159], v[196:199], v[2:5]
	v_mfma_f32_16x16x32_bf16 v[54:57], v[150:153], v[172:175], v[54:57]
	v_mfma_f32_16x16x32_bf16 v[50:53], v[160:163], v[172:175], v[50:53]
	v_mfma_f32_16x16x32_bf16 v[38:41], v[150:153], v[180:183], v[38:41]
	v_mfma_f32_16x16x32_bf16 v[34:37], v[160:163], v[180:183], v[34:37]
	v_mfma_f32_16x16x32_bf16 v[22:25], v[150:153], v[192:195], v[22:25]
	v_mfma_f32_16x16x32_bf16 v[18:21], v[160:163], v[192:195], v[18:21]
	v_mfma_f32_16x16x32_bf16 v[6:9], v[150:153], v[200:203], v[6:9]
	v_mfma_f32_16x16x32_bf16 v[2:5], v[160:163], v[200:203], v[2:5]
	s_barrier
; #define PG8_STAGE(bufoff, gbase, unused) do { _Pragma("unroll") for (int _i = 0; _i < 2; ++_i) \
;         __builtin_amdgcn_global_load_lds((const unsigned*)((const char*)(gbase) + voff + _i * 8192), (LAS unsigned*)(lds + (bufoff) + ldsw + _i * 8192), 16, 0, 0); } while (0)
; #define PG8_LDA(dst, b, h) do { _Pragma("unroll") for (int m = 0; m < 4; ++m) _Pragma("unroll") for (int k = 0; k < 2; ++k) dst[m][k] = *(const LAS bf16x8*)(lds + PG8_SA(b, h) + aoff + m * 2048 + (FP8 ? k * 16 : k * 1024)); } while (0)
; #define PG8_LDB(dst, b, h) do { _Pragma("unroll") for (int n = 0; n < 2; ++n) _Pragma("unroll") for (int k = 0; k < 2; ++k) dst[n][k] = *(const LAS bf16x8*)(lds + PG8_SB(b, h) + boff + n * 2048 + (FP8 ? k * 16 : k * 1024)); } while (0)
; #define PG8_WAIT_V(n) asm volatile("s_waitcnt vmcnt(" #n ")" ::: "memory")
; #define PG8_WAIT_L(n) asm volatile("s_waitcnt lgkmcnt(" #n ")" ::: "memory")
; #define PG8_BAR __builtin_amdgcn_s_barrier()
; #define PG8_SCHED __builtin_amdgcn_sched_barrier(0)
; template <class Epi, class Sched, bool ALIGN_EPI, bool SP2, int MODE  >
; __device__ __forceinline__ void gemm_phase(LAS unsigned char* lds, const Gemm g, const Sched S, const Epi E, unsigned long long& probe_acc, int epi_id, int wv) {
;     ...
;         for (int t = 0; t < nt; t += 2) {
;     ...
;             PG8_WAIT_V(8); PG8_WAIT_L(0); PG8_BAR; PG8_MMA(1, 0, At, B0); PG8_MMA(1, 1, At, B1); PG8_BAR; PG8_SCHED;
;             PG8_LDB(B0, 1, 0); PG8_LDB(B1, 1, 1); PG8_SCHED; PG8_LDA(At, 1, 0); PG8_STAGE(PG8_SA(0, 1), a2 + hA, voffA);
;             PG8_WAIT_V(8); PG8_WAIT_L(0); PG8_BAR; PG8_MMA(0, 0, At, B0); PG8_MMA(0, 1, At, B1); PG8_BAR; PG8_SCHED;
;             PG8_LDA(At, 1, 1); PG8_STAGE(PG8_SB(1, 0), b3, voffB); PG8_STAGE(PG8_SB(1, 1), b3 + hB, voffB); PG8_STAGE(PG8_SA(1, 0), a3, voffA);
;             PG8_WAIT_V(8); PG8_WAIT_L(0); PG8_BAR; PG8_MMA(1, 0, At, B0); PG8_MMA(1, 1, At, B1); PG8_BAR; PG8_SCHED;
	s_setprio 0
	v_add_u32_e32 v0, s31, v166
	ds_read_b128 v[130:133], v0
	ds_read_b128 v[134:137], v0 offset:1024
	ds_read_b128 v[138:141], v0 offset:2048
	ds_read_b128 v[142:145], v0 offset:3072
	v_add_u32_e32 v0, s39, v166
	ds_read_b128 v[146:149], v0
	ds_read_b128 v[150:153], v0 offset:1024
	ds_read_b128 v[156:159], v0 offset:2048
	ds_read_b128 v[160:163], v0 offset:3072
	s_mov_b32 m0, s28
	v_lshl_add_u64 v[206:207], v[204:205], 0, s[96:97]
	ds_read_b128 v[168:171], v167 offset:32768
	ds_read_b128 v[172:175], v167 offset:33792
	ds_read_b128 v[176:179], v167 offset:34816
	ds_read_b128 v[180:183], v167 offset:35840
	ds_read_b128 v[188:191], v167 offset:36864
	ds_read_b128 v[192:195], v167 offset:37888
	ds_read_b128 v[196:199], v167 offset:38912
	ds_read_b128 v[200:203], v167 offset:39936
	global_load_lds_dwordx4 v[206:207], off
	v_lshl_add_u64 v[206:207], v[204:205], 0, s[60:61]
	s_mov_b32 m0, s29
	s_nop 0
	global_load_lds_dwordx4 v[206:207], off
	.p2align 3
	s_waitcnt vmcnt(8)
	s_waitcnt lgkmcnt(0)
	s_setprio 1
	s_barrier
	v_mfma_f32_16x16x32_bf16 v[126:129], v[130:133], v[168:171], v[126:129]
	v_mfma_f32_16x16x32_bf16 v[122:125], v[138:141], v[168:171], v[122:125]
	v_mfma_f32_16x16x32_bf16 v[110:113], v[130:133], v[176:179], v[110:113]
	v_mfma_f32_16x16x32_bf16 v[106:109], v[138:141], v[176:179], v[106:109]
	v_mfma_f32_16x16x32_bf16 v[94:97], v[130:133], v[188:191], v[94:97]
	v_mfma_f32_16x16x32_bf16 v[90:93], v[138:141], v[188:191], v[90:93]
	v_mfma_f32_16x16x32_bf16 v[78:81], v[130:133], v[196:199], v[78:81]
	v_mfma_f32_16x16x32_bf16 v[74:77], v[138:141], v[196:199], v[74:77]
	v_mfma_f32_16x16x32_bf16 v[126:129], v[134:137], v[172:175], v[126:129]
	v_mfma_f32_16x16x32_bf16 v[122:125], v[142:145], v[172:175], v[122:125]
	v_mfma_f32_16x16x32_bf16 v[110:113], v[134:137], v[180:183], v[110:113]
	v_mfma_f32_16x16x32_bf16 v[106:109], v[142:145], v[180:183], v[106:109]
	v_mfma_f32_16x16x32_bf16 v[94:97], v[134:137], v[192:195], v[94:97]
	v_mfma_f32_16x16x32_bf16 v[90:93], v[142:145], v[192:195], v[90:93]
	v_mfma_f32_16x16x32_bf16 v[78:81], v[134:137], v[200:203], v[78:81]
	v_mfma_f32_16x16x32_bf16 v[74:77], v[142:145], v[200:203], v[74:77]
	v_mfma_f32_16x16x32_bf16 v[118:121], v[146:149], v[168:171], v[118:121]
	v_mfma_f32_16x16x32_bf16 v[114:117], v[156:159], v[168:171], v[114:117]
	v_mfma_f32_16x16x32_bf16 v[102:105], v[146:149], v[176:179], v[102:105]
	v_mfma_f32_16x16x32_bf16 v[98:101], v[156:159], v[176:179], v[98:101]
	v_mfma_f32_16x16x32_bf16 v[86:89], v[146:149], v[188:191], v[86:89]
	v_mfma_f32_16x16x32_bf16 v[82:85], v[156:159], v[188:191], v[82:85]
	v_mfma_f32_16x16x32_bf16 v[70:73], v[146:149], v[196:199], v[70:73]
	v_mfma_f32_16x16x32_bf16 v[66:69], v[156:159], v[196:199], v[66:69]
	v_mfma_f32_16x16x32_bf16 v[118:121], v[150:153], v[172:175], v[118:121]
	v_mfma_f32_16x16x32_bf16 v[114:117], v[160:163], v[172:175], v[114:117]
	v_mfma_f32_16x16x32_bf16 v[102:105], v[150:153], v[180:183], v[102:105]
	v_mfma_f32_16x16x32_bf16 v[98:101], v[160:163], v[180:183], v[98:101]
	v_mfma_f32_16x16x32_bf16 v[86:89], v[150:153], v[192:195], v[86:89]
	v_mfma_f32_16x16x32_bf16 v[82:85], v[160:163], v[192:195], v[82:85]
	v_mfma_f32_16x16x32_bf16 v[70:73], v[150:153], v[200:203], v[70:73]
	v_mfma_f32_16x16x32_bf16 v[66:69], v[160:163], v[200:203], v[66:69]
	s_barrier
	s_setprio 0
	s_mov_b32 m0, s34
	v_lshl_add_u64 v[206:207], v[184:185], 0, s[76:77]
	ds_read_b128 v[168:171], v167 offset:49152
	ds_read_b128 v[172:175], v167 offset:50176
	ds_read_b128 v[176:179], v167 offset:51200
	ds_read_b128 v[180:183], v167 offset:52224
	ds_read_b128 v[188:191], v167 offset:53248
	ds_read_b128 v[192:195], v167 offset:54272
	ds_read_b128 v[196:199], v167 offset:55296
	ds_read_b128 v[200:203], v167 offset:56320
	global_load_lds_dwordx4 v[206:207], off
	v_lshl_add_u64 v[206:207], v[184:185], 0, s[78:79]
	s_mov_b32 m0, s35
	s_nop 0
	global_load_lds_dwordx4 v[206:207], off
	v_lshl_add_u64 v[206:207], v[184:185], 0, s[52:53]
	s_mov_b32 m0, s40
	v_lshl_add_u64 v[184:185], v[184:185], 0, s[54:55]
	global_load_lds_dwordx4 v[206:207], off
	s_mov_b32 m0, s41
	s_nop 0
	global_load_lds_dwordx4 v[184:185], off
	v_lshl_add_u64 v[184:185], v[204:205], 0, s[76:77]
	s_mov_b32 m0, s36
	s_nop 0
	global_load_lds_dwordx4 v[184:185], off
	v_lshl_add_u64 v[184:185], v[204:205], 0, s[78:79]
	s_mov_b32 m0, s37
	s_nop 0
	global_load_lds_dwordx4 v[184:185], off
	.p2align 3
	s_waitcnt vmcnt(8)
	s_waitcnt lgkmcnt(0)
	s_setprio 1
	s_barrier
	v_mfma_f32_16x16x32_bf16 v[62:65], v[130:133], v[168:171], v[62:65]
	v_mfma_f32_16x16x32_bf16 v[58:61], v[138:141], v[168:171], v[58:61]
	v_mfma_f32_16x16x32_bf16 v[46:49], v[130:133], v[176:179], v[46:49]
	v_mfma_f32_16x16x32_bf16 v[42:45], v[138:141], v[176:179], v[42:45]
	v_mfma_f32_16x16x32_bf16 v[30:33], v[130:133], v[188:191], v[30:33]
	v_mfma_f32_16x16x32_bf16 v[26:29], v[138:141], v[188:191], v[26:29]
	v_mfma_f32_16x16x32_bf16 v[14:17], v[130:133], v[196:199], v[14:17]
	v_mfma_f32_16x16x32_bf16 v[10:13], v[138:141], v[196:199], v[10:13]
	v_mfma_f32_16x16x32_bf16 v[62:65], v[134:137], v[172:175], v[62:65]
	v_mfma_f32_16x16x32_bf16 v[58:61], v[142:145], v[172:175], v[58:61]
	v_mfma_f32_16x16x32_bf16 v[46:49], v[134:137], v[180:183], v[46:49]
	v_mfma_f32_16x16x32_bf16 v[42:45], v[142:145], v[180:183], v[42:45]
	v_mfma_f32_16x16x32_bf16 v[30:33], v[134:137], v[192:195], v[30:33]
	v_mfma_f32_16x16x32_bf16 v[26:29], v[142:145], v[192:195], v[26:29]
	v_mfma_f32_16x16x32_bf16 v[14:17], v[134:137], v[200:203], v[14:17]
	v_mfma_f32_16x16x32_bf16 v[10:13], v[142:145], v[200:203], v[10:13]
	v_mfma_f32_16x16x32_bf16 v[54:57], v[146:149], v[168:171], v[54:57]
	v_mfma_f32_16x16x32_bf16 v[50:53], v[156:159], v[168:171], v[50:53]
	v_mfma_f32_16x16x32_bf16 v[38:41], v[146:149], v[176:179], v[38:41]
	v_mfma_f32_16x16x32_bf16 v[34:37], v[156:159], v[176:179], v[34:37]
	v_mfma_f32_16x16x32_bf16 v[22:25], v[146:149], v[188:191], v[22:25]
	v_mfma_f32_16x16x32_bf16 v[18:21], v[156:159], v[188:191], v[18:21]
	v_mfma_f32_16x16x32_bf16 v[6:9], v[146:149], v[196:199], v[6:9]
	v_mfma_f32_16x16x32_bf16 v[2:5], v[156:159], v[196:199], v[2:5]
	v_mfma_f32_16x16x32_bf16 v[54:57], v[150:153], v[172:175], v[54:57]
	v_mfma_f32_16x16x32_bf16 v[50:53], v[160:163], v[172:175], v[50:53]
	v_mfma_f32_16x16x32_bf16 v[38:41], v[150:153], v[180:183], v[38:41]
	v_mfma_f32_16x16x32_bf16 v[34:37], v[160:163], v[180:183], v[34:37]
	v_mfma_f32_16x16x32_bf16 v[22:25], v[150:153], v[192:195], v[22:25]
	v_mfma_f32_16x16x32_bf16 v[18:21], v[160:163], v[192:195], v[18:21]
	v_mfma_f32_16x16x32_bf16 v[6:9], v[150:153], v[200:203], v[6:9]
	v_mfma_f32_16x16x32_bf16 v[2:5], v[160:163], v[200:203], v[2:5]
	s_barrier
	s_setprio 0
	s_add_i32 s95, s95, 2
	s_add_u32 s93, s93, 0x8000
	s_addc_u32 s94, s94, 0
	s_cmp_gt_u32 s95, 29
	s_mov_b64 s[18:19], s[20:21]
	s_cbranch_scc0 .LBB0_365
	s_and_b64 vcc, exec, s[14:15]
	s_cbranch_vccz .LBB0_368
	s_barrier

;     __device__ __forceinline__ bool next(int i, Unit& u) const { const int off = i * H + (r >> 1); if (off >= 8 * nN) return false; u.pm = 16 * g + 8 * (r & 1) + (off & 7); u.pn = off >> 3; return true; }
; #define PG8_STAGE(bufoff, gbase, unused) do { _Pragma("unroll") for (int _i = 0; _i < 2; ++_i) \
;         __builtin_amdgcn_global_load_lds((const unsigned*)((const char*)(gbase) + voff + _i * 8192), (LAS unsigned*)(lds + (bufoff) + ldsw + _i * 8192), 16, 0, 0); } while (0)
; #define PG8_LDA(dst, b, h) do { _Pragma("unroll") for (int m = 0; m < 4; ++m) _Pragma("unroll") for (int k = 0; k < 2; ++k) dst[m][k] = *(const LAS bf16x8*)(lds + PG8_SA(b, h) + aoff + m * 2048 + (FP8 ? k * 16 : k * 1024)); } while (0)
; #define PG8_LDB(dst, b, h) do { _Pragma("unroll") for (int n = 0; n < 2; ++n) _Pragma("unroll") for (int k = 0; k < 2; ++k) dst[n][k] = *(const LAS bf16x8*)(lds + PG8_SB(b, h) + boff + n * 2048 + (FP8 ? k * 16 : k * 1024)); } while (0)
; #define PG8_BAR __builtin_amdgcn_s_barrier()
; template <class Epi, class Sched, bool ALIGN_EPI, bool SP2, int MODE  >
; __device__ __forceinline__ void gemm_phase(LAS unsigned char* lds, const Gemm g, const Sched S, const Epi E, unsigned long long& probe_acc, int epi_id, int wv) {
;     ...
;         const bool has_next = S.next(ui + 1, nxt);
;         const char* nA = has_next ? (const char*)g.A + (size_t)nxt.pm * tA + (g.gt ? (size_t)(nxt.pn / g.gt) * gK2 : 0) : cA; const char* nB = has_next ? (const char*)g.Bt + (size_t)nxt.pn * tB : cB;
;         for (int t = 0; t < nt; t += 2) {
;             const bool last = (t == nt - 2);
;             const char* a1 = cA + (size_t)(t + 1) * kstep;
;             const char* a2 = last ? nA : cA + (size_t)(t + 2) * kstep; const char* b2 = last ? nB : cB + (size_t)(t + 2) * kstep;
;             const char* a3 = a2 + kstep; const char* b3 = b2 + kstep;
;             if constexpr (SP2) {
;             PG8_LDB(B0, 0, 0); PG8_LDB(B1, 0, 1); PG8_SCHED; PG8_LDA(At, 0, 0); PG8_STAGE(PG8_SA(1, 1), a1 + hA, voffA);
;             PG8_WAIT_V(8); PG8_WAIT_L(0); PG8_BAR; PG8_MMA(0, 0, At, B0); PG8_MMA(0, 1, At, B1); PG8_BAR; PG8_SCHED;
;             PG8_LDA(At, 0, 1); PG8_STAGE(PG8_SB(0, 0), b2, voffB); PG8_STAGE(PG8_SB(0, 1), b2 + hB, voffB); PG8_STAGE(PG8_SA(0, 0), a2, voffA);
;             PG8_WAIT_V(8); PG8_WAIT_L(0); PG8_BAR; PG8_MMA(1, 0, At, B0); PG8_MMA(1, 1, At, B1); PG8_BAR; PG8_SCHED;
.LBB0_673:
	s_add_u32 s10, s4, 0x8000
	s_addc_u32 s11, s5, 0
	s_add_u32 s4, s6, 0x8000
	s_addc_u32 s5, s7, 0
	s_mov_b32 s6, 0
	s_waitcnt lgkmcnt(0)
	s_waitcnt vmcnt(0)
	v_add_u32_e32 v142, s15, v193
	v_add_u32_e32 v156, s39, v193
	ds_read_b128 v[130:133], v142
	ds_read_b128 v[134:137], v142 offset:1024
	ds_read_b128 v[138:141], v142 offset:2048
	ds_read_b128 v[142:145], v142 offset:3072
	ds_read_b128 v[146:149], v156
	ds_read_b128 v[150:153], v156 offset:1024
	ds_read_b128 v[158:161], v156 offset:2048
	ds_read_b128 v[162:165], v156 offset:3072
	s_add_i32 s40, s6, 2
	s_cmp_eq_u32 s93, s6
	s_cselect_b32 s6, s34, s10
	s_cselect_b32 s9, s87, s5
	s_cselect_b32 s8, s86, s4
	s_cselect_b32 s7, s35, s11
	s_movk_i32 vcc_lo, 0xc000
	v_lshl_add_u64 v[190:191], s[4:5], 0, v[154:155]
	s_mov_b32 vcc_hi, -1
	v_lshl_add_u64 v[196:197], v[190:191], 0, vcc
	s_movk_i32 vcc_lo, 0xe000
	s_add_i32 m0, s88, 0xc000
	s_mov_b32 vcc_hi, -1
	ds_read_b128 v[166:169], v194
	ds_read_b128 v[170:173], v194 offset:1024
	ds_read_b128 v[174:177], v194 offset:2048
	ds_read_b128 v[178:181], v194 offset:3072
	ds_read_b128 v[182:185], v194 offset:4096
	ds_read_b128 v[186:189], v194 offset:5120
	ds_read_b128 v[200:203], v194 offset:6144
	ds_read_b128 v[204:207], v194 offset:7168
	global_load_lds_dwordx4 v[196:197], off
	v_lshl_add_u64 v[190:191], v[190:191], 0, vcc
	s_add_i32 m0, s88, 0xe000
	s_nop 0
	global_load_lds_dwordx4 v[190:191], off
	.p2align 3
	s_waitcnt vmcnt(8)
	s_waitcnt lgkmcnt(0)
	s_setprio 1
	s_barrier
	v_mfma_f32_16x16x32_bf16 v[126:129], v[130:133], v[166:169], 0
	v_mfma_f32_16x16x32_bf16 v[122:125], v[138:141], v[166:169], 0
	v_mfma_f32_16x16x32_bf16 v[118:121], v[130:133], v[174:177], 0
	v_mfma_f32_16x16x32_bf16 v[114:117], v[138:141], v[174:177], 0
	v_mfma_f32_16x16x32_bf16 v[110:113], v[130:133], v[182:185], 0
	v_mfma_f32_16x16x32_bf16 v[106:109], v[138:141], v[182:185], 0
	v_mfma_f32_16x16x32_bf16 v[102:105], v[130:133], v[200:203], 0
	v_mfma_f32_16x16x32_bf16 v[98:101], v[138:141], v[200:203], 0
	v_mfma_f32_16x16x32_bf16 v[126:129], v[134:137], v[170:173], v[126:129]
	v_mfma_f32_16x16x32_bf16 v[122:125], v[142:145], v[170:173], v[122:125]
	v_mfma_f32_16x16x32_bf16 v[118:121], v[134:137], v[178:181], v[118:121]
	v_mfma_f32_16x16x32_bf16 v[114:117], v[142:145], v[178:181], v[114:117]
	v_mfma_f32_16x16x32_bf16 v[110:113], v[134:137], v[186:189], v[110:113]
	v_mfma_f32_16x16x32_bf16 v[106:109], v[142:145], v[186:189], v[106:109]
	v_mfma_f32_16x16x32_bf16 v[102:105], v[134:137], v[204:207], v[102:105]
	v_mfma_f32_16x16x32_bf16 v[98:101], v[142:145], v[204:207], v[98:101]
	v_mfma_f32_16x16x32_bf16 v[62:65], v[146:149], v[166:169], 0
	v_mfma_f32_16x16x32_bf16 v[58:61], v[158:161], v[166:169], 0
	v_mfma_f32_16x16x32_bf16 v[54:57], v[146:149], v[174:177], 0
	v_mfma_f32_16x16x32_bf16 v[50:53], v[158:161], v[174:177], 0
	v_mfma_f32_16x16x32_bf16 v[46:49], v[146:149], v[182:185], 0
	v_mfma_f32_16x16x32_bf16 v[42:45], v[158:161], v[182:185], 0
	v_mfma_f32_16x16x32_bf16 v[38:41], v[146:149], v[200:203], 0
	v_mfma_f32_16x16x32_bf16 v[34:37], v[158:161], v[200:203], 0
	v_mfma_f32_16x16x32_bf16 v[62:65], v[150:153], v[170:173], v[62:65]
	v_mfma_f32_16x16x32_bf16 v[58:61], v[162:165], v[170:173], v[58:61]
	v_mfma_f32_16x16x32_bf16 v[54:57], v[150:153], v[178:181], v[54:57]
	v_mfma_f32_16x16x32_bf16 v[50:53], v[162:165], v[178:181], v[50:53]
	v_mfma_f32_16x16x32_bf16 v[46:49], v[150:153], v[186:189], v[46:49]
	v_mfma_f32_16x16x32_bf16 v[42:45], v[162:165], v[186:189], v[42:45]
	v_mfma_f32_16x16x32_bf16 v[38:41], v[150:153], v[204:207], v[38:41]
	v_mfma_f32_16x16x32_bf16 v[34:37], v[162:165], v[204:207], v[34:37]
	s_barrier
	s_setprio 0
	s_mov_b32 m0, s26
	v_lshl_add_u64 v[190:191], s[6:7], 0, v[0:1]
	s_add_u32 vcc_lo, s6, s13
	ds_read_b128 v[166:169], v194 offset:16384
	ds_read_b128 v[170:173], v194 offset:17408
	ds_read_b128 v[174:177], v194 offset:18432
	ds_read_b128 v[178:181], v194 offset:19456
	ds_read_b128 v[182:185], v194 offset:20480
	ds_read_b128 v[186:189], v194 offset:21504
	ds_read_b128 v[200:203], v194 offset:22528
	ds_read_b128 v[204:207], v194 offset:23552
	global_load_lds_dwordx4 v[190:191], off
	v_lshl_add_u64 v[190:191], v[190:191], 0, s[70:71]
	s_mov_b32 m0, s27
	s_addc_u32 vcc_hi, s7, 0
	global_load_lds_dwordx4 v[190:191], off
	v_lshl_add_u64 v[190:191], vcc, 0, v[0:1]
	s_mov_b32 m0, s84
	s_nop 0
	global_load_lds_dwordx4 v[190:191], off
	v_lshl_add_u64 v[190:191], v[190:191], 0, s[70:71]
	s_mov_b32 m0, s85
	s_nop 0
	global_load_lds_dwordx4 v[190:191], off
	v_lshl_add_u64 v[190:191], s[8:9], 0, v[0:1]
	s_mov_b32 m0, s88
	v_lshl_add_u64 v[196:197], v[190:191], 0, s[70:71]
	global_load_lds_dwordx4 v[190:191], off
	s_mov_b32 m0, s89
	s_nop 0
	global_load_lds_dwordx4 v[196:197], off
	.p2align 3
	s_waitcnt vmcnt(8)
	s_waitcnt lgkmcnt(0)
	s_setprio 1
	s_barrier
; #define PG8_STAGE(bufoff, gbase, unused) do { _Pragma("unroll") for (int _i = 0; _i < 2; ++_i) \
;         __builtin_amdgcn_global_load_lds((const unsigned*)((const char*)(gbase) + voff + _i * 8192), (LAS unsigned*)(lds + (bufoff) + ldsw + _i * 8192), 16, 0, 0); } while (0)
; #define PG8_LDA(dst, b, h) do { _Pragma("unroll") for (int m = 0; m < 4; ++m) _Pragma("unroll") for (int k = 0; k < 2; ++k) dst[m][k] = *(const LAS bf16x8*)(lds + PG8_SA(b, h) + aoff + m * 2048 + (FP8 ? k * 16 : k * 1024)); } while (0)
; #define PG8_LDB(dst, b, h) do { _Pragma("unroll") for (int n = 0; n < 2; ++n) _Pragma("unroll") for (int k = 0; k < 2; ++k) dst[n][k] = *(const LAS bf16x8*)(lds + PG8_SB(b, h) + boff + n * 2048 + (FP8 ? k * 16 : k * 1024)); } while (0)
; #define PG8_WAIT_V(n) asm volatile("s_waitcnt vmcnt(" #n ")" ::: "memory")
; #define PG8_WAIT_L(n) asm volatile("s_waitcnt lgkmcnt(" #n ")" ::: "memory")
; #define PG8_BAR __builtin_amdgcn_s_barrier()
; #define PG8_SCHED __builtin_amdgcn_sched_barrier(0)
; template <class Epi, class Sched, bool ALIGN_EPI, bool SP2, int MODE  >
; __device__ __forceinline__ void gemm_phase(LAS unsigned char* lds, const Gemm g, const Sched S, const Epi E, unsigned long long& probe_acc, int epi_id, int wv) {
;     ...
;             PG8_WAIT_V(8); PG8_WAIT_L(0); PG8_BAR; PG8_MMA(0, 0, At, B0); PG8_MMA(0, 1, At, B1); PG8_BAR; PG8_SCHED;
;             PG8_LDA(At, 0, 1); PG8_STAGE(PG8_SB(0, 0), b2, voffB); PG8_STAGE(PG8_SB(0, 1), b2 + hB, voffB); PG8_STAGE(PG8_SA(0, 0), a2, voffA);
;             PG8_WAIT_V(8); PG8_WAIT_L(0); PG8_BAR; PG8_MMA(1, 0, At, B0); PG8_MMA(1, 1, At, B1); PG8_BAR; PG8_SCHED;
;             PG8_LDB(B0, 1, 0); PG8_LDB(B1, 1, 1); PG8_SCHED; PG8_LDA(At, 1, 0); PG8_STAGE(PG8_SA(0, 1), a2 + hA, voffA);
;             PG8_WAIT_V(8); PG8_WAIT_L(0); PG8_BAR; PG8_MMA(0, 0, At, B0); PG8_MMA(0, 1, At, B1); PG8_BAR; PG8_SCHED;
;             PG8_LDA(At, 1, 1); PG8_STAGE(PG8_SB(1, 0), b3, voffB); PG8_STAGE(PG8_SB(1, 1), b3 + hB, voffB); PG8_STAGE(PG8_SA(1, 0), a3, voffA);
	v_mfma_f32_16x16x32_bf16 v[94:97], v[130:133], v[166:169], 0
	v_mfma_f32_16x16x32_bf16 v[90:93], v[138:141], v[166:169], 0
	v_mfma_f32_16x16x32_bf16 v[86:89], v[130:133], v[174:177], 0
	v_mfma_f32_16x16x32_bf16 v[82:85], v[138:141], v[174:177], 0
	v_mfma_f32_16x16x32_bf16 v[78:81], v[130:133], v[182:185], 0
	v_mfma_f32_16x16x32_bf16 v[74:77], v[138:141], v[182:185], 0
	v_mfma_f32_16x16x32_bf16 v[70:73], v[130:133], v[200:203], 0
	v_mfma_f32_16x16x32_bf16 v[66:69], v[138:141], v[200:203], 0
	v_mfma_f32_16x16x32_bf16 v[94:97], v[134:137], v[170:173], v[94:97]
	v_mfma_f32_16x16x32_bf16 v[90:93], v[142:145], v[170:173], v[90:93]
	v_mfma_f32_16x16x32_bf16 v[86:89], v[134:137], v[178:181], v[86:89]
	v_mfma_f32_16x16x32_bf16 v[82:85], v[142:145], v[178:181], v[82:85]
	v_mfma_f32_16x16x32_bf16 v[78:81], v[134:137], v[186:189], v[78:81]
	v_mfma_f32_16x16x32_bf16 v[74:77], v[142:145], v[186:189], v[74:77]
	v_mfma_f32_16x16x32_bf16 v[70:73], v[134:137], v[204:207], v[70:73]
	v_mfma_f32_16x16x32_bf16 v[66:69], v[142:145], v[204:207], v[66:69]
	v_mfma_f32_16x16x32_bf16 v[30:33], v[146:149], v[166:169], 0
	v_mfma_f32_16x16x32_bf16 v[26:29], v[158:161], v[166:169], 0
	v_mfma_f32_16x16x32_bf16 v[22:25], v[146:149], v[174:177], 0
	v_mfma_f32_16x16x32_bf16 v[18:21], v[158:161], v[174:177], 0
	v_mfma_f32_16x16x32_bf16 v[14:17], v[146:149], v[182:185], 0
	v_mfma_f32_16x16x32_bf16 v[10:13], v[158:161], v[182:185], 0
	v_mfma_f32_16x16x32_bf16 v[6:9], v[146:149], v[200:203], 0
	v_mfma_f32_16x16x32_bf16 v[2:5], v[158:161], v[200:203], 0
	v_mfma_f32_16x16x32_bf16 v[30:33], v[150:153], v[170:173], v[30:33]
	v_mfma_f32_16x16x32_bf16 v[26:29], v[162:165], v[170:173], v[26:29]
	v_mfma_f32_16x16x32_bf16 v[22:25], v[150:153], v[178:181], v[22:25]
	v_mfma_f32_16x16x32_bf16 v[18:21], v[162:165], v[178:181], v[18:21]
	v_mfma_f32_16x16x32_bf16 v[14:17], v[150:153], v[186:189], v[14:17]
	v_mfma_f32_16x16x32_bf16 v[10:13], v[162:165], v[186:189], v[10:13]
	v_mfma_f32_16x16x32_bf16 v[6:9], v[150:153], v[204:207], v[6:9]
	v_mfma_f32_16x16x32_bf16 v[2:5], v[162:165], v[204:207], v[2:5]
	s_barrier
	s_setprio 0
	v_add_u32_e32 v142, s28, v193
	v_add_u32_e32 v156, s94, v193
	ds_read_b128 v[130:133], v142
	ds_read_b128 v[134:137], v142 offset:1024
	ds_read_b128 v[138:141], v142 offset:2048
	ds_read_b128 v[142:145], v142 offset:3072
	ds_read_b128 v[146:149], v156
	ds_read_b128 v[150:153], v156 offset:1024
	ds_read_b128 v[158:161], v156 offset:2048
	ds_read_b128 v[162:165], v156 offset:3072
	s_add_u32 s8, s8, s36
	s_addc_u32 s9, s9, 0
	s_mov_b32 m0, s29
	v_lshl_add_u64 v[196:197], s[8:9], 0, v[0:1]
	ds_read_b128 v[166:169], v194 offset:32768
	ds_read_b128 v[170:173], v194 offset:33792
	ds_read_b128 v[174:177], v194 offset:34816
	ds_read_b128 v[178:181], v194 offset:35840
	ds_read_b128 v[182:185], v194 offset:36864
	ds_read_b128 v[186:189], v194 offset:37888
	ds_read_b128 v[200:203], v194 offset:38912
	ds_read_b128 v[204:207], v194 offset:39936
	global_load_lds_dwordx4 v[196:197], off
	v_lshl_add_u64 v[196:197], v[196:197], 0, s[70:71]
	s_mov_b32 m0, s92
	s_nop 0
	global_load_lds_dwordx4 v[196:197], off
	.p2align 3
	s_waitcnt vmcnt(8)
	s_waitcnt lgkmcnt(0)
	s_setprio 1
	s_barrier
	v_mfma_f32_16x16x32_bf16 v[126:129], v[130:133], v[166:169], v[126:129]
	v_mfma_f32_16x16x32_bf16 v[122:125], v[138:141], v[166:169], v[122:125]
	v_mfma_f32_16x16x32_bf16 v[118:121], v[130:133], v[174:177], v[118:121]
	v_mfma_f32_16x16x32_bf16 v[114:117], v[138:141], v[174:177], v[114:117]
	v_mfma_f32_16x16x32_bf16 v[110:113], v[130:133], v[182:185], v[110:113]
	v_mfma_f32_16x16x32_bf16 v[106:109], v[138:141], v[182:185], v[106:109]
	v_mfma_f32_16x16x32_bf16 v[102:105], v[130:133], v[200:203], v[102:105]
	v_mfma_f32_16x16x32_bf16 v[98:101], v[138:141], v[200:203], v[98:101]
	v_mfma_f32_16x16x32_bf16 v[126:129], v[134:137], v[170:173], v[126:129]
	v_mfma_f32_16x16x32_bf16 v[122:125], v[142:145], v[170:173], v[122:125]
	v_mfma_f32_16x16x32_bf16 v[118:121], v[134:137], v[178:181], v[118:121]
	v_mfma_f32_16x16x32_bf16 v[114:117], v[142:145], v[178:181], v[114:117]
	v_mfma_f32_16x16x32_bf16 v[110:113], v[134:137], v[186:189], v[110:113]
	v_mfma_f32_16x16x32_bf16 v[106:109], v[142:145], v[186:189], v[106:109]
	v_mfma_f32_16x16x32_bf16 v[102:105], v[134:137], v[204:207], v[102:105]
	v_mfma_f32_16x16x32_bf16 v[98:101], v[142:145], v[204:207], v[98:101]
	v_mfma_f32_16x16x32_bf16 v[62:65], v[146:149], v[166:169], v[62:65]
	v_mfma_f32_16x16x32_bf16 v[58:61], v[158:161], v[166:169], v[58:61]
	v_mfma_f32_16x16x32_bf16 v[54:57], v[146:149], v[174:177], v[54:57]
	v_mfma_f32_16x16x32_bf16 v[50:53], v[158:161], v[174:177], v[50:53]
	v_mfma_f32_16x16x32_bf16 v[46:49], v[146:149], v[182:185], v[46:49]
	v_mfma_f32_16x16x32_bf16 v[42:45], v[158:161], v[182:185], v[42:45]
	v_mfma_f32_16x16x32_bf16 v[38:41], v[146:149], v[200:203], v[38:41]
	v_mfma_f32_16x16x32_bf16 v[34:37], v[158:161], v[200:203], v[34:37]
	v_mfma_f32_16x16x32_bf16 v[62:65], v[150:153], v[170:173], v[62:65]
	v_mfma_f32_16x16x32_bf16 v[58:61], v[162:165], v[170:173], v[58:61]
	v_mfma_f32_16x16x32_bf16 v[54:57], v[150:153], v[178:181], v[54:57]
	v_mfma_f32_16x16x32_bf16 v[50:53], v[162:165], v[178:181], v[50:53]
	v_mfma_f32_16x16x32_bf16 v[46:49], v[150:153], v[186:189], v[46:49]
	v_mfma_f32_16x16x32_bf16 v[42:45], v[162:165], v[186:189], v[42:45]
	v_mfma_f32_16x16x32_bf16 v[38:41], v[150:153], v[204:207], v[38:41]
	v_mfma_f32_16x16x32_bf16 v[34:37], v[162:165], v[204:207], v[34:37]
	s_barrier
; #define PG8_STAGE(bufoff, gbase, unused) do { _Pragma("unroll") for (int _i = 0; _i < 2; ++_i) \
;         __builtin_amdgcn_global_load_lds((const unsigned*)((const char*)(gbase) + voff + _i * 8192), (LAS unsigned*)(lds + (bufoff) + ldsw + _i * 8192), 16, 0, 0); } while (0)
; #define PG8_LDA(dst, b, h) do { _Pragma("unroll") for (int m = 0; m < 4; ++m) _Pragma("unroll") for (int k = 0; k < 2; ++k) dst[m][k] = *(const LAS bf16x8*)(lds + PG8_SA(b, h) + aoff + m * 2048 + (FP8 ? k * 16 : k * 1024)); } while (0)
; #define PG8_LDB(dst, b, h) do { _Pragma("unroll") for (int n = 0; n < 2; ++n) _Pragma("unroll") for (int k = 0; k < 2; ++k) dst[n][k] = *(const LAS bf16x8*)(lds + PG8_SB(b, h) + boff + n * 2048 + (FP8 ? k * 16 : k * 1024)); } while (0)
; template <class Epi, class Sched, bool ALIGN_EPI, bool SP2, int MODE  >
; __device__ __forceinline__ void gemm_phase(LAS unsigned char* lds, const Gemm g, const Sched S, const Epi E, unsigned long long& probe_acc, int epi_id, int wv) {
;     ...
;         for (int t = 0; t < nt; t += 2) {
;             const bool last = (t == nt - 2);
;             const char* a1 = cA + (size_t)(t + 1) * kstep;
;             const char* a2 = last ? nA : cA + (size_t)(t + 2) * kstep; const char* b2 = last ? nB : cB + (size_t)(t + 2) * kstep;
;             const char* a3 = a2 + kstep; const char* b3 = b2 + kstep;
;             if constexpr (SP2) {
;             PG8_LDB(B0, 0, 0); PG8_LDB(B1, 0, 1); PG8_SCHED; PG8_LDA(At, 0, 0); PG8_STAGE(PG8_SA(1, 1), a1 + hA, voffA);
;             PG8_WAIT_V(8); PG8_WAIT_L(0); PG8_BAR; PG8_MMA(0, 0, At, B0); PG8_MMA(0, 1, At, B1); PG8_BAR; PG8_SCHED;
;             PG8_LDA(At, 0, 1); PG8_STAGE(PG8_SB(0, 0), b2, voffB); PG8_STAGE(PG8_SB(0, 1), b2 + hB, voffB); PG8_STAGE(PG8_SA(0, 0), a2, voffA);
;             PG8_WAIT_V(8); PG8_WAIT_L(0); PG8_BAR; PG8_MMA(1, 0, At, B0); PG8_MMA(1, 1, At, B1); PG8_BAR; PG8_SCHED;
;             PG8_LDB(B0, 1, 0); PG8_LDB(B1, 1, 1); PG8_SCHED; PG8_LDA(At, 1, 0); PG8_STAGE(PG8_SA(0, 1), a2 + hA, voffA);
;             PG8_WAIT_V(8); PG8_WAIT_L(0); PG8_BAR; PG8_MMA(0, 0, At, B0); PG8_MMA(0, 1, At, B1); PG8_BAR; PG8_SCHED;
;             PG8_LDA(At, 1, 1); PG8_STAGE(PG8_SB(1, 0), b3, voffB); PG8_STAGE(PG8_SB(1, 1), b3 + hB, voffB); PG8_STAGE(PG8_SA(1, 0), a3, voffA);
;             PG8_WAIT_V(8); PG8_WAIT_L(0); PG8_BAR; PG8_MMA(1, 0, At, B0); PG8_MMA(1, 1, At, B1); PG8_BAR; PG8_SCHED;
	s_setprio 0
	s_add_u32 s6, s6, 0x4000
	s_addc_u32 s7, s7, 0
	s_mov_b32 m0, s2
	v_lshl_add_u64 v[196:197], s[6:7], 0, v[0:1]
	s_add_u32 s6, s6, s13
	ds_read_b128 v[166:169], v194 offset:49152
	ds_read_b128 v[170:173], v194 offset:50176
	ds_read_b128 v[174:177], v194 offset:51200
	ds_read_b128 v[178:181], v194 offset:52224
	ds_read_b128 v[182:185], v194 offset:53248
	ds_read_b128 v[186:189], v194 offset:54272
	ds_read_b128 v[200:203], v194 offset:55296
	ds_read_b128 v[204:207], v194 offset:56320
	global_load_lds_dwordx4 v[196:197], off
	v_lshl_add_u64 v[196:197], v[196:197], 0, s[70:71]
	s_mov_b32 m0, s3
	s_addc_u32 s7, s7, 0
	global_load_lds_dwordx4 v[196:197], off
	v_lshl_add_u64 v[196:197], s[6:7], 0, v[0:1]
	s_mov_b32 m0, s12
	s_nop 0
	global_load_lds_dwordx4 v[196:197], off
	v_lshl_add_u64 v[196:197], v[196:197], 0, s[70:71]
	s_mov_b32 m0, s95
	s_nop 0
	global_load_lds_dwordx4 v[196:197], off
	v_lshl_add_u64 v[196:197], v[190:191], 0, s[76:77]
	s_mov_b32 m0, s50
	v_lshl_add_u64 v[190:191], v[190:191], 0, s[78:79]
	global_load_lds_dwordx4 v[196:197], off
	s_mov_b32 m0, s51
	s_nop 0
	global_load_lds_dwordx4 v[190:191], off
	.p2align 3
	s_waitcnt vmcnt(8)
	s_waitcnt lgkmcnt(0)
	s_setprio 1
	s_barrier
	v_mfma_f32_16x16x32_bf16 v[94:97], v[130:133], v[166:169], v[94:97]
	v_mfma_f32_16x16x32_bf16 v[90:93], v[138:141], v[166:169], v[90:93]
	v_mfma_f32_16x16x32_bf16 v[86:89], v[130:133], v[174:177], v[86:89]
	v_mfma_f32_16x16x32_bf16 v[82:85], v[138:141], v[174:177], v[82:85]
	v_mfma_f32_16x16x32_bf16 v[78:81], v[130:133], v[182:185], v[78:81]
	v_mfma_f32_16x16x32_bf16 v[74:77], v[138:141], v[182:185], v[74:77]
	v_mfma_f32_16x16x32_bf16 v[70:73], v[130:133], v[200:203], v[70:73]
	v_mfma_f32_16x16x32_bf16 v[66:69], v[138:141], v[200:203], v[66:69]
	v_mfma_f32_16x16x32_bf16 v[94:97], v[134:137], v[170:173], v[94:97]
	v_mfma_f32_16x16x32_bf16 v[90:93], v[142:145], v[170:173], v[90:93]
	v_mfma_f32_16x16x32_bf16 v[86:89], v[134:137], v[178:181], v[86:89]
	v_mfma_f32_16x16x32_bf16 v[82:85], v[142:145], v[178:181], v[82:85]
	v_mfma_f32_16x16x32_bf16 v[78:81], v[134:137], v[186:189], v[78:81]
	v_mfma_f32_16x16x32_bf16 v[74:77], v[142:145], v[186:189], v[74:77]
	v_mfma_f32_16x16x32_bf16 v[70:73], v[134:137], v[204:207], v[70:73]
	v_mfma_f32_16x16x32_bf16 v[66:69], v[142:145], v[204:207], v[66:69]
	v_mfma_f32_16x16x32_bf16 v[30:33], v[146:149], v[166:169], v[30:33]
	v_mfma_f32_16x16x32_bf16 v[26:29], v[158:161], v[166:169], v[26:29]
	v_mfma_f32_16x16x32_bf16 v[22:25], v[146:149], v[174:177], v[22:25]
	v_mfma_f32_16x16x32_bf16 v[18:21], v[158:161], v[174:177], v[18:21]
	v_mfma_f32_16x16x32_bf16 v[14:17], v[146:149], v[182:185], v[14:17]
	v_mfma_f32_16x16x32_bf16 v[10:13], v[158:161], v[182:185], v[10:13]
	v_mfma_f32_16x16x32_bf16 v[6:9], v[146:149], v[200:203], v[6:9]
	v_mfma_f32_16x16x32_bf16 v[2:5], v[158:161], v[200:203], v[2:5]
	v_mfma_f32_16x16x32_bf16 v[30:33], v[150:153], v[170:173], v[30:33]
	v_mfma_f32_16x16x32_bf16 v[26:29], v[162:165], v[170:173], v[26:29]
	v_mfma_f32_16x16x32_bf16 v[22:25], v[150:153], v[178:181], v[22:25]
	v_mfma_f32_16x16x32_bf16 v[18:21], v[162:165], v[178:181], v[18:21]
	v_mfma_f32_16x16x32_bf16 v[14:17], v[150:153], v[186:189], v[14:17]
	v_mfma_f32_16x16x32_bf16 v[10:13], v[162:165], v[186:189], v[10:13]
	v_mfma_f32_16x16x32_bf16 v[6:9], v[150:153], v[204:207], v[6:9]
	v_mfma_f32_16x16x32_bf16 v[2:5], v[162:165], v[204:207], v[2:5]
	s_barrier
	s_setprio 0
	s_add_u32 s10, s10, 0x8000
	s_addc_u32 s11, s11, 0
	s_add_u32 s4, s4, 0x8000
	s_addc_u32 s5, s5, 0
	s_cmp_ge_u32 s40, s58
	s_mov_b32 s6, s40
.LBB0_674:
	v_add_u32_e32 v142, s15, v193
	v_add_u32_e32 v156, s39, v193
	ds_read_b128 v[130:133], v142
	ds_read_b128 v[134:137], v142 offset:1024
	ds_read_b128 v[138:141], v142 offset:2048
	ds_read_b128 v[142:145], v142 offset:3072
	ds_read_b128 v[146:149], v156
	ds_read_b128 v[150:153], v156 offset:1024
	ds_read_b128 v[158:161], v156 offset:2048
	ds_read_b128 v[162:165], v156 offset:3072
	s_add_i32 s40, s6, 2
	s_cmp_eq_u32 s93, s6
	s_cselect_b32 s6, s34, s10
	s_cselect_b32 s9, s87, s5
	s_cselect_b32 s8, s86, s4
	s_cselect_b32 s7, s35, s11
	s_movk_i32 vcc_lo, 0xc000
	v_lshl_add_u64 v[190:191], s[4:5], 0, v[154:155]
	s_mov_b32 vcc_hi, -1
	v_lshl_add_u64 v[196:197], v[190:191], 0, vcc
	s_movk_i32 vcc_lo, 0xe000
	s_add_i32 m0, s88, 0xc000
	s_mov_b32 vcc_hi, -1
	ds_read_b128 v[166:169], v194
	ds_read_b128 v[170:173], v194 offset:1024
	ds_read_b128 v[174:177], v194 offset:2048
	ds_read_b128 v[178:181], v194 offset:3072
	ds_read_b128 v[182:185], v194 offset:4096
	ds_read_b128 v[186:189], v194 offset:5120
	ds_read_b128 v[200:203], v194 offset:6144
	ds_read_b128 v[204:207], v194 offset:7168
	global_load_lds_dwordx4 v[196:197], off
	v_lshl_add_u64 v[190:191], v[190:191], 0, vcc
	s_add_i32 m0, s88, 0xe000
	s_nop 0
	global_load_lds_dwordx4 v[190:191], off
	.p2align 3
	s_waitcnt vmcnt(8)
	s_waitcnt lgkmcnt(0)
	s_setprio 1
	s_barrier
; #define PG8_STAGE(bufoff, gbase, unused) do { _Pragma("unroll") for (int _i = 0; _i < 2; ++_i) \
;         __builtin_amdgcn_global_load_lds((const unsigned*)((const char*)(gbase) + voff + _i * 8192), (LAS unsigned*)(lds + (bufoff) + ldsw + _i * 8192), 16, 0, 0); } while (0)
; #define PG8_LDA(dst, b, h) do { _Pragma("unroll") for (int m = 0; m < 4; ++m) _Pragma("unroll") for (int k = 0; k < 2; ++k) dst[m][k] = *(const LAS bf16x8*)(lds + PG8_SA(b, h) + aoff + m * 2048 + (FP8 ? k * 16 : k * 1024)); } while (0)
; #define PG8_LDB(dst, b, h) do { _Pragma("unroll") for (int n = 0; n < 2; ++n) _Pragma("unroll") for (int k = 0; k < 2; ++k) dst[n][k] = *(const LAS bf16x8*)(lds + PG8_SB(b, h) + boff + n * 2048 + (FP8 ? k * 16 : k * 1024)); } while (0)
; #define PG8_WAIT_V(n) asm volatile("s_waitcnt vmcnt(" #n ")" ::: "memory")
; #define PG8_WAIT_L(n) asm volatile("s_waitcnt lgkmcnt(" #n ")" ::: "memory")
; #define PG8_BAR __builtin_amdgcn_s_barrier()
; #define PG8_SCHED __builtin_amdgcn_sched_barrier(0)
; template <class Epi, class Sched, bool ALIGN_EPI, bool SP2, int MODE  >
; __device__ __forceinline__ void gemm_phase(LAS unsigned char* lds, const Gemm g, const Sched S, const Epi E, unsigned long long& probe_acc, int epi_id, int wv) {
;     ...
;             PG8_LDB(B0, 0, 0); PG8_LDB(B1, 0, 1); PG8_SCHED; PG8_LDA(At, 0, 0); PG8_STAGE(PG8_SA(1, 1), a1 + hA, voffA);
;             PG8_WAIT_V(8); PG8_WAIT_L(0); PG8_BAR; PG8_MMA(0, 0, At, B0); PG8_MMA(0, 1, At, B1); PG8_BAR; PG8_SCHED;
;             PG8_LDA(At, 0, 1); PG8_STAGE(PG8_SB(0, 0), b2, voffB); PG8_STAGE(PG8_SB(0, 1), b2 + hB, voffB); PG8_STAGE(PG8_SA(0, 0), a2, voffA);
;             PG8_WAIT_V(8); PG8_WAIT_L(0); PG8_BAR; PG8_MMA(1, 0, At, B0); PG8_MMA(1, 1, At, B1); PG8_BAR; PG8_SCHED;
;             PG8_LDB(B0, 1, 0); PG8_LDB(B1, 1, 1); PG8_SCHED; PG8_LDA(At, 1, 0); PG8_STAGE(PG8_SA(0, 1), a2 + hA, voffA);
;             PG8_WAIT_V(8); PG8_WAIT_L(0); PG8_BAR; PG8_MMA(0, 0, At, B0); PG8_MMA(0, 1, At, B1); PG8_BAR; PG8_SCHED;
	v_mfma_f32_16x16x32_bf16 v[126:129], v[130:133], v[166:169], v[126:129]
	v_mfma_f32_16x16x32_bf16 v[122:125], v[138:141], v[166:169], v[122:125]
	v_mfma_f32_16x16x32_bf16 v[118:121], v[130:133], v[174:177], v[118:121]
	v_mfma_f32_16x16x32_bf16 v[114:117], v[138:141], v[174:177], v[114:117]
	v_mfma_f32_16x16x32_bf16 v[110:113], v[130:133], v[182:185], v[110:113]
	v_mfma_f32_16x16x32_bf16 v[106:109], v[138:141], v[182:185], v[106:109]
	v_mfma_f32_16x16x32_bf16 v[102:105], v[130:133], v[200:203], v[102:105]
	v_mfma_f32_16x16x32_bf16 v[98:101], v[138:141], v[200:203], v[98:101]
	v_mfma_f32_16x16x32_bf16 v[126:129], v[134:137], v[170:173], v[126:129]
	v_mfma_f32_16x16x32_bf16 v[122:125], v[142:145], v[170:173], v[122:125]
	v_mfma_f32_16x16x32_bf16 v[118:121], v[134:137], v[178:181], v[118:121]
	v_mfma_f32_16x16x32_bf16 v[114:117], v[142:145], v[178:181], v[114:117]
	v_mfma_f32_16x16x32_bf16 v[110:113], v[134:137], v[186:189], v[110:113]
	v_mfma_f32_16x16x32_bf16 v[106:109], v[142:145], v[186:189], v[106:109]
	v_mfma_f32_16x16x32_bf16 v[102:105], v[134:137], v[204:207], v[102:105]
	v_mfma_f32_16x16x32_bf16 v[98:101], v[142:145], v[204:207], v[98:101]
	v_mfma_f32_16x16x32_bf16 v[62:65], v[146:149], v[166:169], v[62:65]
	v_mfma_f32_16x16x32_bf16 v[58:61], v[158:161], v[166:169], v[58:61]
	v_mfma_f32_16x16x32_bf16 v[54:57], v[146:149], v[174:177], v[54:57]
	v_mfma_f32_16x16x32_bf16 v[50:53], v[158:161], v[174:177], v[50:53]
	v_mfma_f32_16x16x32_bf16 v[46:49], v[146:149], v[182:185], v[46:49]
	v_mfma_f32_16x16x32_bf16 v[42:45], v[158:161], v[182:185], v[42:45]
	v_mfma_f32_16x16x32_bf16 v[38:41], v[146:149], v[200:203], v[38:41]
	v_mfma_f32_16x16x32_bf16 v[34:37], v[158:161], v[200:203], v[34:37]
	v_mfma_f32_16x16x32_bf16 v[62:65], v[150:153], v[170:173], v[62:65]
	v_mfma_f32_16x16x32_bf16 v[58:61], v[162:165], v[170:173], v[58:61]
	v_mfma_f32_16x16x32_bf16 v[54:57], v[150:153], v[178:181], v[54:57]
	v_mfma_f32_16x16x32_bf16 v[50:53], v[162:165], v[178:181], v[50:53]
	v_mfma_f32_16x16x32_bf16 v[46:49], v[150:153], v[186:189], v[46:49]
	v_mfma_f32_16x16x32_bf16 v[42:45], v[162:165], v[186:189], v[42:45]
	v_mfma_f32_16x16x32_bf16 v[38:41], v[150:153], v[204:207], v[38:41]
	v_mfma_f32_16x16x32_bf16 v[34:37], v[162:165], v[204:207], v[34:37]
	s_barrier
	s_setprio 0
	s_mov_b32 m0, s26
	v_lshl_add_u64 v[190:191], s[6:7], 0, v[0:1]
	s_add_u32 vcc_lo, s6, s13
	ds_read_b128 v[166:169], v194 offset:16384
	ds_read_b128 v[170:173], v194 offset:17408
	ds_read_b128 v[174:177], v194 offset:18432
	ds_read_b128 v[178:181], v194 offset:19456
	ds_read_b128 v[182:185], v194 offset:20480
	ds_read_b128 v[186:189], v194 offset:21504
	ds_read_b128 v[200:203], v194 offset:22528
	ds_read_b128 v[204:207], v194 offset:23552
	global_load_lds_dwordx4 v[190:191], off
	v_lshl_add_u64 v[190:191], v[190:191], 0, s[70:71]
	s_mov_b32 m0, s27
	s_addc_u32 vcc_hi, s7, 0
	global_load_lds_dwordx4 v[190:191], off
	v_lshl_add_u64 v[190:191], vcc, 0, v[0:1]
	s_mov_b32 m0, s84
	s_nop 0
	global_load_lds_dwordx4 v[190:191], off
	v_lshl_add_u64 v[190:191], v[190:191], 0, s[70:71]
	s_mov_b32 m0, s85
	s_nop 0
	global_load_lds_dwordx4 v[190:191], off
	v_lshl_add_u64 v[190:191], s[8:9], 0, v[0:1]
	s_mov_b32 m0, s88
	v_lshl_add_u64 v[196:197], v[190:191], 0, s[70:71]
	global_load_lds_dwordx4 v[190:191], off
	s_mov_b32 m0, s89
	s_nop 0
	global_load_lds_dwordx4 v[196:197], off
	.p2align 3
	s_waitcnt vmcnt(8)
	s_waitcnt lgkmcnt(0)
	s_setprio 1
	s_barrier
	v_mfma_f32_16x16x32_bf16 v[94:97], v[130:133], v[166:169], v[94:97]
	v_mfma_f32_16x16x32_bf16 v[90:93], v[138:141], v[166:169], v[90:93]
	v_mfma_f32_16x16x32_bf16 v[86:89], v[130:133], v[174:177], v[86:89]
	v_mfma_f32_16x16x32_bf16 v[82:85], v[138:141], v[174:177], v[82:85]
	v_mfma_f32_16x16x32_bf16 v[78:81], v[130:133], v[182:185], v[78:81]
	v_mfma_f32_16x16x32_bf16 v[74:77], v[138:141], v[182:185], v[74:77]
	v_mfma_f32_16x16x32_bf16 v[70:73], v[130:133], v[200:203], v[70:73]
	v_mfma_f32_16x16x32_bf16 v[66:69], v[138:141], v[200:203], v[66:69]
	v_mfma_f32_16x16x32_bf16 v[94:97], v[134:137], v[170:173], v[94:97]
	v_mfma_f32_16x16x32_bf16 v[90:93], v[142:145], v[170:173], v[90:93]
	v_mfma_f32_16x16x32_bf16 v[86:89], v[134:137], v[178:181], v[86:89]
	v_mfma_f32_16x16x32_bf16 v[82:85], v[142:145], v[178:181], v[82:85]
	v_mfma_f32_16x16x32_bf16 v[78:81], v[134:137], v[186:189], v[78:81]
	v_mfma_f32_16x16x32_bf16 v[74:77], v[142:145], v[186:189], v[74:77]
	v_mfma_f32_16x16x32_bf16 v[70:73], v[134:137], v[204:207], v[70:73]
	v_mfma_f32_16x16x32_bf16 v[66:69], v[142:145], v[204:207], v[66:69]
	v_mfma_f32_16x16x32_bf16 v[30:33], v[146:149], v[166:169], v[30:33]
	v_mfma_f32_16x16x32_bf16 v[26:29], v[158:161], v[166:169], v[26:29]
	v_mfma_f32_16x16x32_bf16 v[22:25], v[146:149], v[174:177], v[22:25]
	v_mfma_f32_16x16x32_bf16 v[18:21], v[158:161], v[174:177], v[18:21]
	v_mfma_f32_16x16x32_bf16 v[14:17], v[146:149], v[182:185], v[14:17]
	v_mfma_f32_16x16x32_bf16 v[10:13], v[158:161], v[182:185], v[10:13]
	v_mfma_f32_16x16x32_bf16 v[6:9], v[146:149], v[200:203], v[6:9]
	v_mfma_f32_16x16x32_bf16 v[2:5], v[158:161], v[200:203], v[2:5]
	v_mfma_f32_16x16x32_bf16 v[30:33], v[150:153], v[170:173], v[30:33]
	v_mfma_f32_16x16x32_bf16 v[26:29], v[162:165], v[170:173], v[26:29]
	v_mfma_f32_16x16x32_bf16 v[22:25], v[150:153], v[178:181], v[22:25]
	v_mfma_f32_16x16x32_bf16 v[18:21], v[162:165], v[178:181], v[18:21]
	v_mfma_f32_16x16x32_bf16 v[14:17], v[150:153], v[186:189], v[14:17]
	v_mfma_f32_16x16x32_bf16 v[10:13], v[162:165], v[186:189], v[10:13]
	v_mfma_f32_16x16x32_bf16 v[6:9], v[150:153], v[204:207], v[6:9]
	v_mfma_f32_16x16x32_bf16 v[2:5], v[162:165], v[204:207], v[2:5]
	s_barrier
; #define PG8_STAGE(bufoff, gbase, unused) do { _Pragma("unroll") for (int _i = 0; _i < 2; ++_i) \
;         __builtin_amdgcn_global_load_lds((const unsigned*)((const char*)(gbase) + voff + _i * 8192), (LAS unsigned*)(lds + (bufoff) + ldsw + _i * 8192), 16, 0, 0); } while (0)
; #define PG8_LDA(dst, b, h) do { _Pragma("unroll") for (int m = 0; m < 4; ++m) _Pragma("unroll") for (int k = 0; k < 2; ++k) dst[m][k] = *(const LAS bf16x8*)(lds + PG8_SA(b, h) + aoff + m * 2048 + (FP8 ? k * 16 : k * 1024)); } while (0)
; #define PG8_LDB(dst, b, h) do { _Pragma("unroll") for (int n = 0; n < 2; ++n) _Pragma("unroll") for (int k = 0; k < 2; ++k) dst[n][k] = *(const LAS bf16x8*)(lds + PG8_SB(b, h) + boff + n * 2048 + (FP8 ? k * 16 : k * 1024)); } while (0)
; #define PG8_WAIT_V(n) asm volatile("s_waitcnt vmcnt(" #n ")" ::: "memory")
; #define PG8_WAIT_L(n) asm volatile("s_waitcnt lgkmcnt(" #n ")" ::: "memory")
; #define PG8_BAR __builtin_amdgcn_s_barrier()
; #define PG8_SCHED __builtin_amdgcn_sched_barrier(0)
; template <class Epi, class Sched, bool ALIGN_EPI, bool SP2, int MODE  >
; __device__ __forceinline__ void gemm_phase(LAS unsigned char* lds, const Gemm g, const Sched S, const Epi E, unsigned long long& probe_acc, int epi_id, int wv) {
;     ...
;             PG8_LDB(B0, 1, 0); PG8_LDB(B1, 1, 1); PG8_SCHED; PG8_LDA(At, 1, 0); PG8_STAGE(PG8_SA(0, 1), a2 + hA, voffA);
;             PG8_WAIT_V(8); PG8_WAIT_L(0); PG8_BAR; PG8_MMA(0, 0, At, B0); PG8_MMA(0, 1, At, B1); PG8_BAR; PG8_SCHED;
	s_setprio 0
	v_add_u32_e32 v142, s28, v193
	v_add_u32_e32 v156, s94, v193
	ds_read_b128 v[130:133], v142
	ds_read_b128 v[134:137], v142 offset:1024
	ds_read_b128 v[138:141], v142 offset:2048
	ds_read_b128 v[142:145], v142 offset:3072
	ds_read_b128 v[146:149], v156
	ds_read_b128 v[150:153], v156 offset:1024
	ds_read_b128 v[158:161], v156 offset:2048
	ds_read_b128 v[162:165], v156 offset:3072
	s_add_u32 s8, s8, s36
	s_addc_u32 s9, s9, 0
	s_mov_b32 m0, s29
	v_lshl_add_u64 v[196:197], s[8:9], 0, v[0:1]
	ds_read_b128 v[166:169], v194 offset:32768
	ds_read_b128 v[170:173], v194 offset:33792
	ds_read_b128 v[174:177], v194 offset:34816
	ds_read_b128 v[178:181], v194 offset:35840
	ds_read_b128 v[182:185], v194 offset:36864
	ds_read_b128 v[186:189], v194 offset:37888
	ds_read_b128 v[200:203], v194 offset:38912
	ds_read_b128 v[204:207], v194 offset:39936
	global_load_lds_dwordx4 v[196:197], off
	v_lshl_add_u64 v[196:197], v[196:197], 0, s[70:71]
	s_mov_b32 m0, s92
	s_nop 0
	global_load_lds_dwordx4 v[196:197], off
	.p2align 3
	s_waitcnt vmcnt(8)
	s_waitcnt lgkmcnt(0)
	s_setprio 1
	s_barrier
	v_mfma_f32_16x16x32_bf16 v[126:129], v[130:133], v[166:169], v[126:129]
	v_mfma_f32_16x16x32_bf16 v[122:125], v[138:141], v[166:169], v[122:125]
	v_mfma_f32_16x16x32_bf16 v[118:121], v[130:133], v[174:177], v[118:121]
	v_mfma_f32_16x16x32_bf16 v[114:117], v[138:141], v[174:177], v[114:117]
	v_mfma_f32_16x16x32_bf16 v[110:113], v[130:133], v[182:185], v[110:113]
	v_mfma_f32_16x16x32_bf16 v[106:109], v[138:141], v[182:185], v[106:109]
	v_mfma_f32_16x16x32_bf16 v[102:105], v[130:133], v[200:203], v[102:105]
	v_mfma_f32_16x16x32_bf16 v[98:101], v[138:141], v[200:203], v[98:101]
	v_mfma_f32_16x16x32_bf16 v[126:129], v[134:137], v[170:173], v[126:129]
	v_mfma_f32_16x16x32_bf16 v[122:125], v[142:145], v[170:173], v[122:125]
	v_mfma_f32_16x16x32_bf16 v[118:121], v[134:137], v[178:181], v[118:121]
	v_mfma_f32_16x16x32_bf16 v[114:117], v[142:145], v[178:181], v[114:117]
	v_mfma_f32_16x16x32_bf16 v[110:113], v[134:137], v[186:189], v[110:113]
	v_mfma_f32_16x16x32_bf16 v[106:109], v[142:145], v[186:189], v[106:109]
	v_mfma_f32_16x16x32_bf16 v[102:105], v[134:137], v[204:207], v[102:105]
	v_mfma_f32_16x16x32_bf16 v[98:101], v[142:145], v[204:207], v[98:101]
	v_mfma_f32_16x16x32_bf16 v[62:65], v[146:149], v[166:169], v[62:65]
	v_mfma_f32_16x16x32_bf16 v[58:61], v[158:161], v[166:169], v[58:61]
	v_mfma_f32_16x16x32_bf16 v[54:57], v[146:149], v[174:177], v[54:57]
	v_mfma_f32_16x16x32_bf16 v[50:53], v[158:161], v[174:177], v[50:53]
	v_mfma_f32_16x16x32_bf16 v[46:49], v[146:149], v[182:185], v[46:49]
	v_mfma_f32_16x16x32_bf16 v[42:45], v[158:161], v[182:185], v[42:45]
	v_mfma_f32_16x16x32_bf16 v[38:41], v[146:149], v[200:203], v[38:41]
	v_mfma_f32_16x16x32_bf16 v[34:37], v[158:161], v[200:203], v[34:37]
	v_mfma_f32_16x16x32_bf16 v[62:65], v[150:153], v[170:173], v[62:65]
	v_mfma_f32_16x16x32_bf16 v[58:61], v[162:165], v[170:173], v[58:61]
	v_mfma_f32_16x16x32_bf16 v[54:57], v[150:153], v[178:181], v[54:57]
	v_mfma_f32_16x16x32_bf16 v[50:53], v[162:165], v[178:181], v[50:53]
	v_mfma_f32_16x16x32_bf16 v[46:49], v[150:153], v[186:189], v[46:49]
	v_mfma_f32_16x16x32_bf16 v[42:45], v[162:165], v[186:189], v[42:45]
	v_mfma_f32_16x16x32_bf16 v[38:41], v[150:153], v[204:207], v[38:41]
	v_mfma_f32_16x16x32_bf16 v[34:37], v[162:165], v[204:207], v[34:37]
	s_barrier
; #define PG8_STAGE(bufoff, gbase, unused) do { _Pragma("unroll") for (int _i = 0; _i < 2; ++_i) \
;         __builtin_amdgcn_global_load_lds((const unsigned*)((const char*)(gbase) + voff + _i * 8192), (LAS unsigned*)(lds + (bufoff) + ldsw + _i * 8192), 16, 0, 0); } while (0)
; #define PG8_LDA(dst, b, h) do { _Pragma("unroll") for (int m = 0; m < 4; ++m) _Pragma("unroll") for (int k = 0; k < 2; ++k) dst[m][k] = *(const LAS bf16x8*)(lds + PG8_SA(b, h) + aoff + m * 2048 + (FP8 ? k * 16 : k * 1024)); } while (0)
; #define PG8_WAIT_V(n) asm volatile("s_waitcnt vmcnt(" #n ")" ::: "memory")
; #define PG8_WAIT_L(n) asm volatile("s_waitcnt lgkmcnt(" #n ")" ::: "memory")
; #define PG8_BAR __builtin_amdgcn_s_barrier()
; #define PG8_SCHED __builtin_amdgcn_sched_barrier(0)
; template <class Epi, class Sched, bool ALIGN_EPI, bool SP2, int MODE  >
; __device__ __forceinline__ void gemm_phase(LAS unsigned char* lds, const Gemm g, const Sched S, const Epi E, unsigned long long& probe_acc, int epi_id, int wv) {
;     ...
;         for (int t = 0; t < nt; t += 2) {
;     ...
;             PG8_LDA(At, 1, 1); PG8_STAGE(PG8_SB(1, 0), b3, voffB); PG8_STAGE(PG8_SB(1, 1), b3 + hB, voffB); PG8_STAGE(PG8_SA(1, 0), a3, voffA);
;             PG8_WAIT_V(8); PG8_WAIT_L(0); PG8_BAR; PG8_MMA(1, 0, At, B0); PG8_MMA(1, 1, At, B1); PG8_BAR; PG8_SCHED;
	s_setprio 0
	s_add_u32 s6, s6, 0x4000
	s_addc_u32 s7, s7, 0
	s_mov_b32 m0, s2
	v_lshl_add_u64 v[196:197], s[6:7], 0, v[0:1]
	s_add_u32 s6, s6, s13
	ds_read_b128 v[166:169], v194 offset:49152
	ds_read_b128 v[170:173], v194 offset:50176
	ds_read_b128 v[174:177], v194 offset:51200
	ds_read_b128 v[178:181], v194 offset:52224
	ds_read_b128 v[182:185], v194 offset:53248
	ds_read_b128 v[186:189], v194 offset:54272
	ds_read_b128 v[200:203], v194 offset:55296
	ds_read_b128 v[204:207], v194 offset:56320
	global_load_lds_dwordx4 v[196:197], off
	v_lshl_add_u64 v[196:197], v[196:197], 0, s[70:71]
	s_mov_b32 m0, s3
	s_addc_u32 s7, s7, 0
	global_load_lds_dwordx4 v[196:197], off
	v_lshl_add_u64 v[196:197], s[6:7], 0, v[0:1]
	s_mov_b32 m0, s12
	s_nop 0
	global_load_lds_dwordx4 v[196:197], off
	v_lshl_add_u64 v[196:197], v[196:197], 0, s[70:71]
	s_mov_b32 m0, s95
	s_nop 0
	global_load_lds_dwordx4 v[196:197], off
	v_lshl_add_u64 v[196:197], v[190:191], 0, s[76:77]
	s_mov_b32 m0, s50
	v_lshl_add_u64 v[190:191], v[190:191], 0, s[78:79]
	global_load_lds_dwordx4 v[196:197], off
	s_mov_b32 m0, s51
	s_nop 0
	global_load_lds_dwordx4 v[190:191], off
	.p2align 3
	s_waitcnt vmcnt(8)
	s_waitcnt lgkmcnt(0)
	s_setprio 1
	s_barrier
	v_mfma_f32_16x16x32_bf16 v[94:97], v[130:133], v[166:169], v[94:97]
	v_mfma_f32_16x16x32_bf16 v[90:93], v[138:141], v[166:169], v[90:93]
	v_mfma_f32_16x16x32_bf16 v[86:89], v[130:133], v[174:177], v[86:89]
	v_mfma_f32_16x16x32_bf16 v[82:85], v[138:141], v[174:177], v[82:85]
	v_mfma_f32_16x16x32_bf16 v[78:81], v[130:133], v[182:185], v[78:81]
	v_mfma_f32_16x16x32_bf16 v[74:77], v[138:141], v[182:185], v[74:77]
	v_mfma_f32_16x16x32_bf16 v[70:73], v[130:133], v[200:203], v[70:73]
	v_mfma_f32_16x16x32_bf16 v[66:69], v[138:141], v[200:203], v[66:69]
	v_mfma_f32_16x16x32_bf16 v[94:97], v[134:137], v[170:173], v[94:97]
	v_mfma_f32_16x16x32_bf16 v[90:93], v[142:145], v[170:173], v[90:93]
	v_mfma_f32_16x16x32_bf16 v[86:89], v[134:137], v[178:181], v[86:89]
	v_mfma_f32_16x16x32_bf16 v[82:85], v[142:145], v[178:181], v[82:85]
	v_mfma_f32_16x16x32_bf16 v[78:81], v[134:137], v[186:189], v[78:81]
	v_mfma_f32_16x16x32_bf16 v[74:77], v[142:145], v[186:189], v[74:77]
	v_mfma_f32_16x16x32_bf16 v[70:73], v[134:137], v[204:207], v[70:73]
	v_mfma_f32_16x16x32_bf16 v[66:69], v[142:145], v[204:207], v[66:69]
	v_mfma_f32_16x16x32_bf16 v[30:33], v[146:149], v[166:169], v[30:33]
	v_mfma_f32_16x16x32_bf16 v[26:29], v[158:161], v[166:169], v[26:29]
	v_mfma_f32_16x16x32_bf16 v[22:25], v[146:149], v[174:177], v[22:25]
	v_mfma_f32_16x16x32_bf16 v[18:21], v[158:161], v[174:177], v[18:21]
	v_mfma_f32_16x16x32_bf16 v[14:17], v[146:149], v[182:185], v[14:17]
	v_mfma_f32_16x16x32_bf16 v[10:13], v[158:161], v[182:185], v[10:13]
	v_mfma_f32_16x16x32_bf16 v[6:9], v[146:149], v[200:203], v[6:9]
	v_mfma_f32_16x16x32_bf16 v[2:5], v[158:161], v[200:203], v[2:5]
	v_mfma_f32_16x16x32_bf16 v[30:33], v[150:153], v[170:173], v[30:33]
	v_mfma_f32_16x16x32_bf16 v[26:29], v[162:165], v[170:173], v[26:29]
	v_mfma_f32_16x16x32_bf16 v[22:25], v[150:153], v[178:181], v[22:25]
	v_mfma_f32_16x16x32_bf16 v[18:21], v[162:165], v[178:181], v[18:21]
	v_mfma_f32_16x16x32_bf16 v[14:17], v[150:153], v[186:189], v[14:17]
	v_mfma_f32_16x16x32_bf16 v[10:13], v[162:165], v[186:189], v[10:13]
	v_mfma_f32_16x16x32_bf16 v[6:9], v[150:153], v[204:207], v[6:9]
	v_mfma_f32_16x16x32_bf16 v[2:5], v[162:165], v[204:207], v[2:5]
	s_barrier
	s_setprio 0
	s_add_u32 s10, s10, 0x8000
	s_addc_u32 s11, s11, 0
	s_add_u32 s4, s4, 0x8000
	s_addc_u32 s5, s5, 0
	s_cmp_ge_u32 s40, s58
	s_mov_b32 s6, s40
	s_cbranch_scc0 .LBB0_674
	v_readlane_b32 s4, v255, 30
	v_readlane_b32 s5, v255, 31
	s_and_b64 vcc, exec, s[4:5]
	s_cbranch_vccz .LBB0_677
	s_barrier

; #define PG8_STAGE(bufoff, gbase, unused) do { _Pragma("unroll") for (int _i = 0; _i < 2; ++_i) \
;         __builtin_amdgcn_global_load_lds((const unsigned*)((const char*)(gbase) + voff + _i * 8192), (LAS unsigned*)(lds + (bufoff) + ldsw + _i * 8192), 16, 0, 0); } while (0)
; #define PG8_LDA(dst, b, h) do { _Pragma("unroll") for (int m = 0; m < 4; ++m) _Pragma("unroll") for (int k = 0; k < 2; ++k) dst[m][k] = *(const LAS bf16x8*)(lds + PG8_SA(b, h) + aoff + m * 2048 + (FP8 ? k * 16 : k * 1024)); } while (0)
; #define PG8_LDB(dst, b, h) do { _Pragma("unroll") for (int n = 0; n < 2; ++n) _Pragma("unroll") for (int k = 0; k < 2; ++k) dst[n][k] = *(const LAS bf16x8*)(lds + PG8_SB(b, h) + boff + n * 2048 + (FP8 ? k * 16 : k * 1024)); } while (0)
; #define PG8_WAIT_V(n) asm volatile("s_waitcnt vmcnt(" #n ")" ::: "memory")
; #define PG8_WAIT_L(n) asm volatile("s_waitcnt lgkmcnt(" #n ")" ::: "memory")
; #define PG8_BAR __builtin_amdgcn_s_barrier()
; #define PG8_SCHED __builtin_amdgcn_sched_barrier(0)
; template <class Epi, class Sched, bool ALIGN_EPI, bool SP2, int MODE  >
; __device__ __forceinline__ void gemm_phase(LAS unsigned char* lds, const Gemm g, const Sched S, const Epi E, unsigned long long& probe_acc, int epi_id, int wv) {
;     ...
;         for (int t = 0; t < nt; t += 2) {
;             const bool last = (t == nt - 2);
;             const char* a1 = cA + (size_t)(t + 1) * kstep;
;             const char* a2 = last ? nA : cA + (size_t)(t + 2) * kstep; const char* b2 = last ? nB : cB + (size_t)(t + 2) * kstep;
;             const char* a3 = a2 + kstep; const char* b3 = b2 + kstep;
;             if constexpr (SP2) {
;             PG8_LDB(B0, 0, 0); PG8_LDB(B1, 0, 1); PG8_SCHED; PG8_LDA(At, 0, 0); PG8_STAGE(PG8_SA(1, 1), a1 + hA, voffA);
;             PG8_WAIT_V(8); PG8_WAIT_L(0); PG8_BAR; PG8_MMA(0, 0, At, B0); PG8_MMA(0, 1, At, B1); PG8_BAR; PG8_SCHED;
;             PG8_LDA(At, 0, 1); PG8_STAGE(PG8_SB(0, 0), b2, voffB); PG8_STAGE(PG8_SB(0, 1), b2 + hB, voffB); PG8_STAGE(PG8_SA(0, 0), a2, voffA);
;             PG8_WAIT_V(8); PG8_WAIT_L(0); PG8_BAR; PG8_MMA(1, 0, At, B0); PG8_MMA(1, 1, At, B1); PG8_BAR; PG8_SCHED;
.LBB0_914:
	v_add_u32_e32 v144, s14, v191
	v_add_u32_e32 v148, s27, v191
	s_add_u32 s8, s4, s6
	ds_read_b128 v[132:135], v144
	v_xor_b32_e32 v154, 16, v144
	ds_read_b128 v[136:139], v154
	ds_read_b128 v[140:143], v144 offset:2048
	ds_read_b128 v[144:147], v154 offset:2048
	ds_read_b128 v[156:159], v148
	v_xor_b32_e32 v154, 16, v148
	ds_read_b128 v[160:163], v154
	ds_read_b128 v[164:167], v148 offset:2048
	ds_read_b128 v[168:171], v154 offset:2048
	s_addc_u32 s9, s5, s7
	s_add_u32 s8, s8, 0x8000
	s_addc_u32 s9, s9, 0
	s_add_u32 s10, s34, s6
	s_addc_u32 s11, s35, s7
	s_cmp_eq_u32 s6, 0xa8000
	s_cselect_b32 s9, s69, s9
	s_cselect_b32 s8, s68, s8
	s_cselect_b32 s11, s91, s11
	s_cselect_b32 s10, s90, s10
	v_lshl_add_u64 v[148:149], v[130:131], 0, s[6:7]
	v_lshl_add_u64 v[150:151], v[148:149], 0, s[76:77]
	s_add_i32 m0, s41, 0xc000
	ds_read_b128 v[172:175], v192
	ds_read_b128 v[176:179], v193
	ds_read_b128 v[180:183], v192 offset:2048
	ds_read_b128 v[184:187], v193 offset:2048
	ds_read_b128 v[212:215], v192 offset:4096
	ds_read_b128 v[216:219], v193 offset:4096
	ds_read_b128 v[220:223], v192 offset:6144
	ds_read_b128 v[224:227], v193 offset:6144
	global_load_lds_dwordx4 v[150:151], off
	v_lshl_add_u64 v[148:149], v[148:149], 0, s[78:79]
	s_add_i32 m0, s41, 0xe000
	s_nop 0
	global_load_lds_dwordx4 v[148:149], off
	.p2align 3
	s_waitcnt vmcnt(8)
	s_waitcnt lgkmcnt(0)
	s_setprio 1
	s_barrier
	v_mfma_scale_f32_16x16x128_f8f6f4 v[126:129], v[132:139], v[172:179], v[126:129], v208, v208 op_sel_hi:[0,0,0]
	v_mfma_scale_f32_16x16x128_f8f6f4 v[122:125], v[140:147], v[172:179], v[122:125], v208, v208 op_sel_hi:[0,0,0]
	v_mfma_scale_f32_16x16x128_f8f6f4 v[118:121], v[132:139], v[180:187], v[118:121], v208, v208 op_sel_hi:[0,0,0]
	v_mfma_scale_f32_16x16x128_f8f6f4 v[114:117], v[140:147], v[180:187], v[114:117], v208, v208 op_sel_hi:[0,0,0]
	v_mfma_scale_f32_16x16x128_f8f6f4 v[110:113], v[132:139], v[212:219], v[110:113], v208, v208 op_sel_hi:[0,0,0]
	v_mfma_scale_f32_16x16x128_f8f6f4 v[106:109], v[140:147], v[212:219], v[106:109], v208, v208 op_sel_hi:[0,0,0]
	v_mfma_scale_f32_16x16x128_f8f6f4 v[102:105], v[132:139], v[220:227], v[102:105], v208, v208 op_sel_hi:[0,0,0]
	v_mfma_scale_f32_16x16x128_f8f6f4 v[98:101], v[140:147], v[220:227], v[98:101], v208, v208 op_sel_hi:[0,0,0]
	v_mfma_scale_f32_16x16x128_f8f6f4 v[148:151], v[156:163], v[172:179], v[62:65], v208, v208 op_sel_hi:[0,0,0]
	v_mfma_scale_f32_16x16x128_f8f6f4 v[172:175], v[164:171], v[172:179], v[58:61], v208, v208 op_sel_hi:[0,0,0]
	v_mfma_scale_f32_16x16x128_f8f6f4 v[176:179], v[156:163], v[180:187], v[54:57], v208, v208 op_sel_hi:[0,0,0]
	v_mfma_scale_f32_16x16x128_f8f6f4 v[180:183], v[164:171], v[180:187], v[50:53], v208, v208 op_sel_hi:[0,0,0]
	v_mfma_scale_f32_16x16x128_f8f6f4 v[184:187], v[156:163], v[212:219], v[46:49], v208, v208 op_sel_hi:[0,0,0]
	v_mfma_scale_f32_16x16x128_f8f6f4 v[194:197], v[164:171], v[212:219], v[42:45], v208, v208 op_sel_hi:[0,0,0]
	v_mfma_scale_f32_16x16x128_f8f6f4 v[200:203], v[156:163], v[220:227], v[38:41], v208, v208 op_sel_hi:[0,0,0]
	v_mfma_scale_f32_16x16x128_f8f6f4 v[212:215], v[164:171], v[220:227], v[34:37], v208, v208 op_sel_hi:[0,0,0]
	s_barrier
	s_setprio 0
	s_mov_b32 m0, s15
	v_lshl_add_u64 v[152:153], s[10:11], 0, v[0:1]
	s_nop 2
	ds_read_b128 v[34:37], v192 offset:16384
	ds_read_b128 v[38:41], v193 offset:16384
	ds_read_b128 v[42:45], v192 offset:18432
	ds_read_b128 v[46:49], v193 offset:18432
	ds_read_b128 v[50:53], v192 offset:20480
	ds_read_b128 v[54:57], v193 offset:20480
	ds_read_b128 v[58:61], v192 offset:22528
	ds_read_b128 v[62:65], v193 offset:22528
	global_load_lds_dwordx4 v[152:153], off
	v_lshl_add_u64 v[188:189], v[152:153], 0, s[70:71]
	s_mov_b32 m0, s26
	s_nop 0
	global_load_lds_dwordx4 v[188:189], off
	v_lshl_add_u64 v[188:189], v[152:153], 0, s[42:43]
	s_mov_b32 m0, s39
	s_nop 0
	global_load_lds_dwordx4 v[188:189], off
	v_lshl_add_u64 v[188:189], v[152:153], 0, s[48:49]
	s_mov_b32 m0, s40
	s_nop 0
	global_load_lds_dwordx4 v[188:189], off
	v_lshl_add_u64 v[188:189], s[8:9], 0, v[0:1]
	s_mov_b32 m0, s41
	v_lshl_add_u64 v[204:205], v[188:189], 0, s[70:71]
	global_load_lds_dwordx4 v[188:189], off
	s_mov_b32 m0, s84
	s_nop 0
	global_load_lds_dwordx4 v[204:205], off
	.p2align 3
	s_waitcnt vmcnt(8)
	s_waitcnt lgkmcnt(0)
	s_setprio 1
	s_barrier
	v_mfma_scale_f32_16x16x128_f8f6f4 v[94:97], v[132:139], v[34:41], v[94:97], v208, v208 op_sel_hi:[0,0,0]
	v_mfma_scale_f32_16x16x128_f8f6f4 v[90:93], v[140:147], v[34:41], v[90:93], v208, v208 op_sel_hi:[0,0,0]
	v_mfma_scale_f32_16x16x128_f8f6f4 v[86:89], v[132:139], v[42:49], v[86:89], v208, v208 op_sel_hi:[0,0,0]
	v_mfma_scale_f32_16x16x128_f8f6f4 v[82:85], v[140:147], v[42:49], v[82:85], v208, v208 op_sel_hi:[0,0,0]
	v_mfma_scale_f32_16x16x128_f8f6f4 v[78:81], v[132:139], v[50:57], v[78:81], v208, v208 op_sel_hi:[0,0,0]
	v_mfma_scale_f32_16x16x128_f8f6f4 v[74:77], v[140:147], v[50:57], v[74:77], v208, v208 op_sel_hi:[0,0,0]
	v_mfma_scale_f32_16x16x128_f8f6f4 v[216:219], v[132:139], v[58:65], v[70:73], v208, v208 op_sel_hi:[0,0,0]
	v_mfma_scale_f32_16x16x128_f8f6f4 v[220:223], v[140:147], v[58:65], v[66:69], v208, v208 op_sel_hi:[0,0,0]
	v_mfma_scale_f32_16x16x128_f8f6f4 v[224:227], v[156:163], v[34:41], v[30:33], v208, v208 op_sel_hi:[0,0,0]
	v_mfma_scale_f32_16x16x128_f8f6f4 v[228:231], v[164:171], v[34:41], v[26:29], v208, v208 op_sel_hi:[0,0,0]
	v_mfma_scale_f32_16x16x128_f8f6f4 v[232:235], v[156:163], v[42:49], v[22:25], v208, v208 op_sel_hi:[0,0,0]
	v_mfma_scale_f32_16x16x128_f8f6f4 v[236:239], v[164:171], v[42:49], v[18:21], v208, v208 op_sel_hi:[0,0,0]
	v_mfma_scale_f32_16x16x128_f8f6f4 v[240:243], v[156:163], v[50:57], v[14:17], v208, v208 op_sel_hi:[0,0,0]
	v_mfma_scale_f32_16x16x128_f8f6f4 v[244:247], v[164:171], v[50:57], v[10:13], v208, v208 op_sel_hi:[0,0,0]
	v_mfma_scale_f32_16x16x128_f8f6f4 v[248:251], v[156:163], v[58:65], v[6:9], v208, v208 op_sel_hi:[0,0,0]
	v_mfma_scale_f32_16x16x128_f8f6f4 v[204:207], v[164:171], v[58:65], v[2:5], v208, v208 op_sel_hi:[0,0,0]
	s_barrier
; #define PG8_STAGE(bufoff, gbase, unused) do { _Pragma("unroll") for (int _i = 0; _i < 2; ++_i) \
;         __builtin_amdgcn_global_load_lds((const unsigned*)((const char*)(gbase) + voff + _i * 8192), (LAS unsigned*)(lds + (bufoff) + ldsw + _i * 8192), 16, 0, 0); } while (0)
; #define PG8_LDA(dst, b, h) do { _Pragma("unroll") for (int m = 0; m < 4; ++m) _Pragma("unroll") for (int k = 0; k < 2; ++k) dst[m][k] = *(const LAS bf16x8*)(lds + PG8_SA(b, h) + aoff + m * 2048 + (FP8 ? k * 16 : k * 1024)); } while (0)
; #define PG8_LDB(dst, b, h) do { _Pragma("unroll") for (int n = 0; n < 2; ++n) _Pragma("unroll") for (int k = 0; k < 2; ++k) dst[n][k] = *(const LAS bf16x8*)(lds + PG8_SB(b, h) + boff + n * 2048 + (FP8 ? k * 16 : k * 1024)); } while (0)
; #define PG8_WAIT_V(n) asm volatile("s_waitcnt vmcnt(" #n ")" ::: "memory")
; #define PG8_WAIT_L(n) asm volatile("s_waitcnt lgkmcnt(" #n ")" ::: "memory")
; #define PG8_BAR __builtin_amdgcn_s_barrier()
; #define PG8_SCHED __builtin_amdgcn_sched_barrier(0)
; template <class Epi, class Sched, bool ALIGN_EPI, bool SP2, int MODE  >
; __device__ __forceinline__ void gemm_phase(LAS unsigned char* lds, const Gemm g, const Sched S, const Epi E, unsigned long long& probe_acc, int epi_id, int wv) {
;     ...
;             PG8_LDB(B0, 1, 0); PG8_LDB(B1, 1, 1); PG8_SCHED; PG8_LDA(At, 1, 0); PG8_STAGE(PG8_SA(0, 1), a2 + hA, voffA);
;             PG8_WAIT_V(8); PG8_WAIT_L(0); PG8_BAR; PG8_MMA(0, 0, At, B0); PG8_MMA(0, 1, At, B1); PG8_BAR; PG8_SCHED;
;             PG8_LDA(At, 1, 1); PG8_STAGE(PG8_SB(1, 0), b3, voffB); PG8_STAGE(PG8_SB(1, 1), b3 + hB, voffB); PG8_STAGE(PG8_SA(1, 0), a3, voffA);
;             PG8_WAIT_V(8); PG8_WAIT_L(0); PG8_BAR; PG8_MMA(1, 0, At, B0); PG8_MMA(1, 1, At, B1); PG8_BAR; PG8_SCHED;
	s_setprio 0
	s_nop 1
	v_add_u32_e32 v14, s89, v191
	v_add_u32_e32 v18, s29, v191
	s_nop 0
	ds_read_b128 v[2:5], v14
	v_xor_b32_e32 v154, 16, v14
	ds_read_b128 v[6:9], v154
	ds_read_b128 v[10:13], v14 offset:2048
	ds_read_b128 v[14:17], v154 offset:2048
	ds_read_b128 v[132:135], v18
	v_xor_b32_e32 v154, 16, v18
	ds_read_b128 v[136:139], v154
	ds_read_b128 v[140:143], v18 offset:2048
	ds_read_b128 v[144:147], v154 offset:2048
	s_add_u32 s8, s8, s12
	s_addc_u32 s9, s9, 0
	s_mov_b32 m0, s85
	v_lshl_add_u64 v[42:43], s[8:9], 0, v[0:1]
	ds_read_b128 v[18:21], v192 offset:32768
	ds_read_b128 v[22:25], v193 offset:32768
	ds_read_b128 v[26:29], v192 offset:34816
	ds_read_b128 v[30:33], v193 offset:34816
	ds_read_b128 v[34:37], v192 offset:36864
	ds_read_b128 v[38:41], v193 offset:36864
	ds_read_b128 v[66:69], v192 offset:38912
	ds_read_b128 v[70:73], v193 offset:38912
	global_load_lds_dwordx4 v[42:43], off
	v_lshl_add_u64 v[42:43], v[42:43], 0, s[70:71]
	s_mov_b32 m0, s88
	s_nop 0
	global_load_lds_dwordx4 v[42:43], off
	.p2align 3
	s_waitcnt vmcnt(8)
	s_waitcnt lgkmcnt(0)
	s_setprio 1
	s_barrier
	v_mfma_scale_f32_16x16x128_f8f6f4 v[126:129], v[2:9], v[18:25], v[126:129], v208, v208 op_sel_hi:[0,0,0]
	v_mfma_scale_f32_16x16x128_f8f6f4 v[122:125], v[10:17], v[18:25], v[122:125], v208, v208 op_sel_hi:[0,0,0]
	v_mfma_scale_f32_16x16x128_f8f6f4 v[118:121], v[2:9], v[26:33], v[118:121], v208, v208 op_sel_hi:[0,0,0]
	v_mfma_scale_f32_16x16x128_f8f6f4 v[114:117], v[10:17], v[26:33], v[114:117], v208, v208 op_sel_hi:[0,0,0]
	v_mfma_scale_f32_16x16x128_f8f6f4 v[110:113], v[2:9], v[34:41], v[110:113], v208, v208 op_sel_hi:[0,0,0]
	v_mfma_scale_f32_16x16x128_f8f6f4 v[106:109], v[10:17], v[34:41], v[106:109], v208, v208 op_sel_hi:[0,0,0]
	v_mfma_scale_f32_16x16x128_f8f6f4 v[102:105], v[2:9], v[66:73], v[102:105], v208, v208 op_sel_hi:[0,0,0]
	v_mfma_scale_f32_16x16x128_f8f6f4 v[98:101], v[10:17], v[66:73], v[98:101], v208, v208 op_sel_hi:[0,0,0]
	v_mfma_scale_f32_16x16x128_f8f6f4 v[62:65], v[132:139], v[18:25], v[148:151], v208, v208 op_sel_hi:[0,0,0]
	v_mfma_scale_f32_16x16x128_f8f6f4 v[58:61], v[140:147], v[18:25], v[172:175], v208, v208 op_sel_hi:[0,0,0]
	v_mfma_scale_f32_16x16x128_f8f6f4 v[54:57], v[132:139], v[26:33], v[176:179], v208, v208 op_sel_hi:[0,0,0]
	v_mfma_scale_f32_16x16x128_f8f6f4 v[50:53], v[140:147], v[26:33], v[180:183], v208, v208 op_sel_hi:[0,0,0]
	v_mfma_scale_f32_16x16x128_f8f6f4 v[46:49], v[132:139], v[34:41], v[184:187], v208, v208 op_sel_hi:[0,0,0]
	v_mfma_scale_f32_16x16x128_f8f6f4 v[42:45], v[140:147], v[34:41], v[194:197], v208, v208 op_sel_hi:[0,0,0]
	v_mfma_scale_f32_16x16x128_f8f6f4 v[38:41], v[132:139], v[66:73], v[200:203], v208, v208 op_sel_hi:[0,0,0]
	v_mfma_scale_f32_16x16x128_f8f6f4 v[34:37], v[140:147], v[66:73], v[212:215], v208, v208 op_sel_hi:[0,0,0]
	s_barrier
	s_setprio 0
	s_mov_b32 m0, s92
	v_lshl_add_u64 v[26:27], v[152:153], 0, s[76:77]
	ds_read_b128 v[18:21], v192 offset:49152
	ds_read_b128 v[22:25], v193 offset:49152
	ds_read_b128 v[156:159], v192 offset:51200
	ds_read_b128 v[160:163], v193 offset:51200
	ds_read_b128 v[164:167], v192 offset:53248
	ds_read_b128 v[168:171], v193 offset:53248
	ds_read_b128 v[172:175], v192 offset:55296
	ds_read_b128 v[176:179], v193 offset:55296
	global_load_lds_dwordx4 v[26:27], off
	v_lshl_add_u64 v[26:27], v[152:153], 0, s[78:79]
	s_mov_b32 m0, s93
	s_nop 0
	global_load_lds_dwordx4 v[26:27], off
	v_lshl_add_u64 v[26:27], v[152:153], 0, s[44:45]
	s_mov_b32 m0, s0
	s_nop 0
	global_load_lds_dwordx4 v[26:27], off
	v_lshl_add_u64 v[26:27], v[152:153], 0, s[56:57]
	s_mov_b32 m0, s1
	s_nop 0
	global_load_lds_dwordx4 v[26:27], off
	v_lshl_add_u64 v[26:27], v[188:189], 0, s[76:77]
	s_mov_b32 m0, s94
	s_nop 0
	global_load_lds_dwordx4 v[26:27], off
	v_lshl_add_u64 v[26:27], v[188:189], 0, s[78:79]
	s_mov_b32 m0, s95
	s_nop 0
	global_load_lds_dwordx4 v[26:27], off
	.p2align 3
	s_waitcnt vmcnt(8)
	s_waitcnt lgkmcnt(0)
	s_setprio 1
	s_barrier
	v_mfma_scale_f32_16x16x128_f8f6f4 v[94:97], v[2:9], v[18:25], v[94:97], v208, v208 op_sel_hi:[0,0,0]
	v_mfma_scale_f32_16x16x128_f8f6f4 v[90:93], v[10:17], v[18:25], v[90:93], v208, v208 op_sel_hi:[0,0,0]
	v_mfma_scale_f32_16x16x128_f8f6f4 v[86:89], v[2:9], v[156:163], v[86:89], v208, v208 op_sel_hi:[0,0,0]
	v_mfma_scale_f32_16x16x128_f8f6f4 v[82:85], v[10:17], v[156:163], v[82:85], v208, v208 op_sel_hi:[0,0,0]
	v_mfma_scale_f32_16x16x128_f8f6f4 v[78:81], v[2:9], v[164:171], v[78:81], v208, v208 op_sel_hi:[0,0,0]
	v_mfma_scale_f32_16x16x128_f8f6f4 v[74:77], v[10:17], v[164:171], v[74:77], v208, v208 op_sel_hi:[0,0,0]
	v_mfma_scale_f32_16x16x128_f8f6f4 v[70:73], v[2:9], v[172:179], v[216:219], v208, v208 op_sel_hi:[0,0,0]
	v_mfma_scale_f32_16x16x128_f8f6f4 v[66:69], v[10:17], v[172:179], v[220:223], v208, v208 op_sel_hi:[0,0,0]
	v_mfma_scale_f32_16x16x128_f8f6f4 v[30:33], v[132:139], v[18:25], v[224:227], v208, v208 op_sel_hi:[0,0,0]
	v_mfma_scale_f32_16x16x128_f8f6f4 v[26:29], v[140:147], v[18:25], v[228:231], v208, v208 op_sel_hi:[0,0,0]
	v_mfma_scale_f32_16x16x128_f8f6f4 v[22:25], v[132:139], v[156:163], v[232:235], v208, v208 op_sel_hi:[0,0,0]
	v_mfma_scale_f32_16x16x128_f8f6f4 v[18:21], v[140:147], v[156:163], v[236:239], v208, v208 op_sel_hi:[0,0,0]
	v_mfma_scale_f32_16x16x128_f8f6f4 v[14:17], v[132:139], v[164:171], v[240:243], v208, v208 op_sel_hi:[0,0,0]
	v_mfma_scale_f32_16x16x128_f8f6f4 v[10:13], v[140:147], v[164:171], v[244:247], v208, v208 op_sel_hi:[0,0,0]
	v_mfma_scale_f32_16x16x128_f8f6f4 v[6:9], v[132:139], v[172:179], v[248:251], v208, v208 op_sel_hi:[0,0,0]
	v_mfma_scale_f32_16x16x128_f8f6f4 v[2:5], v[140:147], v[172:179], v[204:207], v208, v208 op_sel_hi:[0,0,0]
	s_barrier
	s_setprio 0
	s_add_i32 s46, s46, 2
	s_add_u32 s6, s6, 0x8000
	s_addc_u32 s7, s7, 0
	s_cmp_gt_u32 s46, 41
	s_cbranch_scc0 .LBB0_914
	v_readlane_b32 s4, v255, 1
	v_readlane_b32 s5, v255, 2
	s_and_b64 vcc, exec, s[4:5]
	s_cbranch_vccz .LBB0_917
	s_barrier

;     __device__ __forceinline__ bool next(int i, Unit& u) const { const int off = i * H + (r >> 1); if (off >= 8 * nN) return false; u.pm = 16 * g + 8 * (r & 1) + (off & 7); u.pn = off >> 3; return true; }
; #define PG8_STAGE(bufoff, gbase, unused) do { _Pragma("unroll") for (int _i = 0; _i < 2; ++_i) \
;         __builtin_amdgcn_global_load_lds((const unsigned*)((const char*)(gbase) + voff + _i * 8192), (LAS unsigned*)(lds + (bufoff) + ldsw + _i * 8192), 16, 0, 0); } while (0)
; #define PG8_LDA(dst, b, h) do { _Pragma("unroll") for (int m = 0; m < 4; ++m) _Pragma("unroll") for (int k = 0; k < 2; ++k) dst[m][k] = *(const LAS bf16x8*)(lds + PG8_SA(b, h) + aoff + m * 2048 + (FP8 ? k * 16 : k * 1024)); } while (0)
; #define PG8_LDB(dst, b, h) do { _Pragma("unroll") for (int n = 0; n < 2; ++n) _Pragma("unroll") for (int k = 0; k < 2; ++k) dst[n][k] = *(const LAS bf16x8*)(lds + PG8_SB(b, h) + boff + n * 2048 + (FP8 ? k * 16 : k * 1024)); } while (0)
; #define PG8_BAR __builtin_amdgcn_s_barrier()
; template <class Epi, class Sched, bool ALIGN_EPI, bool SP2, int MODE  >
; __device__ __forceinline__ void gemm_phase(LAS unsigned char* lds, const Gemm g, const Sched S, const Epi E, unsigned long long& probe_acc, int epi_id, int wv) {
;     ...
;         const bool has_next = S.next(ui + 1, nxt);
;         const char* nA = has_next ? (const char*)g.A + (size_t)nxt.pm * tA + (g.gt ? (size_t)(nxt.pn / g.gt) * gK2 : 0) : cA; const char* nB = has_next ? (const char*)g.Bt + (size_t)nxt.pn * tB : cB;
;         for (int t = 0; t < nt; t += 2) {
;             const bool last = (t == nt - 2);
;             const char* a1 = cA + (size_t)(t + 1) * kstep;
;             const char* a2 = last ? nA : cA + (size_t)(t + 2) * kstep; const char* b2 = last ? nB : cB + (size_t)(t + 2) * kstep;
;             const char* a3 = a2 + kstep; const char* b3 = b2 + kstep;
;             if constexpr (SP2) {
;             PG8_LDB(B0, 0, 0); PG8_LDB(B1, 0, 1); PG8_SCHED; PG8_LDA(At, 0, 0); PG8_STAGE(PG8_SA(1, 1), a1 + hA, voffA);
;             PG8_WAIT_V(8); PG8_WAIT_L(0); PG8_BAR; PG8_MMA(0, 0, At, B0); PG8_MMA(0, 1, At, B1); PG8_BAR; PG8_SCHED;
;             PG8_LDA(At, 0, 1); PG8_STAGE(PG8_SB(0, 0), b2, voffB); PG8_STAGE(PG8_SB(0, 1), b2 + hB, voffB); PG8_STAGE(PG8_SA(0, 0), a2, voffA);
;             PG8_WAIT_V(8); PG8_WAIT_L(0); PG8_BAR; PG8_MMA(1, 0, At, B0); PG8_MMA(1, 1, At, B1); PG8_BAR; PG8_SCHED;
.LBB0_1153:
	s_add_u32 s8, s4, s40
	s_addc_u32 s9, s5, 0
	s_add_u32 s10, s6, 0x8000
	s_waitcnt vmcnt(0)
	v_lshl_add_u64 v[130:131], s[8:9], 0, v[0:1]
	s_addc_u32 s11, s7, 0
	s_mov_b32 s34, -2
	s_mov_b64 s[6:7], 0
	s_waitcnt lgkmcnt(0)
	s_mov_b64 s[42:43], 0xb0000
	v_add_u32_e32 v144, s90, v200
	v_add_u32_e32 v160, s15, v200
	s_add_u32 s8, s4, s6
	ds_read_b128 v[132:135], v144
	ds_read_b128 v[136:139], v144 offset:1024
	ds_read_b128 v[140:143], v144 offset:2048
	ds_read_b128 v[144:147], v144 offset:3072
	ds_read_b128 v[148:151], v160
	ds_read_b128 v[152:155], v160 offset:1024
	ds_read_b128 v[156:159], v160 offset:2048
	ds_read_b128 v[164:167], v160 offset:3072
	s_addc_u32 s9, s5, s7
	s_add_u32 s8, s8, 0x8000
	s_addc_u32 s9, s9, 0
	s_add_u32 s28, s10, s6
	s_addc_u32 s29, s11, s7
	s_cmp_eq_u32 s6, 0xa8000
	s_cselect_b32 s9, s67, s9
	s_cselect_b32 s8, s66, s8
	s_cselect_b32 vcc_hi, s87, s29
	s_cselect_b32 vcc_lo, s86, s28
	v_lshl_add_u64 v[160:161], v[130:131], 0, s[6:7]
	v_lshl_add_u64 v[196:197], v[160:161], 0, s[76:77]
	s_add_i32 m0, s0, 0xc000
	ds_read_b128 v[168:171], v201
	ds_read_b128 v[172:175], v201 offset:1024
	ds_read_b128 v[176:179], v201 offset:2048
	ds_read_b128 v[180:183], v201 offset:3072
	ds_read_b128 v[184:187], v201 offset:4096
	ds_read_b128 v[188:191], v201 offset:5120
	ds_read_b128 v[192:195], v201 offset:6144
	ds_read_b128 v[212:215], v201 offset:7168
	global_load_lds_dwordx4 v[196:197], off
	v_lshl_add_u64 v[160:161], v[160:161], 0, s[78:79]
	s_add_i32 m0, s0, 0xe000
	s_nop 0
	global_load_lds_dwordx4 v[160:161], off
	.p2align 3
	s_waitcnt vmcnt(8)
	s_waitcnt lgkmcnt(0)
	s_setprio 1
	s_barrier
	v_mfma_i32_16x16x64_i8 v[122:125], v[132:135], v[168:171], 0
	v_mfma_i32_16x16x64_i8 v[126:129], v[140:143], v[168:171], 0
	v_mfma_i32_16x16x64_i8 v[114:117], v[132:135], v[176:179], 0
	v_mfma_i32_16x16x64_i8 v[118:121], v[140:143], v[176:179], 0
	v_mfma_i32_16x16x64_i8 v[106:109], v[132:135], v[184:187], 0
	v_mfma_i32_16x16x64_i8 v[110:113], v[140:143], v[184:187], 0
	v_mfma_i32_16x16x64_i8 v[98:101], v[132:135], v[192:195], 0
	v_mfma_i32_16x16x64_i8 v[102:105], v[140:143], v[192:195], 0
	v_mfma_i32_16x16x64_i8 v[122:125], v[136:139], v[172:175], v[122:125]
	v_mfma_i32_16x16x64_i8 v[126:129], v[144:147], v[172:175], v[126:129]
	v_mfma_i32_16x16x64_i8 v[114:117], v[136:139], v[180:183], v[114:117]
	v_mfma_i32_16x16x64_i8 v[118:121], v[144:147], v[180:183], v[118:121]
	v_mfma_i32_16x16x64_i8 v[106:109], v[136:139], v[188:191], v[106:109]
	v_mfma_i32_16x16x64_i8 v[110:113], v[144:147], v[188:191], v[110:113]
	v_mfma_i32_16x16x64_i8 v[98:101], v[136:139], v[212:215], v[98:101]
	v_mfma_i32_16x16x64_i8 v[102:105], v[144:147], v[212:215], v[102:105]
	v_mfma_i32_16x16x64_i8 v[58:61], v[148:151], v[168:171], 0
	v_mfma_i32_16x16x64_i8 v[62:65], v[156:159], v[168:171], 0
	v_mfma_i32_16x16x64_i8 v[50:53], v[148:151], v[176:179], 0
	v_mfma_i32_16x16x64_i8 v[54:57], v[156:159], v[176:179], 0
	v_mfma_i32_16x16x64_i8 v[42:45], v[148:151], v[184:187], 0
	v_mfma_i32_16x16x64_i8 v[46:49], v[156:159], v[184:187], 0
	v_mfma_i32_16x16x64_i8 v[34:37], v[148:151], v[192:195], 0
	v_mfma_i32_16x16x64_i8 v[38:41], v[156:159], v[192:195], 0
	v_mfma_i32_16x16x64_i8 v[58:61], v[152:155], v[172:175], v[58:61]
	v_mfma_i32_16x16x64_i8 v[62:65], v[164:167], v[172:175], v[62:65]
	v_mfma_i32_16x16x64_i8 v[50:53], v[152:155], v[180:183], v[50:53]
	v_mfma_i32_16x16x64_i8 v[54:57], v[164:167], v[180:183], v[54:57]
	v_mfma_i32_16x16x64_i8 v[42:45], v[152:155], v[188:191], v[42:45]
	v_mfma_i32_16x16x64_i8 v[46:49], v[164:167], v[188:191], v[46:49]
	v_mfma_i32_16x16x64_i8 v[34:37], v[152:155], v[212:215], v[34:37]
	v_mfma_i32_16x16x64_i8 v[38:41], v[164:167], v[212:215], v[38:41]
	s_barrier
	s_setprio 0
	s_mov_b32 m0, s91
	v_lshl_add_u64 v[160:161], vcc, 0, v[0:1]
	ds_read_b128 v[168:171], v201 offset:16384
	ds_read_b128 v[172:175], v201 offset:17408
	ds_read_b128 v[176:179], v201 offset:18432
	ds_read_b128 v[180:183], v201 offset:19456
	ds_read_b128 v[184:187], v201 offset:20480
	ds_read_b128 v[188:191], v201 offset:21504
	ds_read_b128 v[192:195], v201 offset:22528
	ds_read_b128 v[212:215], v201 offset:23552
	global_load_lds_dwordx4 v[160:161], off
	v_lshl_add_u64 v[196:197], v[160:161], 0, s[70:71]
	s_mov_b32 m0, s14
	s_nop 0
	global_load_lds_dwordx4 v[196:197], off
	v_lshl_add_u64 v[196:197], v[160:161], 0, s[42:43]
	s_mov_b32 m0, s26
	s_nop 0
	global_load_lds_dwordx4 v[196:197], off
	v_lshl_add_u64 v[196:197], v[160:161], 0, s[48:49]
	s_mov_b32 m0, s27
	s_nop 0
	global_load_lds_dwordx4 v[196:197], off
	v_lshl_add_u64 v[196:197], s[8:9], 0, v[0:1]
	s_mov_b32 m0, s0
	v_lshl_add_u64 v[202:203], v[196:197], 0, s[70:71]
	global_load_lds_dwordx4 v[196:197], off
	s_mov_b32 m0, s1
	s_nop 0
	global_load_lds_dwordx4 v[202:203], off
	.p2align 3
	s_waitcnt vmcnt(8)
	s_waitcnt lgkmcnt(0)
	s_setprio 1
	s_barrier
; #define PG8_STAGE(bufoff, gbase, unused) do { _Pragma("unroll") for (int _i = 0; _i < 2; ++_i) \
;         __builtin_amdgcn_global_load_lds((const unsigned*)((const char*)(gbase) + voff + _i * 8192), (LAS unsigned*)(lds + (bufoff) + ldsw + _i * 8192), 16, 0, 0); } while (0)
; #define PG8_LDA(dst, b, h) do { _Pragma("unroll") for (int m = 0; m < 4; ++m) _Pragma("unroll") for (int k = 0; k < 2; ++k) dst[m][k] = *(const LAS bf16x8*)(lds + PG8_SA(b, h) + aoff + m * 2048 + (FP8 ? k * 16 : k * 1024)); } while (0)
; #define PG8_LDB(dst, b, h) do { _Pragma("unroll") for (int n = 0; n < 2; ++n) _Pragma("unroll") for (int k = 0; k < 2; ++k) dst[n][k] = *(const LAS bf16x8*)(lds + PG8_SB(b, h) + boff + n * 2048 + (FP8 ? k * 16 : k * 1024)); } while (0)
; #define PG8_WAIT_V(n) asm volatile("s_waitcnt vmcnt(" #n ")" ::: "memory")
; #define PG8_WAIT_L(n) asm volatile("s_waitcnt lgkmcnt(" #n ")" ::: "memory")
; #define PG8_BAR __builtin_amdgcn_s_barrier()
; #define PG8_SCHED __builtin_amdgcn_sched_barrier(0)
; template <class Epi, class Sched, bool ALIGN_EPI, bool SP2, int MODE  >
; __device__ __forceinline__ void gemm_phase(LAS unsigned char* lds, const Gemm g, const Sched S, const Epi E, unsigned long long& probe_acc, int epi_id, int wv) {
;     ...
;             PG8_WAIT_V(8); PG8_WAIT_L(0); PG8_BAR; PG8_MMA(0, 0, At, B0); PG8_MMA(0, 1, At, B1); PG8_BAR; PG8_SCHED;
;             PG8_LDA(At, 0, 1); PG8_STAGE(PG8_SB(0, 0), b2, voffB); PG8_STAGE(PG8_SB(0, 1), b2 + hB, voffB); PG8_STAGE(PG8_SA(0, 0), a2, voffA);
;             PG8_WAIT_V(8); PG8_WAIT_L(0); PG8_BAR; PG8_MMA(1, 0, At, B0); PG8_MMA(1, 1, At, B1); PG8_BAR; PG8_SCHED;
;             PG8_LDB(B0, 1, 0); PG8_LDB(B1, 1, 1); PG8_SCHED; PG8_LDA(At, 1, 0); PG8_STAGE(PG8_SA(0, 1), a2 + hA, voffA);
;             PG8_WAIT_V(8); PG8_WAIT_L(0); PG8_BAR; PG8_MMA(0, 0, At, B0); PG8_MMA(0, 1, At, B1); PG8_BAR; PG8_SCHED;
	v_mfma_i32_16x16x64_i8 v[90:93], v[132:135], v[168:171], 0
	v_mfma_i32_16x16x64_i8 v[94:97], v[140:143], v[168:171], 0
	v_mfma_i32_16x16x64_i8 v[82:85], v[132:135], v[176:179], 0
	v_mfma_i32_16x16x64_i8 v[86:89], v[140:143], v[176:179], 0
	v_mfma_i32_16x16x64_i8 v[74:77], v[132:135], v[184:187], 0
	v_mfma_i32_16x16x64_i8 v[78:81], v[140:143], v[184:187], 0
	v_mfma_i32_16x16x64_i8 v[66:69], v[132:135], v[192:195], 0
	v_mfma_i32_16x16x64_i8 v[70:73], v[140:143], v[192:195], 0
	v_mfma_i32_16x16x64_i8 v[90:93], v[136:139], v[172:175], v[90:93]
	v_mfma_i32_16x16x64_i8 v[94:97], v[144:147], v[172:175], v[94:97]
	v_mfma_i32_16x16x64_i8 v[82:85], v[136:139], v[180:183], v[82:85]
	v_mfma_i32_16x16x64_i8 v[86:89], v[144:147], v[180:183], v[86:89]
	v_mfma_i32_16x16x64_i8 v[74:77], v[136:139], v[188:191], v[74:77]
	v_mfma_i32_16x16x64_i8 v[78:81], v[144:147], v[188:191], v[78:81]
	v_mfma_i32_16x16x64_i8 v[66:69], v[136:139], v[212:215], v[66:69]
	v_mfma_i32_16x16x64_i8 v[70:73], v[144:147], v[212:215], v[70:73]
	v_mfma_i32_16x16x64_i8 v[26:29], v[148:151], v[168:171], 0
	v_mfma_i32_16x16x64_i8 v[30:33], v[156:159], v[168:171], 0
	v_mfma_i32_16x16x64_i8 v[18:21], v[148:151], v[176:179], 0
	v_mfma_i32_16x16x64_i8 v[22:25], v[156:159], v[176:179], 0
	v_mfma_i32_16x16x64_i8 v[10:13], v[148:151], v[184:187], 0
	v_mfma_i32_16x16x64_i8 v[14:17], v[156:159], v[184:187], 0
	v_mfma_i32_16x16x64_i8 v[2:5], v[148:151], v[192:195], 0
	v_mfma_i32_16x16x64_i8 v[6:9], v[156:159], v[192:195], 0
	v_mfma_i32_16x16x64_i8 v[26:29], v[152:155], v[172:175], v[26:29]
	v_mfma_i32_16x16x64_i8 v[30:33], v[164:167], v[172:175], v[30:33]
	v_mfma_i32_16x16x64_i8 v[18:21], v[152:155], v[180:183], v[18:21]
	v_mfma_i32_16x16x64_i8 v[22:25], v[164:167], v[180:183], v[22:25]
	v_mfma_i32_16x16x64_i8 v[10:13], v[152:155], v[188:191], v[10:13]
	v_mfma_i32_16x16x64_i8 v[14:17], v[164:167], v[188:191], v[14:17]
	v_mfma_i32_16x16x64_i8 v[2:5], v[152:155], v[212:215], v[2:5]
	v_mfma_i32_16x16x64_i8 v[6:9], v[164:167], v[212:215], v[6:9]
	s_barrier
	s_setprio 0
	v_add_u32_e32 v144, s88, v200
	v_add_u32_e32 v162, s95, v200
	ds_read_b128 v[132:135], v144
	ds_read_b128 v[136:139], v144 offset:1024
	ds_read_b128 v[140:143], v144 offset:2048
	ds_read_b128 v[144:147], v144 offset:3072
	ds_read_b128 v[148:151], v162
	ds_read_b128 v[152:155], v162 offset:1024
	ds_read_b128 v[156:159], v162 offset:2048
	ds_read_b128 v[164:167], v162 offset:3072
	s_add_u32 s8, s8, s40
	s_addc_u32 s9, s9, 0
	s_mov_b32 m0, s36
	v_lshl_add_u64 v[202:203], s[8:9], 0, v[0:1]
	ds_read_b128 v[168:171], v201 offset:32768
	ds_read_b128 v[172:175], v201 offset:33792
	ds_read_b128 v[176:179], v201 offset:34816
	ds_read_b128 v[180:183], v201 offset:35840
	ds_read_b128 v[184:187], v201 offset:36864
	ds_read_b128 v[188:191], v201 offset:37888
	ds_read_b128 v[192:195], v201 offset:38912
	ds_read_b128 v[212:215], v201 offset:39936
	global_load_lds_dwordx4 v[202:203], off
	v_lshl_add_u64 v[202:203], v[202:203], 0, s[70:71]
	s_mov_b32 m0, s37
	s_nop 0
	global_load_lds_dwordx4 v[202:203], off
	.p2align 3
	s_waitcnt vmcnt(8)
	s_waitcnt lgkmcnt(0)
	s_setprio 1
	s_barrier
	v_mfma_i32_16x16x64_i8 v[122:125], v[132:135], v[168:171], v[122:125]
	v_mfma_i32_16x16x64_i8 v[126:129], v[140:143], v[168:171], v[126:129]
	v_mfma_i32_16x16x64_i8 v[114:117], v[132:135], v[176:179], v[114:117]
	v_mfma_i32_16x16x64_i8 v[118:121], v[140:143], v[176:179], v[118:121]
	v_mfma_i32_16x16x64_i8 v[106:109], v[132:135], v[184:187], v[106:109]
	v_mfma_i32_16x16x64_i8 v[110:113], v[140:143], v[184:187], v[110:113]
	v_mfma_i32_16x16x64_i8 v[98:101], v[132:135], v[192:195], v[98:101]
	v_mfma_i32_16x16x64_i8 v[102:105], v[140:143], v[192:195], v[102:105]
	v_mfma_i32_16x16x64_i8 v[122:125], v[136:139], v[172:175], v[122:125]
	v_mfma_i32_16x16x64_i8 v[126:129], v[144:147], v[172:175], v[126:129]
	v_mfma_i32_16x16x64_i8 v[114:117], v[136:139], v[180:183], v[114:117]
	v_mfma_i32_16x16x64_i8 v[118:121], v[144:147], v[180:183], v[118:121]
	v_mfma_i32_16x16x64_i8 v[106:109], v[136:139], v[188:191], v[106:109]
	v_mfma_i32_16x16x64_i8 v[110:113], v[144:147], v[188:191], v[110:113]
	v_mfma_i32_16x16x64_i8 v[98:101], v[136:139], v[212:215], v[98:101]
	v_mfma_i32_16x16x64_i8 v[102:105], v[144:147], v[212:215], v[102:105]
	v_mfma_i32_16x16x64_i8 v[58:61], v[148:151], v[168:171], v[58:61]
	v_mfma_i32_16x16x64_i8 v[62:65], v[156:159], v[168:171], v[62:65]
	v_mfma_i32_16x16x64_i8 v[50:53], v[148:151], v[176:179], v[50:53]
	v_mfma_i32_16x16x64_i8 v[54:57], v[156:159], v[176:179], v[54:57]
	v_mfma_i32_16x16x64_i8 v[42:45], v[148:151], v[184:187], v[42:45]
	v_mfma_i32_16x16x64_i8 v[46:49], v[156:159], v[184:187], v[46:49]
	v_mfma_i32_16x16x64_i8 v[34:37], v[148:151], v[192:195], v[34:37]
	v_mfma_i32_16x16x64_i8 v[38:41], v[156:159], v[192:195], v[38:41]
	v_mfma_i32_16x16x64_i8 v[58:61], v[152:155], v[172:175], v[58:61]
	v_mfma_i32_16x16x64_i8 v[62:65], v[164:167], v[172:175], v[62:65]
	v_mfma_i32_16x16x64_i8 v[50:53], v[152:155], v[180:183], v[50:53]
	v_mfma_i32_16x16x64_i8 v[54:57], v[164:167], v[180:183], v[54:57]
	v_mfma_i32_16x16x64_i8 v[42:45], v[152:155], v[188:191], v[42:45]
	v_mfma_i32_16x16x64_i8 v[46:49], v[164:167], v[188:191], v[46:49]
	v_mfma_i32_16x16x64_i8 v[34:37], v[152:155], v[212:215], v[34:37]
	v_mfma_i32_16x16x64_i8 v[38:41], v[164:167], v[212:215], v[38:41]
	s_barrier
; #define PG8_STAGE(bufoff, gbase, unused) do { _Pragma("unroll") for (int _i = 0; _i < 2; ++_i) \
;         __builtin_amdgcn_global_load_lds((const unsigned*)((const char*)(gbase) + voff + _i * 8192), (LAS unsigned*)(lds + (bufoff) + ldsw + _i * 8192), 16, 0, 0); } while (0)
; #define PG8_LDA(dst, b, h) do { _Pragma("unroll") for (int m = 0; m < 4; ++m) _Pragma("unroll") for (int k = 0; k < 2; ++k) dst[m][k] = *(const LAS bf16x8*)(lds + PG8_SA(b, h) + aoff + m * 2048 + (FP8 ? k * 16 : k * 1024)); } while (0)
; #define PG8_LDB(dst, b, h) do { _Pragma("unroll") for (int n = 0; n < 2; ++n) _Pragma("unroll") for (int k = 0; k < 2; ++k) dst[n][k] = *(const LAS bf16x8*)(lds + PG8_SB(b, h) + boff + n * 2048 + (FP8 ? k * 16 : k * 1024)); } while (0)
; template <class Epi, class Sched, bool ALIGN_EPI, bool SP2, int MODE  >
; __device__ __forceinline__ void gemm_phase(LAS unsigned char* lds, const Gemm g, const Sched S, const Epi E, unsigned long long& probe_acc, int epi_id, int wv) {
;     ...
;         for (int t = 0; t < nt; t += 2) {
;             const bool last = (t == nt - 2);
;             const char* a1 = cA + (size_t)(t + 1) * kstep;
;             const char* a2 = last ? nA : cA + (size_t)(t + 2) * kstep; const char* b2 = last ? nB : cB + (size_t)(t + 2) * kstep;
;             const char* a3 = a2 + kstep; const char* b3 = b2 + kstep;
;             if constexpr (SP2) {
;             PG8_LDB(B0, 0, 0); PG8_LDB(B1, 0, 1); PG8_SCHED; PG8_LDA(At, 0, 0); PG8_STAGE(PG8_SA(1, 1), a1 + hA, voffA);
;             PG8_WAIT_V(8); PG8_WAIT_L(0); PG8_BAR; PG8_MMA(0, 0, At, B0); PG8_MMA(0, 1, At, B1); PG8_BAR; PG8_SCHED;
;             PG8_LDA(At, 0, 1); PG8_STAGE(PG8_SB(0, 0), b2, voffB); PG8_STAGE(PG8_SB(0, 1), b2 + hB, voffB); PG8_STAGE(PG8_SA(0, 0), a2, voffA);
;             PG8_WAIT_V(8); PG8_WAIT_L(0); PG8_BAR; PG8_MMA(1, 0, At, B0); PG8_MMA(1, 1, At, B1); PG8_BAR; PG8_SCHED;
;             PG8_LDB(B0, 1, 0); PG8_LDB(B1, 1, 1); PG8_SCHED; PG8_LDA(At, 1, 0); PG8_STAGE(PG8_SA(0, 1), a2 + hA, voffA);
;             PG8_WAIT_V(8); PG8_WAIT_L(0); PG8_BAR; PG8_MMA(0, 0, At, B0); PG8_MMA(0, 1, At, B1); PG8_BAR; PG8_SCHED;
;             PG8_LDA(At, 1, 1); PG8_STAGE(PG8_SB(1, 0), b3, voffB); PG8_STAGE(PG8_SB(1, 1), b3 + hB, voffB); PG8_STAGE(PG8_SA(1, 0), a3, voffA);
;             PG8_WAIT_V(8); PG8_WAIT_L(0); PG8_BAR; PG8_MMA(1, 0, At, B0); PG8_MMA(1, 1, At, B1); PG8_BAR; PG8_SCHED;
	s_setprio 0
	s_mov_b32 m0, s89
	v_lshl_add_u64 v[202:203], v[160:161], 0, s[76:77]
	ds_read_b128 v[168:171], v201 offset:49152
	ds_read_b128 v[172:175], v201 offset:50176
	ds_read_b128 v[176:179], v201 offset:51200
	ds_read_b128 v[180:183], v201 offset:52224
	ds_read_b128 v[184:187], v201 offset:53248
	ds_read_b128 v[188:191], v201 offset:54272
	ds_read_b128 v[192:195], v201 offset:55296
	ds_read_b128 v[212:215], v201 offset:56320
	global_load_lds_dwordx4 v[202:203], off
	v_lshl_add_u64 v[202:203], v[160:161], 0, s[78:79]
	s_mov_b32 m0, s92
	s_nop 0
	global_load_lds_dwordx4 v[202:203], off
	v_lshl_add_u64 v[202:203], v[160:161], 0, s[44:45]
	s_mov_b32 m0, s84
	v_lshl_add_u64 v[160:161], v[160:161], 0, s[56:57]
	global_load_lds_dwordx4 v[202:203], off
	s_mov_b32 m0, s12
	s_nop 0
	global_load_lds_dwordx4 v[160:161], off
	v_lshl_add_u64 v[160:161], v[196:197], 0, s[76:77]
	s_mov_b32 m0, s93
	s_nop 0
	global_load_lds_dwordx4 v[160:161], off
	v_lshl_add_u64 v[160:161], v[196:197], 0, s[78:79]
	s_mov_b32 m0, s94
	s_nop 0
	global_load_lds_dwordx4 v[160:161], off
	.p2align 3
	s_waitcnt vmcnt(8)
	s_waitcnt lgkmcnt(0)
	s_setprio 1
	s_barrier
	v_mfma_i32_16x16x64_i8 v[90:93], v[132:135], v[168:171], v[90:93]
	v_mfma_i32_16x16x64_i8 v[94:97], v[140:143], v[168:171], v[94:97]
	v_mfma_i32_16x16x64_i8 v[82:85], v[132:135], v[176:179], v[82:85]
	v_mfma_i32_16x16x64_i8 v[86:89], v[140:143], v[176:179], v[86:89]
	v_mfma_i32_16x16x64_i8 v[74:77], v[132:135], v[184:187], v[74:77]
	v_mfma_i32_16x16x64_i8 v[78:81], v[140:143], v[184:187], v[78:81]
	v_mfma_i32_16x16x64_i8 v[66:69], v[132:135], v[192:195], v[66:69]
	v_mfma_i32_16x16x64_i8 v[70:73], v[140:143], v[192:195], v[70:73]
	v_mfma_i32_16x16x64_i8 v[90:93], v[136:139], v[172:175], v[90:93]
	v_mfma_i32_16x16x64_i8 v[94:97], v[144:147], v[172:175], v[94:97]
	v_mfma_i32_16x16x64_i8 v[82:85], v[136:139], v[180:183], v[82:85]
	v_mfma_i32_16x16x64_i8 v[86:89], v[144:147], v[180:183], v[86:89]
	v_mfma_i32_16x16x64_i8 v[74:77], v[136:139], v[188:191], v[74:77]
	v_mfma_i32_16x16x64_i8 v[78:81], v[144:147], v[188:191], v[78:81]
	v_mfma_i32_16x16x64_i8 v[66:69], v[136:139], v[212:215], v[66:69]
	v_mfma_i32_16x16x64_i8 v[70:73], v[144:147], v[212:215], v[70:73]
	v_mfma_i32_16x16x64_i8 v[26:29], v[148:151], v[168:171], v[26:29]
	v_mfma_i32_16x16x64_i8 v[30:33], v[156:159], v[168:171], v[30:33]
	v_mfma_i32_16x16x64_i8 v[18:21], v[148:151], v[176:179], v[18:21]
	v_mfma_i32_16x16x64_i8 v[22:25], v[156:159], v[176:179], v[22:25]
	v_mfma_i32_16x16x64_i8 v[10:13], v[148:151], v[184:187], v[10:13]
	v_mfma_i32_16x16x64_i8 v[14:17], v[156:159], v[184:187], v[14:17]
	v_mfma_i32_16x16x64_i8 v[2:5], v[148:151], v[192:195], v[2:5]
	v_mfma_i32_16x16x64_i8 v[6:9], v[156:159], v[192:195], v[6:9]
	v_mfma_i32_16x16x64_i8 v[26:29], v[152:155], v[172:175], v[26:29]
	v_mfma_i32_16x16x64_i8 v[30:33], v[164:167], v[172:175], v[30:33]
	v_mfma_i32_16x16x64_i8 v[18:21], v[152:155], v[180:183], v[18:21]
	v_mfma_i32_16x16x64_i8 v[22:25], v[164:167], v[180:183], v[22:25]
	v_mfma_i32_16x16x64_i8 v[10:13], v[152:155], v[188:191], v[10:13]
	v_mfma_i32_16x16x64_i8 v[14:17], v[164:167], v[188:191], v[14:17]
	v_mfma_i32_16x16x64_i8 v[2:5], v[152:155], v[212:215], v[2:5]
	v_mfma_i32_16x16x64_i8 v[6:9], v[164:167], v[212:215], v[6:9]
	s_barrier
	s_setprio 0
	s_add_i32 s34, s34, 2
	s_add_u32 s6, s6, 0x8000
	s_addc_u32 s7, s7, 0
	s_cmp_gt_u32 s34, 41
.LBB0_1154:
	v_add_u32_e32 v144, s90, v200
	v_add_u32_e32 v160, s15, v200
	s_add_u32 s8, s4, s6
	ds_read_b128 v[132:135], v144
	ds_read_b128 v[136:139], v144 offset:1024
	ds_read_b128 v[140:143], v144 offset:2048
	ds_read_b128 v[144:147], v144 offset:3072
	ds_read_b128 v[148:151], v160
	ds_read_b128 v[152:155], v160 offset:1024
	ds_read_b128 v[156:159], v160 offset:2048
	ds_read_b128 v[164:167], v160 offset:3072
	s_addc_u32 s9, s5, s7
	s_add_u32 s8, s8, 0x8000
	s_addc_u32 s9, s9, 0
	s_add_u32 s28, s10, s6
	s_addc_u32 s29, s11, s7
	s_cmp_eq_u32 s6, 0xa8000
	s_cselect_b32 s9, s67, s9
	s_cselect_b32 s8, s66, s8
	s_cselect_b32 vcc_hi, s87, s29
	s_cselect_b32 vcc_lo, s86, s28
	v_lshl_add_u64 v[160:161], v[130:131], 0, s[6:7]
	v_lshl_add_u64 v[196:197], v[160:161], 0, s[76:77]
	s_add_i32 m0, s0, 0xc000
	ds_read_b128 v[168:171], v201
	ds_read_b128 v[172:175], v201 offset:1024
	ds_read_b128 v[176:179], v201 offset:2048
	ds_read_b128 v[180:183], v201 offset:3072
	ds_read_b128 v[184:187], v201 offset:4096
	ds_read_b128 v[188:191], v201 offset:5120
	ds_read_b128 v[192:195], v201 offset:6144
	ds_read_b128 v[212:215], v201 offset:7168
	global_load_lds_dwordx4 v[196:197], off
	v_lshl_add_u64 v[160:161], v[160:161], 0, s[78:79]
	s_add_i32 m0, s0, 0xe000
	s_nop 0
	global_load_lds_dwordx4 v[160:161], off
	.p2align 3
	s_waitcnt vmcnt(8)
	s_waitcnt lgkmcnt(0)
	s_setprio 1
	s_barrier
; #define PG8_STAGE(bufoff, gbase, unused) do { _Pragma("unroll") for (int _i = 0; _i < 2; ++_i) \
;         __builtin_amdgcn_global_load_lds((const unsigned*)((const char*)(gbase) + voff + _i * 8192), (LAS unsigned*)(lds + (bufoff) + ldsw + _i * 8192), 16, 0, 0); } while (0)
; #define PG8_LDA(dst, b, h) do { _Pragma("unroll") for (int m = 0; m < 4; ++m) _Pragma("unroll") for (int k = 0; k < 2; ++k) dst[m][k] = *(const LAS bf16x8*)(lds + PG8_SA(b, h) + aoff + m * 2048 + (FP8 ? k * 16 : k * 1024)); } while (0)
; #define PG8_LDB(dst, b, h) do { _Pragma("unroll") for (int n = 0; n < 2; ++n) _Pragma("unroll") for (int k = 0; k < 2; ++k) dst[n][k] = *(const LAS bf16x8*)(lds + PG8_SB(b, h) + boff + n * 2048 + (FP8 ? k * 16 : k * 1024)); } while (0)
; #define PG8_WAIT_V(n) asm volatile("s_waitcnt vmcnt(" #n ")" ::: "memory")
; #define PG8_WAIT_L(n) asm volatile("s_waitcnt lgkmcnt(" #n ")" ::: "memory")
; #define PG8_BAR __builtin_amdgcn_s_barrier()
; #define PG8_SCHED __builtin_amdgcn_sched_barrier(0)
; template <class Epi, class Sched, bool ALIGN_EPI, bool SP2, int MODE  >
; __device__ __forceinline__ void gemm_phase(LAS unsigned char* lds, const Gemm g, const Sched S, const Epi E, unsigned long long& probe_acc, int epi_id, int wv) {
;     ...
;             PG8_LDB(B0, 0, 0); PG8_LDB(B1, 0, 1); PG8_SCHED; PG8_LDA(At, 0, 0); PG8_STAGE(PG8_SA(1, 1), a1 + hA, voffA);
;             PG8_WAIT_V(8); PG8_WAIT_L(0); PG8_BAR; PG8_MMA(0, 0, At, B0); PG8_MMA(0, 1, At, B1); PG8_BAR; PG8_SCHED;
;             PG8_LDA(At, 0, 1); PG8_STAGE(PG8_SB(0, 0), b2, voffB); PG8_STAGE(PG8_SB(0, 1), b2 + hB, voffB); PG8_STAGE(PG8_SA(0, 0), a2, voffA);
;             PG8_WAIT_V(8); PG8_WAIT_L(0); PG8_BAR; PG8_MMA(1, 0, At, B0); PG8_MMA(1, 1, At, B1); PG8_BAR; PG8_SCHED;
;             PG8_LDB(B0, 1, 0); PG8_LDB(B1, 1, 1); PG8_SCHED; PG8_LDA(At, 1, 0); PG8_STAGE(PG8_SA(0, 1), a2 + hA, voffA);
;             PG8_WAIT_V(8); PG8_WAIT_L(0); PG8_BAR; PG8_MMA(0, 0, At, B0); PG8_MMA(0, 1, At, B1); PG8_BAR; PG8_SCHED;
	v_mfma_i32_16x16x64_i8 v[122:125], v[132:135], v[168:171], v[122:125]
	v_mfma_i32_16x16x64_i8 v[126:129], v[140:143], v[168:171], v[126:129]
	v_mfma_i32_16x16x64_i8 v[114:117], v[132:135], v[176:179], v[114:117]
	v_mfma_i32_16x16x64_i8 v[118:121], v[140:143], v[176:179], v[118:121]
	v_mfma_i32_16x16x64_i8 v[106:109], v[132:135], v[184:187], v[106:109]
	v_mfma_i32_16x16x64_i8 v[110:113], v[140:143], v[184:187], v[110:113]
	v_mfma_i32_16x16x64_i8 v[98:101], v[132:135], v[192:195], v[98:101]
	v_mfma_i32_16x16x64_i8 v[102:105], v[140:143], v[192:195], v[102:105]
	v_mfma_i32_16x16x64_i8 v[122:125], v[136:139], v[172:175], v[122:125]
	v_mfma_i32_16x16x64_i8 v[126:129], v[144:147], v[172:175], v[126:129]
	v_mfma_i32_16x16x64_i8 v[114:117], v[136:139], v[180:183], v[114:117]
	v_mfma_i32_16x16x64_i8 v[118:121], v[144:147], v[180:183], v[118:121]
	v_mfma_i32_16x16x64_i8 v[106:109], v[136:139], v[188:191], v[106:109]
	v_mfma_i32_16x16x64_i8 v[110:113], v[144:147], v[188:191], v[110:113]
	v_mfma_i32_16x16x64_i8 v[98:101], v[136:139], v[212:215], v[98:101]
	v_mfma_i32_16x16x64_i8 v[102:105], v[144:147], v[212:215], v[102:105]
	v_mfma_i32_16x16x64_i8 v[58:61], v[148:151], v[168:171], v[58:61]
	v_mfma_i32_16x16x64_i8 v[62:65], v[156:159], v[168:171], v[62:65]
	v_mfma_i32_16x16x64_i8 v[50:53], v[148:151], v[176:179], v[50:53]
	v_mfma_i32_16x16x64_i8 v[54:57], v[156:159], v[176:179], v[54:57]
	v_mfma_i32_16x16x64_i8 v[42:45], v[148:151], v[184:187], v[42:45]
	v_mfma_i32_16x16x64_i8 v[46:49], v[156:159], v[184:187], v[46:49]
	v_mfma_i32_16x16x64_i8 v[34:37], v[148:151], v[192:195], v[34:37]
	v_mfma_i32_16x16x64_i8 v[38:41], v[156:159], v[192:195], v[38:41]
	v_mfma_i32_16x16x64_i8 v[58:61], v[152:155], v[172:175], v[58:61]
	v_mfma_i32_16x16x64_i8 v[62:65], v[164:167], v[172:175], v[62:65]
	v_mfma_i32_16x16x64_i8 v[50:53], v[152:155], v[180:183], v[50:53]
	v_mfma_i32_16x16x64_i8 v[54:57], v[164:167], v[180:183], v[54:57]
	v_mfma_i32_16x16x64_i8 v[42:45], v[152:155], v[188:191], v[42:45]
	v_mfma_i32_16x16x64_i8 v[46:49], v[164:167], v[188:191], v[46:49]
	v_mfma_i32_16x16x64_i8 v[34:37], v[152:155], v[212:215], v[34:37]
	v_mfma_i32_16x16x64_i8 v[38:41], v[164:167], v[212:215], v[38:41]
	s_barrier
	s_setprio 0
	s_mov_b32 m0, s91
	v_lshl_add_u64 v[160:161], vcc, 0, v[0:1]
	ds_read_b128 v[168:171], v201 offset:16384
	ds_read_b128 v[172:175], v201 offset:17408
	ds_read_b128 v[176:179], v201 offset:18432
	ds_read_b128 v[180:183], v201 offset:19456
	ds_read_b128 v[184:187], v201 offset:20480
	ds_read_b128 v[188:191], v201 offset:21504
	ds_read_b128 v[192:195], v201 offset:22528
	ds_read_b128 v[212:215], v201 offset:23552
	global_load_lds_dwordx4 v[160:161], off
	v_lshl_add_u64 v[196:197], v[160:161], 0, s[70:71]
	s_mov_b32 m0, s14
	s_nop 0
	global_load_lds_dwordx4 v[196:197], off
	v_lshl_add_u64 v[196:197], v[160:161], 0, s[42:43]
	s_mov_b32 m0, s26
	s_nop 0
	global_load_lds_dwordx4 v[196:197], off
	v_lshl_add_u64 v[196:197], v[160:161], 0, s[48:49]
	s_mov_b32 m0, s27
	s_nop 0
	global_load_lds_dwordx4 v[196:197], off
	v_lshl_add_u64 v[196:197], s[8:9], 0, v[0:1]
	s_mov_b32 m0, s0
	v_lshl_add_u64 v[202:203], v[196:197], 0, s[70:71]
	global_load_lds_dwordx4 v[196:197], off
	s_mov_b32 m0, s1
	s_nop 0
	global_load_lds_dwordx4 v[202:203], off
	.p2align 3
	s_waitcnt vmcnt(8)
	s_waitcnt lgkmcnt(0)
	s_setprio 1
	s_barrier
	v_mfma_i32_16x16x64_i8 v[90:93], v[132:135], v[168:171], v[90:93]
	v_mfma_i32_16x16x64_i8 v[94:97], v[140:143], v[168:171], v[94:97]
	v_mfma_i32_16x16x64_i8 v[82:85], v[132:135], v[176:179], v[82:85]
	v_mfma_i32_16x16x64_i8 v[86:89], v[140:143], v[176:179], v[86:89]
	v_mfma_i32_16x16x64_i8 v[74:77], v[132:135], v[184:187], v[74:77]
	v_mfma_i32_16x16x64_i8 v[78:81], v[140:143], v[184:187], v[78:81]
	v_mfma_i32_16x16x64_i8 v[66:69], v[132:135], v[192:195], v[66:69]
	v_mfma_i32_16x16x64_i8 v[70:73], v[140:143], v[192:195], v[70:73]
	v_mfma_i32_16x16x64_i8 v[90:93], v[136:139], v[172:175], v[90:93]
	v_mfma_i32_16x16x64_i8 v[94:97], v[144:147], v[172:175], v[94:97]
	v_mfma_i32_16x16x64_i8 v[82:85], v[136:139], v[180:183], v[82:85]
	v_mfma_i32_16x16x64_i8 v[86:89], v[144:147], v[180:183], v[86:89]
	v_mfma_i32_16x16x64_i8 v[74:77], v[136:139], v[188:191], v[74:77]
	v_mfma_i32_16x16x64_i8 v[78:81], v[144:147], v[188:191], v[78:81]
	v_mfma_i32_16x16x64_i8 v[66:69], v[136:139], v[212:215], v[66:69]
	v_mfma_i32_16x16x64_i8 v[70:73], v[144:147], v[212:215], v[70:73]
	v_mfma_i32_16x16x64_i8 v[26:29], v[148:151], v[168:171], v[26:29]
	v_mfma_i32_16x16x64_i8 v[30:33], v[156:159], v[168:171], v[30:33]
	v_mfma_i32_16x16x64_i8 v[18:21], v[148:151], v[176:179], v[18:21]
	v_mfma_i32_16x16x64_i8 v[22:25], v[156:159], v[176:179], v[22:25]
	v_mfma_i32_16x16x64_i8 v[10:13], v[148:151], v[184:187], v[10:13]
	v_mfma_i32_16x16x64_i8 v[14:17], v[156:159], v[184:187], v[14:17]
	v_mfma_i32_16x16x64_i8 v[2:5], v[148:151], v[192:195], v[2:5]
	v_mfma_i32_16x16x64_i8 v[6:9], v[156:159], v[192:195], v[6:9]
	v_mfma_i32_16x16x64_i8 v[26:29], v[152:155], v[172:175], v[26:29]
	v_mfma_i32_16x16x64_i8 v[30:33], v[164:167], v[172:175], v[30:33]
	v_mfma_i32_16x16x64_i8 v[18:21], v[152:155], v[180:183], v[18:21]
	v_mfma_i32_16x16x64_i8 v[22:25], v[164:167], v[180:183], v[22:25]
	v_mfma_i32_16x16x64_i8 v[10:13], v[152:155], v[188:191], v[10:13]
	v_mfma_i32_16x16x64_i8 v[14:17], v[164:167], v[188:191], v[14:17]
	v_mfma_i32_16x16x64_i8 v[2:5], v[152:155], v[212:215], v[2:5]
	v_mfma_i32_16x16x64_i8 v[6:9], v[164:167], v[212:215], v[6:9]
	s_barrier
; #define PG8_STAGE(bufoff, gbase, unused) do { _Pragma("unroll") for (int _i = 0; _i < 2; ++_i) \
;         __builtin_amdgcn_global_load_lds((const unsigned*)((const char*)(gbase) + voff + _i * 8192), (LAS unsigned*)(lds + (bufoff) + ldsw + _i * 8192), 16, 0, 0); } while (0)
; #define PG8_LDA(dst, b, h) do { _Pragma("unroll") for (int m = 0; m < 4; ++m) _Pragma("unroll") for (int k = 0; k < 2; ++k) dst[m][k] = *(const LAS bf16x8*)(lds + PG8_SA(b, h) + aoff + m * 2048 + (FP8 ? k * 16 : k * 1024)); } while (0)
; #define PG8_LDB(dst, b, h) do { _Pragma("unroll") for (int n = 0; n < 2; ++n) _Pragma("unroll") for (int k = 0; k < 2; ++k) dst[n][k] = *(const LAS bf16x8*)(lds + PG8_SB(b, h) + boff + n * 2048 + (FP8 ? k * 16 : k * 1024)); } while (0)
; #define PG8_WAIT_V(n) asm volatile("s_waitcnt vmcnt(" #n ")" ::: "memory")
; #define PG8_WAIT_L(n) asm volatile("s_waitcnt lgkmcnt(" #n ")" ::: "memory")
; #define PG8_BAR __builtin_amdgcn_s_barrier()
; #define PG8_SCHED __builtin_amdgcn_sched_barrier(0)
; template <class Epi, class Sched, bool ALIGN_EPI, bool SP2, int MODE  >
; __device__ __forceinline__ void gemm_phase(LAS unsigned char* lds, const Gemm g, const Sched S, const Epi E, unsigned long long& probe_acc, int epi_id, int wv) {
;     ...
;             PG8_WAIT_V(8); PG8_WAIT_L(0); PG8_BAR; PG8_MMA(1, 0, At, B0); PG8_MMA(1, 1, At, B1); PG8_BAR; PG8_SCHED;
;             PG8_LDB(B0, 1, 0); PG8_LDB(B1, 1, 1); PG8_SCHED; PG8_LDA(At, 1, 0); PG8_STAGE(PG8_SA(0, 1), a2 + hA, voffA);
;             PG8_WAIT_V(8); PG8_WAIT_L(0); PG8_BAR; PG8_MMA(0, 0, At, B0); PG8_MMA(0, 1, At, B1); PG8_BAR; PG8_SCHED;
;             PG8_LDA(At, 1, 1); PG8_STAGE(PG8_SB(1, 0), b3, voffB); PG8_STAGE(PG8_SB(1, 1), b3 + hB, voffB); PG8_STAGE(PG8_SA(1, 0), a3, voffA);
;             PG8_WAIT_V(8); PG8_WAIT_L(0); PG8_BAR; PG8_MMA(1, 0, At, B0); PG8_MMA(1, 1, At, B1); PG8_BAR; PG8_SCHED;
	s_setprio 0
	v_add_u32_e32 v144, s88, v200
	v_add_u32_e32 v162, s95, v200
	ds_read_b128 v[132:135], v144
	ds_read_b128 v[136:139], v144 offset:1024
	ds_read_b128 v[140:143], v144 offset:2048
	ds_read_b128 v[144:147], v144 offset:3072
	ds_read_b128 v[148:151], v162
	ds_read_b128 v[152:155], v162 offset:1024
	ds_read_b128 v[156:159], v162 offset:2048
	ds_read_b128 v[164:167], v162 offset:3072
	s_add_u32 s8, s8, s40
	s_addc_u32 s9, s9, 0
	s_mov_b32 m0, s36
	v_lshl_add_u64 v[202:203], s[8:9], 0, v[0:1]
	ds_read_b128 v[168:171], v201 offset:32768
	ds_read_b128 v[172:175], v201 offset:33792
	ds_read_b128 v[176:179], v201 offset:34816
	ds_read_b128 v[180:183], v201 offset:35840
	ds_read_b128 v[184:187], v201 offset:36864
	ds_read_b128 v[188:191], v201 offset:37888
	ds_read_b128 v[192:195], v201 offset:38912
	ds_read_b128 v[212:215], v201 offset:39936
	global_load_lds_dwordx4 v[202:203], off
	v_lshl_add_u64 v[202:203], v[202:203], 0, s[70:71]
	s_mov_b32 m0, s37
	s_nop 0
	global_load_lds_dwordx4 v[202:203], off
	.p2align 3
	s_waitcnt vmcnt(8)
	s_waitcnt lgkmcnt(0)
	s_setprio 1
	s_barrier
	v_mfma_i32_16x16x64_i8 v[122:125], v[132:135], v[168:171], v[122:125]
	v_mfma_i32_16x16x64_i8 v[126:129], v[140:143], v[168:171], v[126:129]
	v_mfma_i32_16x16x64_i8 v[114:117], v[132:135], v[176:179], v[114:117]
	v_mfma_i32_16x16x64_i8 v[118:121], v[140:143], v[176:179], v[118:121]
	v_mfma_i32_16x16x64_i8 v[106:109], v[132:135], v[184:187], v[106:109]
	v_mfma_i32_16x16x64_i8 v[110:113], v[140:143], v[184:187], v[110:113]
	v_mfma_i32_16x16x64_i8 v[98:101], v[132:135], v[192:195], v[98:101]
	v_mfma_i32_16x16x64_i8 v[102:105], v[140:143], v[192:195], v[102:105]
	v_mfma_i32_16x16x64_i8 v[122:125], v[136:139], v[172:175], v[122:125]
	v_mfma_i32_16x16x64_i8 v[126:129], v[144:147], v[172:175], v[126:129]
	v_mfma_i32_16x16x64_i8 v[114:117], v[136:139], v[180:183], v[114:117]
	v_mfma_i32_16x16x64_i8 v[118:121], v[144:147], v[180:183], v[118:121]
	v_mfma_i32_16x16x64_i8 v[106:109], v[136:139], v[188:191], v[106:109]
	v_mfma_i32_16x16x64_i8 v[110:113], v[144:147], v[188:191], v[110:113]
	v_mfma_i32_16x16x64_i8 v[98:101], v[136:139], v[212:215], v[98:101]
	v_mfma_i32_16x16x64_i8 v[102:105], v[144:147], v[212:215], v[102:105]
	v_mfma_i32_16x16x64_i8 v[58:61], v[148:151], v[168:171], v[58:61]
	v_mfma_i32_16x16x64_i8 v[62:65], v[156:159], v[168:171], v[62:65]
	v_mfma_i32_16x16x64_i8 v[50:53], v[148:151], v[176:179], v[50:53]
	v_mfma_i32_16x16x64_i8 v[54:57], v[156:159], v[176:179], v[54:57]
	v_mfma_i32_16x16x64_i8 v[42:45], v[148:151], v[184:187], v[42:45]
	v_mfma_i32_16x16x64_i8 v[46:49], v[156:159], v[184:187], v[46:49]
	v_mfma_i32_16x16x64_i8 v[34:37], v[148:151], v[192:195], v[34:37]
	v_mfma_i32_16x16x64_i8 v[38:41], v[156:159], v[192:195], v[38:41]
	v_mfma_i32_16x16x64_i8 v[58:61], v[152:155], v[172:175], v[58:61]
	v_mfma_i32_16x16x64_i8 v[62:65], v[164:167], v[172:175], v[62:65]
	v_mfma_i32_16x16x64_i8 v[50:53], v[152:155], v[180:183], v[50:53]
	v_mfma_i32_16x16x64_i8 v[54:57], v[164:167], v[180:183], v[54:57]
	v_mfma_i32_16x16x64_i8 v[42:45], v[152:155], v[188:191], v[42:45]
	v_mfma_i32_16x16x64_i8 v[46:49], v[164:167], v[188:191], v[46:49]
	v_mfma_i32_16x16x64_i8 v[34:37], v[152:155], v[212:215], v[34:37]
	v_mfma_i32_16x16x64_i8 v[38:41], v[164:167], v[212:215], v[38:41]
	s_barrier
	s_setprio 0
	s_mov_b32 m0, s89
	v_lshl_add_u64 v[202:203], v[160:161], 0, s[76:77]
	ds_read_b128 v[168:171], v201 offset:49152
	ds_read_b128 v[172:175], v201 offset:50176
	ds_read_b128 v[176:179], v201 offset:51200
	ds_read_b128 v[180:183], v201 offset:52224
	ds_read_b128 v[184:187], v201 offset:53248
	ds_read_b128 v[188:191], v201 offset:54272
	ds_read_b128 v[192:195], v201 offset:55296
	ds_read_b128 v[212:215], v201 offset:56320
	global_load_lds_dwordx4 v[202:203], off
	v_lshl_add_u64 v[202:203], v[160:161], 0, s[78:79]
	s_mov_b32 m0, s92
	s_nop 0
	global_load_lds_dwordx4 v[202:203], off
	v_lshl_add_u64 v[202:203], v[160:161], 0, s[44:45]
	s_mov_b32 m0, s84
	v_lshl_add_u64 v[160:161], v[160:161], 0, s[56:57]
	global_load_lds_dwordx4 v[202:203], off
	s_mov_b32 m0, s12
	s_nop 0
	global_load_lds_dwordx4 v[160:161], off
	v_lshl_add_u64 v[160:161], v[196:197], 0, s[76:77]
	s_mov_b32 m0, s93
	s_nop 0
	global_load_lds_dwordx4 v[160:161], off
	v_lshl_add_u64 v[160:161], v[196:197], 0, s[78:79]
	s_mov_b32 m0, s94
	s_nop 0
	global_load_lds_dwordx4 v[160:161], off
	.p2align 3
	s_waitcnt vmcnt(8)
	s_waitcnt lgkmcnt(0)
	s_setprio 1
	s_barrier
	v_mfma_i32_16x16x64_i8 v[90:93], v[132:135], v[168:171], v[90:93]
	v_mfma_i32_16x16x64_i8 v[94:97], v[140:143], v[168:171], v[94:97]
	v_mfma_i32_16x16x64_i8 v[82:85], v[132:135], v[176:179], v[82:85]
	v_mfma_i32_16x16x64_i8 v[86:89], v[140:143], v[176:179], v[86:89]
	v_mfma_i32_16x16x64_i8 v[74:77], v[132:135], v[184:187], v[74:77]
	v_mfma_i32_16x16x64_i8 v[78:81], v[140:143], v[184:187], v[78:81]
	v_mfma_i32_16x16x64_i8 v[66:69], v[132:135], v[192:195], v[66:69]
	v_mfma_i32_16x16x64_i8 v[70:73], v[140:143], v[192:195], v[70:73]
	v_mfma_i32_16x16x64_i8 v[90:93], v[136:139], v[172:175], v[90:93]
	v_mfma_i32_16x16x64_i8 v[94:97], v[144:147], v[172:175], v[94:97]
	v_mfma_i32_16x16x64_i8 v[82:85], v[136:139], v[180:183], v[82:85]
	v_mfma_i32_16x16x64_i8 v[86:89], v[144:147], v[180:183], v[86:89]
	v_mfma_i32_16x16x64_i8 v[74:77], v[136:139], v[188:191], v[74:77]
	v_mfma_i32_16x16x64_i8 v[78:81], v[144:147], v[188:191], v[78:81]
	v_mfma_i32_16x16x64_i8 v[66:69], v[136:139], v[212:215], v[66:69]
	v_mfma_i32_16x16x64_i8 v[70:73], v[144:147], v[212:215], v[70:73]
	v_mfma_i32_16x16x64_i8 v[26:29], v[148:151], v[168:171], v[26:29]
	v_mfma_i32_16x16x64_i8 v[30:33], v[156:159], v[168:171], v[30:33]
	v_mfma_i32_16x16x64_i8 v[18:21], v[148:151], v[176:179], v[18:21]
	v_mfma_i32_16x16x64_i8 v[22:25], v[156:159], v[176:179], v[22:25]
	v_mfma_i32_16x16x64_i8 v[10:13], v[148:151], v[184:187], v[10:13]
	v_mfma_i32_16x16x64_i8 v[14:17], v[156:159], v[184:187], v[14:17]
	v_mfma_i32_16x16x64_i8 v[2:5], v[148:151], v[192:195], v[2:5]
	v_mfma_i32_16x16x64_i8 v[6:9], v[156:159], v[192:195], v[6:9]
	v_mfma_i32_16x16x64_i8 v[26:29], v[152:155], v[172:175], v[26:29]
	v_mfma_i32_16x16x64_i8 v[30:33], v[164:167], v[172:175], v[30:33]
	v_mfma_i32_16x16x64_i8 v[18:21], v[152:155], v[180:183], v[18:21]
	v_mfma_i32_16x16x64_i8 v[22:25], v[164:167], v[180:183], v[22:25]
	v_mfma_i32_16x16x64_i8 v[10:13], v[152:155], v[188:191], v[10:13]
	v_mfma_i32_16x16x64_i8 v[14:17], v[164:167], v[188:191], v[14:17]
	v_mfma_i32_16x16x64_i8 v[2:5], v[152:155], v[212:215], v[2:5]
	v_mfma_i32_16x16x64_i8 v[6:9], v[164:167], v[212:215], v[6:9]
	s_barrier
	s_setprio 0
	s_add_i32 s34, s34, 2
	s_add_u32 s6, s6, 0x8000
	s_addc_u32 s7, s7, 0
	s_cmp_gt_u32 s34, 41
	s_cbranch_scc0 .LBB0_1154
	v_readlane_b32 s4, v255, 34
	v_readlane_b32 s5, v255, 35
	s_and_b64 vcc, exec, s[4:5]
	s_cbranch_vccz .LBB0_1157
	s_barrier
